# v3 (diag hoist + fast k_s/v_s state copy + F1 pool/f1 rebalance) plus down_reduce folded into final norm (phase 21 and its barrier removed)
# speedup vs baseline: 1.0088x; 1.0088x over previous
; __device__ __forceinline__ float delta_prep(const Params& p, int l, int h, bool isP, int grow0, int t0, int nvalid, int bb, char* sm) {
;     ...
;         for (int ii = 0; ii < 16; ++ii) a[ii] = xs[(ib * 16 + ii) * 256 + tid];
; #pragma unroll
;         for (int j = 0; j < 16; ++j) {
;           const float xj = a[j];
;           const float* mp = MT + (ib * 16 + j) * 64 + ib * 16;
; #pragma unroll
;           for (int ii = j + 1; ii < 16; ++ii) a[ii] -= mp[ii] * xj;
;         }
; __device__ __forceinline__ void phase_f1(const Params& p, int l, char* sm) {
;   constexpr int NPOOL = (NBP * NCH + 16) * 4;
;   for (int it = blockIdx.x; it < NUNIT_P + NPOOL; it += gridDim.x) {
;     if (it < NUNIT_P) f1_unit(p, l, it, sm);
.LBB0_735:
	s_cmp_gt_i32 s94, 2
	s_cselect_b64 s[0:1], -1, 0
	s_cmp_lt_i32 s95, 3
	s_cselect_b64 s[2:3], -1, 0
	s_or_b64 s[0:1], s[0:1], s[2:3]
	s_and_b64 vcc, exec, s[0:1]
	s_cbranch_vccnz .LBB0_1263
	s_cmpk_gt_i32 s54, 0x105f
	s_cbranch_scc1 .LBB0_1061
	v_readlane_b32 s0, v247, 60
	v_readlane_b32 s1, v247, 61
	s_add_u32 s90, s0, 0x6420000
	s_addc_u32 s91, s1, 0
	s_add_u32 s34, s0, 0x13c40000
	s_addc_u32 s35, s1, 0
	s_add_u32 s36, s0, 0xc80000
	s_addc_u32 s37, s1, 0
	s_add_u32 s22, s0, 0x1eea0000
	s_addc_u32 s23, s1, 0
	s_add_u32 s24, s0, 0x1efaa000
	s_addc_u32 s25, s1, 0
	s_add_u32 s26, s0, 0x15d80000
	s_addc_u32 s27, s1, 0
	s_add_i32 s0, 0, 0x23c04
	v_writelane_b32 v247, s0, 63
	s_add_i32 s0, 0, 0x23c28
	v_writelane_b32 v246, s0, 0
	s_add_i32 s0, 0, 0x23c08
	v_writelane_b32 v246, s0, 1
	s_add_i32 s0, 0, 0x23d08
	v_writelane_b32 v246, s0, 2
	s_add_i32 s0, 0, 0x23c38
	v_writelane_b32 v246, s0, 3
	s_add_i32 s0, 0, 0x23d38
	v_writelane_b32 v246, s0, 4
	s_add_i32 s0, 0, 0x23e0c
	v_writelane_b32 v246, s0, 5
	s_add_i32 s0, 0, 0x23e30
	v_writelane_b32 v246, s0, 6
	s_add_i32 s0, 0, 0x23e10
	v_writelane_b32 v246, s0, 7
	s_add_i32 s0, 0, 0x23f10
	v_writelane_b32 v246, s0, 8
	s_add_i32 s0, 0, 0x24014
	v_writelane_b32 v246, s0, 9
	s_add_i32 s0, 0, 0x23c18
	v_writelane_b32 v246, s0, 10
	s_add_i32 s0, 0, 0x23d18
	v_writelane_b32 v246, s0, 11
	s_add_i32 s0, 0, 0x24018
	v_writelane_b32 v246, s0, 12
	s_add_i32 s0, 0, 0x24118
	v_writelane_b32 v246, s0, 13
	s_add_i32 s0, 0, 0x2421c
	v_writelane_b32 v246, s0, 14
	s_add_i32 s0, 0, 0x23e20
	v_writelane_b32 v246, s0, 15
	s_add_i32 s0, 0, 0x23f20
	v_writelane_b32 v246, s0, 16
	s_add_i32 s0, 0, 0x24220
	v_writelane_b32 v246, s0, 17
	s_add_i32 s0, 0, 0x24320
	v_writelane_b32 v246, s0, 18
	s_add_i32 s0, 0, 0x24424
	v_writelane_b32 v246, s0, 19
	s_add_i32 s0, 0, 0x23d28
	v_writelane_b32 v246, s0, 20
	s_add_i32 s0, 0, 0x24028
	v_writelane_b32 v246, s0, 21
	s_add_i32 s0, 0, 0x24128
	v_writelane_b32 v246, s0, 22
	s_add_i32 s0, 0, 0x24428
	v_writelane_b32 v246, s0, 23
	s_add_i32 s0, 0, 0x24528
	v_writelane_b32 v246, s0, 24
	s_add_i32 s0, 0, 0x2462c
	v_writelane_b32 v246, s0, 25
	s_add_i32 s0, 0, 0x23f30
	v_writelane_b32 v246, s0, 26
	s_add_i32 s0, 0, 0x24230
	v_writelane_b32 v246, s0, 27
	s_add_i32 s0, 0, 0x24330
	v_writelane_b32 v246, s0, 28
	s_add_i32 s0, 0, 0x24630
	v_writelane_b32 v246, s0, 29
	s_add_i32 s0, 0, 0x24730
	v_writelane_b32 v246, s0, 30
	s_add_i32 s0, 0, 0x24834
	v_writelane_b32 v246, s0, 31
	s_add_i32 s0, 0, 0x24038
	v_writelane_b32 v246, s0, 32
	s_add_i32 s0, 0, 0x24138
	v_writelane_b32 v246, s0, 33
	s_add_i32 s0, 0, 0x24438
	v_writelane_b32 v246, s0, 34
	s_add_i32 s0, 0, 0x24538
	v_writelane_b32 v246, s0, 35
	s_add_i32 s0, 0, 0x24c44
	v_writelane_b32 v246, s0, 36
	s_add_i32 s0, 0, 0x24c68
	v_writelane_b32 v246, s0, 37
	s_add_i32 s0, 0, 0x24c48
	v_writelane_b32 v246, s0, 38
	s_add_i32 s0, 0, 0x24d48
	v_writelane_b32 v246, s0, 39
	s_add_i32 s0, 0, 0x24c78
	v_writelane_b32 v246, s0, 40
	s_add_i32 s0, 0, 0x24d78
	v_writelane_b32 v246, s0, 41
	s_add_i32 s0, 0, 0x24e4c
	v_writelane_b32 v246, s0, 42
	s_add_i32 s0, 0, 0x24e70
	v_writelane_b32 v246, s0, 43
	s_add_i32 s0, 0, 0x24e50
	v_writelane_b32 v246, s0, 44
	s_add_i32 s0, 0, 0x24f50
	v_writelane_b32 v246, s0, 45
	s_add_i32 s0, 0, 0x25054
	v_writelane_b32 v246, s0, 47
	s_add_i32 s0, 0, 0x24c58
	v_writelane_b32 v246, s0, 48
	s_add_i32 s0, 0, 0x24d58
	v_writelane_b32 v246, s0, 49
	s_add_i32 s0, 0, 0x25058
	v_writelane_b32 v246, s0, 50
	s_add_i32 s0, 0, 0x25158
	v_writelane_b32 v246, s0, 51
	s_add_i32 s0, 0, 0x2525c
	v_writelane_b32 v246, s0, 52
	s_add_i32 s0, 0, 0x24e60
	v_writelane_b32 v246, s0, 53
	s_add_i32 s0, 0, 0x24f60
	v_writelane_b32 v246, s0, 54
	s_add_i32 s0, 0, 0x25260
	v_writelane_b32 v246, s0, 55
	s_add_i32 s0, 0, 0x25360
	v_writelane_b32 v246, s0, 56
	s_add_i32 s0, 0, 0x25464
	v_writelane_b32 v246, s0, 57
	s_add_i32 s0, 0, 0x24d68
	v_writelane_b32 v246, s0, 58
	s_add_i32 s0, 0, 0x25068
	v_writelane_b32 v246, s0, 59
	s_add_i32 s0, 0, 0x25168
	v_writelane_b32 v246, s0, 60
	s_add_i32 s0, 0, 0x25468
	v_writelane_b32 v246, s0, 61
	s_add_i32 s0, 0, 0x25568
	v_writelane_b32 v246, s0, 62
	s_add_i32 s0, 0, 0x2566c
	v_writelane_b32 v246, s0, 63
	s_add_i32 s0, 0, 0x24f70
	v_writelane_b32 v245, s0, 0
	s_add_i32 s0, 0, 0x25270
	v_writelane_b32 v245, s0, 1
	s_add_i32 s0, 0, 0x25370
	v_writelane_b32 v245, s0, 2
	s_add_i32 s0, 0, 0x25670
	v_writelane_b32 v245, s0, 3
	s_add_i32 s0, 0, 0x25770
	v_writelane_b32 v245, s0, 4
	s_add_i32 s0, 0, 0x25874
	v_writelane_b32 v245, s0, 5
	s_add_i32 s0, 0, 0x25078
	v_writelane_b32 v245, s0, 6
	s_add_i32 s0, 0, 0x25178
	v_writelane_b32 v245, s0, 7
	s_add_i32 s0, 0, 0x25478
	v_writelane_b32 v245, s0, 8
	s_add_i32 s0, 0, 0x25578
	v_writelane_b32 v245, s0, 9
	s_add_i32 s0, 0, 0x25878
	v_writelane_b32 v245, s0, 10
	s_add_i32 s0, 0, 0x25978
	v_writelane_b32 v245, s0, 11
	s_add_i32 s0, 0, 0x25a7c
	v_writelane_b32 v245, s0, 12
	s_add_i32 s0, 0, 0x25c84
	v_writelane_b32 v245, s0, 13
	s_add_i32 s0, 0, 0x25ca8
	v_writelane_b32 v245, s0, 14
	s_add_i32 s0, 0, 0x25c88
	v_writelane_b32 v245, s0, 15
	s_add_i32 s0, 0, 0x25d88
	v_writelane_b32 v245, s0, 16
	s_add_i32 s0, 0, 0x25cb8
	v_writelane_b32 v245, s0, 17
	s_add_i32 s0, 0, 0x25db8
	v_writelane_b32 v245, s0, 18
; __device__ __forceinline__ float delta_prep(const Params& p, int l, int h, bool isP, int grow0, int t0, int nvalid, int bb, char* sm) {
;     ...
;         for (int ii = 0; ii < 16; ++ii) a[ii] = xs[(ib * 16 + ii) * 256 + tid];
; #pragma unroll
;         for (int j = 0; j < 16; ++j) {
;           const float xj = a[j];
;           const float* mp = MT + (ib * 16 + j) * 64 + ib * 16;
; #pragma unroll
;           for (int ii = j + 1; ii < 16; ++ii) a[ii] -= mp[ii] * xj;
;         }
; __device__ __forceinline__ void phase_f1(const Params& p, int l, char* sm) {
;   constexpr int NPOOL = (NBP * NCH + 16) * 4;
;   for (int it = blockIdx.x; it < NUNIT_P + NPOOL; it += gridDim.x) {
;     if (it < NUNIT_P) f1_unit(p, l, it, sm);
	s_add_i32 s0, 0, 0x25e8c
	v_writelane_b32 v245, s0, 19
	s_add_i32 s0, 0, 0x25eb0
	v_writelane_b32 v245, s0, 20
	s_add_i32 s0, 0, 0x25e90
	v_writelane_b32 v245, s0, 21
	s_add_i32 s0, 0, 0x25f90
	v_writelane_b32 v245, s0, 22
	s_add_i32 s0, 0, 0x26094
	v_writelane_b32 v245, s0, 23
	s_add_i32 s0, 0, 0x25c98
	v_writelane_b32 v245, s0, 24
	s_add_i32 s0, 0, 0x25d98
	v_writelane_b32 v245, s0, 25
	s_add_i32 s0, 0, 0x26098
	v_writelane_b32 v245, s0, 26
	s_add_i32 s0, 0, 0x26198
	v_writelane_b32 v245, s0, 27
	s_add_i32 s0, 0, 0x2629c
	v_writelane_b32 v245, s0, 28
	s_add_i32 s0, 0, 0x25ea0
	v_writelane_b32 v245, s0, 29
	s_add_i32 s0, 0, 0x25fa0
	v_writelane_b32 v245, s0, 30
	s_add_i32 s0, 0, 0x262a0
	v_writelane_b32 v245, s0, 31
	s_add_i32 s0, 0, 0x263a0
	v_writelane_b32 v245, s0, 32
	s_add_i32 s0, 0, 0x264a4
	v_writelane_b32 v245, s0, 33
	s_add_i32 s0, 0, 0x25da8
	v_writelane_b32 v245, s0, 34
	s_add_i32 s0, 0, 0x260a8
	v_writelane_b32 v245, s0, 35
	s_add_i32 s0, 0, 0x261a8
	v_writelane_b32 v245, s0, 36
	s_add_i32 s0, 0, 0x264a8
	v_writelane_b32 v245, s0, 37
	s_add_i32 s0, 0, 0x265a8
	v_writelane_b32 v245, s0, 38
	s_add_i32 s0, 0, 0x266ac
	v_writelane_b32 v245, s0, 39
	s_add_i32 s0, 0, 0x25fb0
	v_writelane_b32 v245, s0, 40
	s_add_i32 s0, 0, 0x262b0
	v_writelane_b32 v245, s0, 41
	s_add_i32 s0, 0, 0x263b0
	v_writelane_b32 v245, s0, 42
	s_add_i32 s0, 0, 0x266b0
	v_writelane_b32 v245, s0, 43
	s_add_i32 s0, 0, 0x267b0
	v_writelane_b32 v245, s0, 44
	s_add_i32 s0, 0, 0x268b4
	v_writelane_b32 v245, s0, 45
	s_add_i32 s0, 0, 0x260b8
	v_writelane_b32 v245, s0, 46
	s_add_i32 s0, 0, 0x261b8
	v_writelane_b32 v245, s0, 47
	s_add_i32 s0, 0, 0x264b8
	v_writelane_b32 v245, s0, 48
	s_add_i32 s0, 0, 0x265b8
	v_writelane_b32 v245, s0, 49
	s_add_i32 s0, 0, 0x268b8
	v_writelane_b32 v245, s0, 50
	s_add_i32 s0, 0, 0x269b8
	v_writelane_b32 v245, s0, 51
	s_add_i32 s0, 0, 0x26abc
	v_writelane_b32 v245, s0, 52
	s_add_i32 s0, 0, 0x26cc4
	v_writelane_b32 v245, s0, 53
	s_add_i32 s0, 0, 0x26ce8
	v_writelane_b32 v245, s0, 54
	s_add_i32 s0, 0, 0x26cc8
	v_writelane_b32 v245, s0, 55
	s_add_i32 s0, 0, 0x26dc8
	v_writelane_b32 v245, s0, 56
	s_add_i32 s0, 0, 0x26cf8
	v_writelane_b32 v245, s0, 57
	s_add_i32 s0, 0, 0x26df8
	v_writelane_b32 v245, s0, 58
	s_add_i32 s0, 0, 0x26ecc
	v_writelane_b32 v245, s0, 59
	s_add_i32 s0, 0, 0x26ef0
	v_writelane_b32 v245, s0, 60
	s_add_i32 s0, 0, 0x26ed0
	v_writelane_b32 v245, s0, 61
	s_add_i32 s0, 0, 0x26fd0
	v_writelane_b32 v245, s0, 62
	s_add_i32 s0, 0, 0x270d4
	v_writelane_b32 v245, s0, 63
	s_add_i32 s0, 0, 0x26cd8
	v_writelane_b32 v244, s0, 0
	s_add_i32 s0, 0, 0x26dd8
	v_writelane_b32 v244, s0, 1
	s_add_i32 s0, 0, 0x270d8
	v_writelane_b32 v244, s0, 2
	s_add_i32 s0, 0, 0x271d8
	v_writelane_b32 v244, s0, 3
	s_add_i32 s0, 0, 0x272dc
	v_writelane_b32 v244, s0, 4
	s_add_i32 s0, 0, 0x26ee0
	v_writelane_b32 v244, s0, 5
	s_add_i32 s0, 0, 0x26fe0
	v_writelane_b32 v244, s0, 6
	s_add_i32 s0, 0, 0x272e0
	v_writelane_b32 v244, s0, 7
	s_add_i32 s0, 0, 0x273e0
	v_writelane_b32 v244, s0, 8
	s_add_i32 s0, 0, 0x274e4
	v_writelane_b32 v244, s0, 9
	s_add_i32 s0, 0, 0x26de8
	v_writelane_b32 v244, s0, 10
	s_add_i32 s0, 0, 0x270e8
	v_writelane_b32 v244, s0, 11
	s_add_i32 s0, 0, 0x271e8
	v_writelane_b32 v244, s0, 12
	s_add_i32 s0, 0, 0x274e8
	v_writelane_b32 v244, s0, 13
	s_add_i32 s0, 0, 0x275e8
	v_writelane_b32 v244, s0, 14
	s_add_i32 s0, 0, 0x276ec
	v_writelane_b32 v244, s0, 15
	s_add_i32 s0, 0, 0x26ff0
	v_writelane_b32 v244, s0, 16
	s_add_i32 s0, 0, 0x272f0
	v_writelane_b32 v244, s0, 17
	s_add_i32 s0, 0, 0x273f0
	v_writelane_b32 v244, s0, 18
	s_add_i32 s0, 0, 0x276f0
	v_writelane_b32 v244, s0, 19
	s_add_i32 s0, 0, 0x277f0
	v_writelane_b32 v244, s0, 20
	s_add_i32 s0, 0, 0x278f4
	v_writelane_b32 v244, s0, 21
	s_add_i32 s0, 0, 0x270f8
	v_writelane_b32 v244, s0, 22
	s_add_i32 s0, 0, 0x271f8
	v_writelane_b32 v244, s0, 23
	s_add_i32 s0, 0, 0x274f8
	v_writelane_b32 v244, s0, 24
	s_add_i32 s0, 0, 0x275f8
	v_writelane_b32 v244, s0, 25
	s_add_i32 s0, 0, 0x278f8
	v_writelane_b32 v244, s0, 26
	s_add_i32 s0, 0, 0x279f8
	v_writelane_b32 v244, s0, 27
	s_add_i32 s0, 0, 0x27afc
	v_mbcnt_lo_u32_b32 v0, -1, 0
	v_writelane_b32 v244, s0, 28
	v_readlane_b32 s0, v247, 62
	s_movk_i32 s42, 0x2010
	v_mov_b32_e32 v61, 0
	s_mov_b32 s43, 0xb21642c9
	s_movk_i32 s44, 0xffe9
	s_mov_b32 s54, 0x8031
	s_movk_i32 s46, 0x110
	s_movk_i32 s76, 0x1000
	s_movk_i32 s77, 0x2000
	s_movk_i32 s78, 0x3000
	s_add_i32 s50, 0, 0xc9e0
	s_mov_b32 s51, 0x5040100
	s_mov_b32 s86, 0x7a44c6b
	s_movk_i32 s87, 0xfbd0
	s_movk_i32 s88, 0x90
	s_add_i32 s89, 0, 0x13c00
	s_movk_i32 s21, 0x43
	s_mov_b32 s79, 0xbfb8aa3b
	v_mov_b32_e32 v156, 0x3ecc95a3
	s_mov_b32 s45, 0x3fb8aa3b
	s_mov_b32 s92, 0xc2ce8ed0
	s_mov_b32 s93, 0x42b17218
	s_add_i32 s33, 0, 0x27c00
	s_movk_i32 s82, 0x4000
	s_mov_b32 s83, 0x800000
	s_add_i32 s47, 0, 0x4400
	s_add_i32 s48, 0, 0x23c00
	s_movk_i32 s49, 0x80
	v_mov_b32_e32 v157, 0x7f800000
	v_mov_b32_e32 v62, 0x3f317218
	v_mbcnt_hi_u32_b32 v158, -1, v0
	v_mov_b32_e32 v159, 0xffffb800
	v_mov_b32_e32 v160, 0xf400
	v_mov_b32_e32 v161, 0x4400
	s_add_i32 s39, 0, 0x24838
	s_add_i32 s40, 0, 0x24938
	s_add_i32 s41, 0, 0x24a3c
	s_add_i32 s38, 0, 0x27cfc
	s_mov_b64 s[94:95], 0x2000
	s_mov_b32 s96, s0
	s_mov_b32 s28, 0
	s_mov_b32 s101, 0
	s_branch .LBB0_740

; __device__ __forceinline__ void pool_item(const Params& p, int l, int it, char* smem_c) {
;     ...
;   const int rt = it >> 2, g = it & 3;
;   int grow0, nrows, t0 = 0;
;   const bool isP = rt < NBP * NCH;
;   if (isP) { int b = rt / NCH, i = rt - b * NCH; t0 = i * 64; nrows = min(64, TP - t0); grow0 = b * TP + t0; }
;   else { grow0 = ROWS_P + (rt - NBP * NCH) * 64; nrows = 64; }
; __device__ __forceinline__ void phase_f1(const Params& p, int l, char* sm) {
;     ...
;   for (int it = blockIdx.x; it < NUNIT_P + NPOOL; it += gridDim.x) {
;     if (it < NUNIT_P) f1_unit(p, l, it, sm);
;     else pool_item(p, l, it - NUNIT_P, sm);
.LBB0_739:
	s_add_i32 s96, s96, s84
	s_cmpk_lg_u32 s84, 0x100
	s_cbranch_scc1 .Lf1bal0_std
	v_readlane_b32 s100, v247, 62
	s_nop 1
	s_cmp_lt_u32 s100, 16
	s_cbranch_scc0 .Lf1bal0_hi
	s_cmpk_lt_i32 s96, 0xe00
	s_cbranch_scc1 .Lf1bal0_cont
	s_branch .Lf1bal0_exit
.Lf1bal0_hi:
	s_cmpk_gt_i32 s96, 0x105f
	s_cbranch_scc0 .Lf1bal0_cont
	s_cmp_lg_u32 s101, 0
	s_cbranch_scc1 .Lf1bal0_exit
	s_sub_u32 s100, s100, 0x60
	s_cmp_lt_u32 s100, 48
	s_cbranch_scc0 .Lf1bal0_exit
	s_mov_b32 s101, 1
	s_lshr_b32 s96, s100, 4
	s_add_u32 s96, s96, 14
	s_lshl_b32 s96, s96, 8
	s_and_b32 s100, s100, 15
	s_add_u32 s96, s96, s100
	s_branch .Lf1bal0_cont
.Lf1bal0_std:
	s_cmpk_gt_i32 s96, 0x105f
	s_cbranch_scc0 .Lf1bal0_cont
.Lf1bal0_exit:
	s_waitcnt lgkmcnt(0)
	s_branch .LBB0_1061
.Lf1bal0_cont:
	s_waitcnt lgkmcnt(0)
.LBB0_740:
	s_ashr_i32 s97, s96, 31
	s_cmpk_gt_i32 s96, 0x80f
	s_mov_b64 s[0:1], -1
	s_cbranch_scc0 .LBB0_866
	s_add_i32 s6, s96, 0xfffff7f0
	s_lshr_b32 s7, s6, 2
	s_cmpk_lt_u32 s6, 0x810
	s_cselect_b64 s[2:3], -1, 0
	s_cmpk_gt_u32 s6, 0x80f
	s_cselect_b64 s[0:1], -1, 0
	v_mov_b32_e32 v35, v224
	s_mov_b64 s[4:5], -1
	s_and_b64 vcc, exec, s[0:1]
	s_cbranch_vccz .LBB0_743
	s_lshl_b32 s4, s7, 6
	s_add_i32 s20, s4, 0xffffff40
	s_mov_b64 s[4:5], 0

; __device__ __forceinline__ void pool_item(const Params& p, int l, int it, char* smem_c) {
;     ...
;   const int rt = it >> 2, g = it & 3;
;   int grow0, nrows, t0 = 0;
;   const bool isP = rt < NBP * NCH;
;   if (isP) { int b = rt / NCH, i = rt - b * NCH; t0 = i * 64; nrows = min(64, TP - t0); grow0 = b * TP + t0; }
;   else { grow0 = ROWS_P + (rt - NBP * NCH) * 64; nrows = 64; }
;   const int wnd = 2 << g;
;   {
;     uint4 sv[6];
;     const int nch = isP ? 79 * 16 : 184 * 16;
; #pragma unroll
;     for (int i = 0; i < 6; ++i) {
;       const int c = tid + i * NTHR;
;       uint4 v = make_uint4(0u, 0u, 0u, 0u);
;       if (c < nch) {
;         const int rr = c >> 4, ch = c & 15;
;         if (isP) {
;           const int t = t0 - 15 + rr;
;           if (t >= 0 && t < TP) v = *(const uint4*)(B1 + (size_t)(grow0 - 15 + rr) * LD1 + g * 128 + ch * 8);
;         } else {
;           const int sg = rr / 23, pp = rr - sg * 23;
;           const int bb = ((grow0 - ROWS_P) >> 3) + sg;
;           if (pp < 15) {
;             const float* s = p.state_pool + ((size_t)(l * NBS + bb) * 15 + pp) * 512 + g * 128 + ch * 8;
;             float4 f0 = *(const float4*)s, f1 = *(const float4*)(s + 4);
;             v.x = pack2(f0.x, f0.y); v.y = pack2(f0.z, f0.w); v.z = pack2(f1.x, f1.y); v.w = pack2(f1.z, f1.w);
;           } else v = *(const uint4*)(B1 + (size_t)(ROWS_P + bb * TS + pp - 15) * LD1 + g * 128 + ch * 8);
;         }
.LBB0_746:
	s_add_i32 s31, s96, 0xfffff7f0
	s_lshr_b32 s31, s31, 8
	s_add_i32 s31, s31, s96
	s_and_b32 s31, s31, 3
	s_add_i32 s4, s20, 0xffff7fc0
	s_ashr_i32 s55, s4, 3
	s_lshl_b32 s4, s31, 8
	v_and_b32_e32 v34, 15, v35
	s_add_u32 s4, s90, s4
	s_addc_u32 s5, s91, 0
	v_lshlrev_b32_e32 v60, 4, v34
	v_readlane_b32 s60, v247, 7
	v_lshl_add_u64 v[24:25], s[4:5], 0, v[60:61]
	s_lshl_b32 s4, s31, 9
	v_readlane_b32 s64, v247, 11
	v_readlane_b32 s65, v247, 12
	s_add_u32 s4, s64, s4
	s_addc_u32 s5, s65, 0
	v_lshlrev_b32_e32 v60, 5, v34
	s_waitcnt lgkmcnt(0)
	v_lshl_add_u64 v[26:27], s[4:5], 0, v[60:61]
	s_add_i32 s53, s30, -15
	s_add_i32 s52, s20, -15
	v_cmp_gt_i32_e64 s[4:5], s56, v35
	v_mov_b32_e32 v0, 0
	v_mov_b32_e32 v4, 0
	v_mov_b32_e32 v5, 0
	v_mov_b32_e32 v6, 0
	v_mov_b32_e32 v7, 0
	v_readlane_b32 s61, v247, 8
	v_readlane_b32 s62, v247, 9
	v_readlane_b32 s63, v247, 10
	v_readlane_b32 s66, v247, 13
	v_readlane_b32 s67, v247, 14
	v_readlane_b32 s68, v247, 15
	v_readlane_b32 s69, v247, 16
	v_readlane_b32 s70, v247, 17
	v_readlane_b32 s71, v247, 18
	v_readlane_b32 s72, v247, 19
	v_readlane_b32 s73, v247, 20
	v_readlane_b32 s74, v247, 21
	v_readlane_b32 s75, v247, 22
	s_and_saveexec_b64 s[6:7], s[4:5]
	s_cbranch_execz .LBB0_757
	v_ashrrev_i32_e32 v1, 4, v35
	s_mov_b64 s[8:9], -1
	s_and_b64 vcc, exec, s[0:1]
	s_cbranch_vccz .LBB0_753
	v_mul_hi_i32 v2, v1, s43
	v_add_u32_e32 v2, v2, v1
	v_lshrrev_b32_e32 v3, 31, v2
	v_ashrrev_i32_e32 v2, 4, v2
	v_add_u32_e32 v3, v2, v3
	v_mad_i32_i24 v2, v3, s44, v1
	v_add_u32_e32 v8, s55, v3
	v_cmp_lt_i32_e32 vcc, 14, v2
	s_and_saveexec_b64 s[8:9], vcc
	s_xor_b64 s[8:9], exec, s[8:9]
	s_cbranch_execz .LBB0_750
	v_lshlrev_b32_e32 v3, 3, v8
	v_add3_u32 v2, v2, v3, s54
	v_ashrrev_i32_e32 v3, 31, v2
	v_lshlrev_b64 v[2:3], 12, v[2:3]
	v_lshl_add_u64 v[2:3], v[24:25], 0, v[2:3]
	global_load_dwordx4 v[4:7], v[2:3], off

; __device__ __forceinline__ float delta_prep(const Params& p, int l, int h, bool isP, int grow0, int t0, int nvalid, int bb, char* sm) {
;     ...
; #pragma unroll
;     for (int ib = 0; ib < 4; ++ib) {
;       if (ib * 16 >= nvalid) break;
;       if (ib > 0) {
;         f32x4 a0 = (f32x4){0.f, 0.f, 0.f, 0.f}, a1 = a0;
;         const bfraw* xb0 = (w < 4) ? XTu + ((2 * w) * 16 + r) * 72 : XTw + ((2 * w - 8) * 16 + r) * 72;
;         const bfraw* xb1 = xb0 + 16 * 72;
; #pragma unroll
;         for (int kk = 0; kk < 2; ++kk) {
;           if (kk * 32 < ib * 16) {
;             bf16x8 am = *(const bf16x8*)(Mb + (ib * 16 + r) * 72 + kk * 32 + q * 8);
;             bf16x8 b0 = *(const bf16x8*)(xb0 + kk * 32 + q * 8);
;             bf16x8 b1 = *(const bf16x8*)(xb1 + kk * 32 + q * 8);
;             a0 = mfma16(am, b0, a0);
;             a1 = mfma16(am, b1, a1);
;           }
;         }
; #pragma unroll
;         for (int g = 0; g < 4; ++g) {
;           float* rp = xs + (ib * 16 + q * 4 + g) * 256 + w * 32 + r;
;           rp[0] -= a0[g];
;           rp[16] -= a1[g];
;         }
;         __syncthreads();
;       }
;       if (tid < 256) {
;         float a[16];
; #pragma unroll
;         for (int ii = 0; ii < 16; ++ii) a[ii] = xs[(ib * 16 + ii) * 256 + tid];
; #pragma unroll
;         for (int j = 0; j < 16; ++j) {
;           const float xj = a[j];
;           const float* mp = MT + (ib * 16 + j) * 64 + ib * 16;
; #pragma unroll
;           for (int ii = j + 1; ii < 16; ++ii) a[ii] -= mp[ii] * xj;
;         }
;         bfraw* dst = (tid < 128) ? XTu + tid * 72 + ib * 16 : XTw + (tid - 128) * 72 + ib * 16;
;         *(uint4*)dst = pack8(a);
;         *(uint4*)(dst + 8) = pack8(a + 8);
;       }
;       __syncthreads();
.LBB0_1030:
	s_or_b64 exec, exec, s[0:1]
	v_mul_lo_u32 v0, v64, s88
	v_add_u32_e32 v36, 0, v0
	s_movk_i32 s0, 0x100
	v_add_u32_e32 v15, 0xffffb800, v36
	v_add_u32_e32 v0, 0xf400, v36
	v_cmp_gt_i32_e32 vcc, s49, v64
	v_cmp_gt_i32_e64 s[4:5], s0, v64
	v_lshl_add_u32 v40, v64, 2, s89
	v_cndmask_b32_e32 v31, v15, v0, vcc
	s_waitcnt lgkmcnt(0)
	s_barrier
	s_and_saveexec_b64 s[0:1], s[4:5]
	s_cbranch_execz .LBB0_1032
	ds_read2st64_b32 v[166:167], v40 offset1:4
	ds_read2st64_b32 v[168:169], v40 offset0:8 offset1:12
	ds_read2st64_b32 v[170:171], v40 offset0:16 offset1:20
	ds_read2st64_b32 v[172:173], v40 offset0:24 offset1:28
	ds_read2st64_b32 v[174:175], v40 offset0:32 offset1:36
	ds_read2st64_b32 v[176:177], v40 offset0:40 offset1:44
	ds_read2st64_b32 v[178:179], v40 offset0:48 offset1:52
	ds_read2st64_b32 v[180:181], v40 offset0:56 offset1:60
	v_mov_b32_e32 v165, 0x23c00
	ds_read_b32 v182, v165 offset:4
	ds_read_b64 v[184:185], v165 offset:8
	ds_read_b128 v[186:189], v165 offset:16
	ds_read_b128 v[190:193], v165 offset:32
	ds_read_b128 v[194:197], v165 offset:48
	ds_read_b64 v[198:199], v165 offset:264
	ds_read_b128 v[200:203], v165 offset:272
	ds_read_b128 v[204:207], v165 offset:288
	ds_read_b128 v[208:211], v165 offset:304
	ds_read_b32 v183, v165 offset:524
	ds_read_b128 v[212:215], v165 offset:528
	ds_read_b128 v[216:219], v165 offset:544
	ds_read_b128 v[220:223], v165 offset:560
	s_waitcnt lgkmcnt(13)
	ds_read_b128 v[226:229], v165 offset:784
	ds_read_b128 v[230:233], v165 offset:800
	ds_read_b128 v[234:237], v165 offset:816
	s_waitcnt lgkmcnt(11)
	v_fma_f32 v167, -v166, v182, v167
	v_pk_fma_f32 v[168:169], v[166:167], v[184:185], v[168:169] op_sel_hi:[0,1,1] neg_lo:[1,0,0] neg_hi:[1,0,0]
	v_pk_fma_f32 v[170:171], v[166:167], v[186:187], v[170:171] op_sel_hi:[0,1,1] neg_lo:[1,0,0] neg_hi:[1,0,0]
	v_pk_fma_f32 v[172:173], v[166:167], v[188:189], v[172:173] op_sel_hi:[0,1,1] neg_lo:[1,0,0] neg_hi:[1,0,0]
	v_pk_fma_f32 v[174:175], v[166:167], v[190:191], v[174:175] op_sel_hi:[0,1,1] neg_lo:[1,0,0] neg_hi:[1,0,0]
	v_pk_fma_f32 v[176:177], v[166:167], v[192:193], v[176:177] op_sel_hi:[0,1,1] neg_lo:[1,0,0] neg_hi:[1,0,0]
	v_pk_fma_f32 v[178:179], v[166:167], v[194:195], v[178:179] op_sel_hi:[0,1,1] neg_lo:[1,0,0] neg_hi:[1,0,0]
	v_pk_fma_f32 v[180:181], v[166:167], v[196:197], v[180:181] op_sel_hi:[0,1,1] neg_lo:[1,0,0] neg_hi:[1,0,0]
	ds_read_b32 v182, v165 offset:1044
	ds_read_b64 v[184:185], v165 offset:1048
	ds_read_b128 v[186:189], v165 offset:1056
	ds_read_b128 v[190:193], v165 offset:1072
	s_waitcnt lgkmcnt(11)
	v_pk_fma_f32 v[168:169], v[166:167], v[198:199], v[168:169] op_sel:[1,0,0] op_sel_hi:[1,1,1] neg_lo:[1,0,0] neg_hi:[1,0,0]
	v_pk_fma_f32 v[170:171], v[166:167], v[200:201], v[170:171] op_sel:[1,0,0] op_sel_hi:[1,1,1] neg_lo:[1,0,0] neg_hi:[1,0,0]
	v_pk_fma_f32 v[172:173], v[166:167], v[202:203], v[172:173] op_sel:[1,0,0] op_sel_hi:[1,1,1] neg_lo:[1,0,0] neg_hi:[1,0,0]
	v_pk_fma_f32 v[174:175], v[166:167], v[204:205], v[174:175] op_sel:[1,0,0] op_sel_hi:[1,1,1] neg_lo:[1,0,0] neg_hi:[1,0,0]
	v_pk_fma_f32 v[176:177], v[166:167], v[206:207], v[176:177] op_sel:[1,0,0] op_sel_hi:[1,1,1] neg_lo:[1,0,0] neg_hi:[1,0,0]
	v_pk_fma_f32 v[178:179], v[166:167], v[208:209], v[178:179] op_sel:[1,0,0] op_sel_hi:[1,1,1] neg_lo:[1,0,0] neg_hi:[1,0,0]
	v_pk_fma_f32 v[180:181], v[166:167], v[210:211], v[180:181] op_sel:[1,0,0] op_sel_hi:[1,1,1] neg_lo:[1,0,0] neg_hi:[1,0,0]
	ds_read_b64 v[194:195], v165 offset:1304
	ds_read_b128 v[196:199], v165 offset:1312
	ds_read_b128 v[200:203], v165 offset:1328
	s_waitcnt lgkmcnt(10)
	v_fma_f32 v169, -v168, v183, v169
	v_pk_fma_f32 v[170:171], v[168:169], v[212:213], v[170:171] op_sel_hi:[0,1,1] neg_lo:[1,0,0] neg_hi:[1,0,0]
	v_pk_fma_f32 v[172:173], v[168:169], v[214:215], v[172:173] op_sel_hi:[0,1,1] neg_lo:[1,0,0] neg_hi:[1,0,0]
	v_pk_fma_f32 v[174:175], v[168:169], v[216:217], v[174:175] op_sel_hi:[0,1,1] neg_lo:[1,0,0] neg_hi:[1,0,0]
	v_pk_fma_f32 v[176:177], v[168:169], v[218:219], v[176:177] op_sel_hi:[0,1,1] neg_lo:[1,0,0] neg_hi:[1,0,0]
	v_pk_fma_f32 v[178:179], v[168:169], v[220:221], v[178:179] op_sel_hi:[0,1,1] neg_lo:[1,0,0] neg_hi:[1,0,0]
	v_pk_fma_f32 v[180:181], v[168:169], v[222:223], v[180:181] op_sel_hi:[0,1,1] neg_lo:[1,0,0] neg_hi:[1,0,0]
	ds_read_b32 v183, v165 offset:1564
	ds_read_b128 v[204:207], v165 offset:1568
	ds_read_b128 v[208:211], v165 offset:1584
	s_waitcnt lgkmcnt(10)
	v_pk_fma_f32 v[170:171], v[168:169], v[226:227], v[170:171] op_sel:[1,0,0] op_sel_hi:[1,1,1] neg_lo:[1,0,0] neg_hi:[1,0,0]
	v_pk_fma_f32 v[172:173], v[168:169], v[228:229], v[172:173] op_sel:[1,0,0] op_sel_hi:[1,1,1] neg_lo:[1,0,0] neg_hi:[1,0,0]
	v_pk_fma_f32 v[174:175], v[168:169], v[230:231], v[174:175] op_sel:[1,0,0] op_sel_hi:[1,1,1] neg_lo:[1,0,0] neg_hi:[1,0,0]
	v_pk_fma_f32 v[176:177], v[168:169], v[232:233], v[176:177] op_sel:[1,0,0] op_sel_hi:[1,1,1] neg_lo:[1,0,0] neg_hi:[1,0,0]
	v_pk_fma_f32 v[178:179], v[168:169], v[234:235], v[178:179] op_sel:[1,0,0] op_sel_hi:[1,1,1] neg_lo:[1,0,0] neg_hi:[1,0,0]
	v_pk_fma_f32 v[180:181], v[168:169], v[236:237], v[180:181] op_sel:[1,0,0] op_sel_hi:[1,1,1] neg_lo:[1,0,0] neg_hi:[1,0,0]
	ds_read_b128 v[212:215], v165 offset:1824
	ds_read_b128 v[216:219], v165 offset:1840
	s_waitcnt lgkmcnt(8)
	v_fma_f32 v171, -v170, v182, v171
	v_pk_fma_f32 v[172:173], v[170:171], v[184:185], v[172:173] op_sel_hi:[0,1,1] neg_lo:[1,0,0] neg_hi:[1,0,0]
	v_pk_fma_f32 v[174:175], v[170:171], v[186:187], v[174:175] op_sel_hi:[0,1,1] neg_lo:[1,0,0] neg_hi:[1,0,0]
	v_pk_fma_f32 v[176:177], v[170:171], v[188:189], v[176:177] op_sel_hi:[0,1,1] neg_lo:[1,0,0] neg_hi:[1,0,0]
	v_pk_fma_f32 v[178:179], v[170:171], v[190:191], v[178:179] op_sel_hi:[0,1,1] neg_lo:[1,0,0] neg_hi:[1,0,0]
	v_pk_fma_f32 v[180:181], v[170:171], v[192:193], v[180:181] op_sel_hi:[0,1,1] neg_lo:[1,0,0] neg_hi:[1,0,0]
	ds_read_b32 v182, v165 offset:2084
	ds_read_b64 v[184:185], v165 offset:2088
	ds_read_b128 v[186:189], v165 offset:2096
	s_waitcnt lgkmcnt(8)
; __device__ __forceinline__ float delta_prep(const Params& p, int l, int h, bool isP, int grow0, int t0, int nvalid, int bb, char* sm) {
;     ...
;       if (ib > 0) {
;         f32x4 a0 = (f32x4){0.f, 0.f, 0.f, 0.f}, a1 = a0;
;         const bfraw* xb0 = (w < 4) ? XTu + ((2 * w) * 16 + r) * 72 : XTw + ((2 * w - 8) * 16 + r) * 72;
;         const bfraw* xb1 = xb0 + 16 * 72;
; #pragma unroll
;         for (int kk = 0; kk < 2; ++kk) {
;           if (kk * 32 < ib * 16) {
;             bf16x8 am = *(const bf16x8*)(Mb + (ib * 16 + r) * 72 + kk * 32 + q * 8);
;             bf16x8 b0 = *(const bf16x8*)(xb0 + kk * 32 + q * 8);
;             bf16x8 b1 = *(const bf16x8*)(xb1 + kk * 32 + q * 8);
;             a0 = mfma16(am, b0, a0);
;             a1 = mfma16(am, b1, a1);
;           }
;         }
; #pragma unroll
;         for (int g = 0; g < 4; ++g) {
;           float* rp = xs + (ib * 16 + q * 4 + g) * 256 + w * 32 + r;
;           rp[0] -= a0[g];
;           rp[16] -= a1[g];
;         }
;         __syncthreads();
;       }
;       if (tid < 256) {
;         float a[16];
; #pragma unroll
;         for (int ii = 0; ii < 16; ++ii) a[ii] = xs[(ib * 16 + ii) * 256 + tid];
; #pragma unroll
;         for (int j = 0; j < 16; ++j) {
;           const float xj = a[j];
;           const float* mp = MT + (ib * 16 + j) * 64 + ib * 16;
; #pragma unroll
;           for (int ii = j + 1; ii < 16; ++ii) a[ii] -= mp[ii] * xj;
;         }
;         bfraw* dst = (tid < 128) ? XTu + tid * 72 + ib * 16 : XTw + (tid - 128) * 72 + ib * 16;
;         *(uint4*)dst = pack8(a);
;         *(uint4*)(dst + 8) = pack8(a + 8);
;       }
;       __syncthreads();
	v_pk_fma_f32 v[172:173], v[170:171], v[194:195], v[172:173] op_sel:[1,0,0] op_sel_hi:[1,1,1] neg_lo:[1,0,0] neg_hi:[1,0,0]
	v_pk_fma_f32 v[174:175], v[170:171], v[196:197], v[174:175] op_sel:[1,0,0] op_sel_hi:[1,1,1] neg_lo:[1,0,0] neg_hi:[1,0,0]
	v_pk_fma_f32 v[176:177], v[170:171], v[198:199], v[176:177] op_sel:[1,0,0] op_sel_hi:[1,1,1] neg_lo:[1,0,0] neg_hi:[1,0,0]
	v_pk_fma_f32 v[178:179], v[170:171], v[200:201], v[178:179] op_sel:[1,0,0] op_sel_hi:[1,1,1] neg_lo:[1,0,0] neg_hi:[1,0,0]
	v_pk_fma_f32 v[180:181], v[170:171], v[202:203], v[180:181] op_sel:[1,0,0] op_sel_hi:[1,1,1] neg_lo:[1,0,0] neg_hi:[1,0,0]
	ds_read_b64 v[190:191], v165 offset:2344
	ds_read_b128 v[192:195], v165 offset:2352
	s_waitcnt lgkmcnt(7)
	v_fma_f32 v173, -v172, v183, v173
	v_pk_fma_f32 v[174:175], v[172:173], v[204:205], v[174:175] op_sel_hi:[0,1,1] neg_lo:[1,0,0] neg_hi:[1,0,0]
	v_pk_fma_f32 v[176:177], v[172:173], v[206:207], v[176:177] op_sel_hi:[0,1,1] neg_lo:[1,0,0] neg_hi:[1,0,0]
	v_pk_fma_f32 v[178:179], v[172:173], v[208:209], v[178:179] op_sel_hi:[0,1,1] neg_lo:[1,0,0] neg_hi:[1,0,0]
	v_pk_fma_f32 v[180:181], v[172:173], v[210:211], v[180:181] op_sel_hi:[0,1,1] neg_lo:[1,0,0] neg_hi:[1,0,0]
	ds_read_b32 v183, v165 offset:2604
	ds_read_b128 v[196:199], v165 offset:2608
	s_waitcnt lgkmcnt(7)
	v_pk_fma_f32 v[174:175], v[172:173], v[212:213], v[174:175] op_sel:[1,0,0] op_sel_hi:[1,1,1] neg_lo:[1,0,0] neg_hi:[1,0,0]
	v_pk_fma_f32 v[176:177], v[172:173], v[214:215], v[176:177] op_sel:[1,0,0] op_sel_hi:[1,1,1] neg_lo:[1,0,0] neg_hi:[1,0,0]
	v_pk_fma_f32 v[178:179], v[172:173], v[216:217], v[178:179] op_sel:[1,0,0] op_sel_hi:[1,1,1] neg_lo:[1,0,0] neg_hi:[1,0,0]
	v_pk_fma_f32 v[180:181], v[172:173], v[218:219], v[180:181] op_sel:[1,0,0] op_sel_hi:[1,1,1] neg_lo:[1,0,0] neg_hi:[1,0,0]
	ds_read_b128 v[200:203], v165 offset:2864
	s_waitcnt lgkmcnt(5)
	v_fma_f32 v175, -v174, v182, v175
	v_pk_fma_f32 v[176:177], v[174:175], v[184:185], v[176:177] op_sel_hi:[0,1,1] neg_lo:[1,0,0] neg_hi:[1,0,0]
	v_pk_fma_f32 v[178:179], v[174:175], v[186:187], v[178:179] op_sel_hi:[0,1,1] neg_lo:[1,0,0] neg_hi:[1,0,0]
	v_pk_fma_f32 v[180:181], v[174:175], v[188:189], v[180:181] op_sel_hi:[0,1,1] neg_lo:[1,0,0] neg_hi:[1,0,0]
	ds_read_b32 v182, v165 offset:3124
	ds_read_b64 v[184:185], v165 offset:3128
	s_waitcnt lgkmcnt(5)
	v_pk_fma_f32 v[176:177], v[174:175], v[190:191], v[176:177] op_sel:[1,0,0] op_sel_hi:[1,1,1] neg_lo:[1,0,0] neg_hi:[1,0,0]
	v_pk_fma_f32 v[178:179], v[174:175], v[192:193], v[178:179] op_sel:[1,0,0] op_sel_hi:[1,1,1] neg_lo:[1,0,0] neg_hi:[1,0,0]
	v_pk_fma_f32 v[180:181], v[174:175], v[194:195], v[180:181] op_sel:[1,0,0] op_sel_hi:[1,1,1] neg_lo:[1,0,0] neg_hi:[1,0,0]
	ds_read_b64 v[186:187], v165 offset:3384
	s_waitcnt lgkmcnt(4)
	v_fma_f32 v177, -v176, v183, v177
	v_pk_fma_f32 v[178:179], v[176:177], v[196:197], v[178:179] op_sel_hi:[0,1,1] neg_lo:[1,0,0] neg_hi:[1,0,0]
	v_pk_fma_f32 v[180:181], v[176:177], v[198:199], v[180:181] op_sel_hi:[0,1,1] neg_lo:[1,0,0] neg_hi:[1,0,0]
	ds_read_b32 v183, v165 offset:3644
	s_waitcnt lgkmcnt(4)
	v_pk_fma_f32 v[178:179], v[176:177], v[200:201], v[178:179] op_sel:[1,0,0] op_sel_hi:[1,1,1] neg_lo:[1,0,0] neg_hi:[1,0,0]
	v_pk_fma_f32 v[180:181], v[176:177], v[202:203], v[180:181] op_sel:[1,0,0] op_sel_hi:[1,1,1] neg_lo:[1,0,0] neg_hi:[1,0,0]
	s_waitcnt lgkmcnt(2)
	v_fma_f32 v179, -v178, v182, v179
	v_pk_fma_f32 v[180:181], v[178:179], v[184:185], v[180:181] op_sel_hi:[0,1,1] neg_lo:[1,0,0] neg_hi:[1,0,0]
	s_waitcnt lgkmcnt(1)
	v_pk_fma_f32 v[180:181], v[178:179], v[186:187], v[180:181] op_sel:[1,0,0] op_sel_hi:[1,1,1] neg_lo:[1,0,0] neg_hi:[1,0,0]
	s_waitcnt lgkmcnt(0)
	v_fma_f32 v181, -v180, v183, v181
	v_cvt_pk_bf16_f32 v182, v166, v167
	v_cvt_pk_bf16_f32 v183, v168, v169
	v_cvt_pk_bf16_f32 v184, v170, v171
	v_cvt_pk_bf16_f32 v185, v172, v173
	ds_write_b128 v31, v[182:185]
	v_cvt_pk_bf16_f32 v186, v174, v175
	v_cvt_pk_bf16_f32 v187, v176, v177
	v_cvt_pk_bf16_f32 v188, v178, v179
	v_cvt_pk_bf16_f32 v189, v180, v181
	ds_write_b128 v31, v[186:189] offset:16
	v_readlane_b32 s6, v246, 35
.LBB0_1032:
	s_or_b64 exec, exec, s[0:1]
	s_andn2_b64 vcc, exec, s[16:17]
	s_waitcnt lgkmcnt(0)
	s_barrier
	s_cbranch_vccnz .LBB0_1040
	v_lshl_or_b32 v1, v38, 5, v39
	v_lshlrev_b32_e32 v0, 2, v39
	v_mul_lo_u32 v1, v1, s88
	v_lshlrev_b32_e32 v2, 7, v38
	v_add_u32_e32 v1, 0, v1
	v_add3_u32 v8, s89, v0, v2
	v_cndmask_b32_e64 v0, v159, v160, s[2:3]
	v_lshlrev_b32_e32 v2, 1, v41
	v_add3_u32 v38, v1, v0, v2
	v_mad_u32_u24 v0, v42, s88, v19
	ds_read_b128 v[0:3], v0 offset:34816
	ds_read_b128 v[4:7], v38
	ds_read_b128 v[20:23], v38 offset:2304
	v_lshlrev_b32_e32 v9, 12, v27
	v_add_u32_e32 v25, v8, v9
	v_add_u32_e32 v10, 0x4000, v25
	ds_read2_b32 v[8:9], v10 offset1:16
	s_waitcnt lgkmcnt(2)
	v_mfma_f32_16x16x32_bf16 v[4:7], v[0:3], v[4:7], 0
	s_waitcnt lgkmcnt(1)
	v_mfma_f32_16x16x32_bf16 v[0:3], v[0:3], v[20:23], 0
	s_waitcnt lgkmcnt(0)
	s_nop 4
	v_sub_f32_e32 v4, v8, v4
	s_nop 0
	v_sub_f32_e32 v0, v9, v0
	ds_write2_b32 v10, v4, v0 offset1:16
	v_add_u32_e32 v0, 0x4400, v25
	ds_read2_b32 v[8:9], v0 offset1:16
	s_waitcnt lgkmcnt(0)
	v_sub_f32_e32 v4, v8, v5
	v_sub_f32_e32 v1, v9, v1
	ds_write2_b32 v0, v4, v1 offset1:16
	v_add_u32_e32 v4, 0x4800, v25
	ds_read2_b32 v[0:1], v4 offset1:16
	s_waitcnt lgkmcnt(0)
	v_sub_f32_e32 v0, v0, v6
	v_sub_f32_e32 v1, v1, v2
	v_add_u32_e32 v2, 0x4c00, v25
	ds_write2_b32 v4, v0, v1 offset1:16
	ds_read2_b32 v[0:1], v2 offset1:16
	s_waitcnt lgkmcnt(0)
	v_sub_f32_e32 v0, v0, v7
	v_sub_f32_e32 v1, v1, v3
	ds_write2_b32 v2, v0, v1 offset1:16
	s_waitcnt lgkmcnt(0)
	s_barrier
	s_and_saveexec_b64 s[0:1], s[4:5]
	s_cbranch_execz .LBB0_1035
; __device__ __forceinline__ float delta_prep(const Params& p, int l, int h, bool isP, int grow0, int t0, int nvalid, int bb, char* sm) {
;     ...
;       if (ib > 0) {
;         f32x4 a0 = (f32x4){0.f, 0.f, 0.f, 0.f}, a1 = a0;
;         const bfraw* xb0 = (w < 4) ? XTu + ((2 * w) * 16 + r) * 72 : XTw + ((2 * w - 8) * 16 + r) * 72;
;         const bfraw* xb1 = xb0 + 16 * 72;
; #pragma unroll
;         for (int kk = 0; kk < 2; ++kk) {
;           if (kk * 32 < ib * 16) {
;             bf16x8 am = *(const bf16x8*)(Mb + (ib * 16 + r) * 72 + kk * 32 + q * 8);
;             bf16x8 b0 = *(const bf16x8*)(xb0 + kk * 32 + q * 8);
;             bf16x8 b1 = *(const bf16x8*)(xb1 + kk * 32 + q * 8);
;             a0 = mfma16(am, b0, a0);
;             a1 = mfma16(am, b1, a1);
;           }
;         }
; #pragma unroll
;         for (int g = 0; g < 4; ++g) {
;           float* rp = xs + (ib * 16 + q * 4 + g) * 256 + w * 32 + r;
;           rp[0] -= a0[g];
;           rp[16] -= a1[g];
;         }
;         __syncthreads();
;       }
;       if (tid < 256) {
;         float a[16];
; #pragma unroll
;         for (int ii = 0; ii < 16; ++ii) a[ii] = xs[(ib * 16 + ii) * 256 + tid];
; #pragma unroll
;         for (int j = 0; j < 16; ++j) {
;           const float xj = a[j];
;           const float* mp = MT + (ib * 16 + j) * 64 + ib * 16;
; #pragma unroll
;           for (int ii = j + 1; ii < 16; ++ii) a[ii] -= mp[ii] * xj;
;         }
;         bfraw* dst = (tid < 128) ? XTu + tid * 72 + ib * 16 : XTw + (tid - 128) * 72 + ib * 16;
;         *(uint4*)dst = pack8(a);
;         *(uint4*)(dst + 8) = pack8(a + 8);
;       }
;       __syncthreads();
	ds_read2st64_b32 v[166:167], v40 offset0:64 offset1:68
	ds_read2st64_b32 v[168:169], v40 offset0:72 offset1:76
	ds_read2st64_b32 v[170:171], v40 offset0:80 offset1:84
	ds_read2st64_b32 v[172:173], v40 offset0:88 offset1:92
	ds_read2st64_b32 v[174:175], v40 offset0:96 offset1:100
	ds_read2st64_b32 v[176:177], v40 offset0:104 offset1:108
	ds_read2st64_b32 v[178:179], v40 offset0:112 offset1:116
	ds_read2st64_b32 v[180:181], v40 offset0:120 offset1:124
	v_mov_b32_e32 v165, 0x23c00
	ds_read_b32 v182, v165 offset:4164
	ds_read_b64 v[184:185], v165 offset:4168
	ds_read_b128 v[186:189], v165 offset:4176
	ds_read_b128 v[190:193], v165 offset:4192
	ds_read_b128 v[194:197], v165 offset:4208
	ds_read_b64 v[198:199], v165 offset:4424
	ds_read_b128 v[200:203], v165 offset:4432
	ds_read_b128 v[204:207], v165 offset:4448
	ds_read_b128 v[208:211], v165 offset:4464
	ds_read_b32 v183, v165 offset:4684
	ds_read_b128 v[212:215], v165 offset:4688
	ds_read_b128 v[216:219], v165 offset:4704
	ds_read_b128 v[220:223], v165 offset:4720
	s_waitcnt lgkmcnt(13)
	ds_read_b128 v[226:229], v165 offset:4944
	ds_read_b128 v[230:233], v165 offset:4960
	ds_read_b128 v[234:237], v165 offset:4976
	s_waitcnt lgkmcnt(11)
	v_fma_f32 v167, -v166, v182, v167
	v_pk_fma_f32 v[168:169], v[166:167], v[184:185], v[168:169] op_sel_hi:[0,1,1] neg_lo:[1,0,0] neg_hi:[1,0,0]
	v_pk_fma_f32 v[170:171], v[166:167], v[186:187], v[170:171] op_sel_hi:[0,1,1] neg_lo:[1,0,0] neg_hi:[1,0,0]
	v_pk_fma_f32 v[172:173], v[166:167], v[188:189], v[172:173] op_sel_hi:[0,1,1] neg_lo:[1,0,0] neg_hi:[1,0,0]
	v_pk_fma_f32 v[174:175], v[166:167], v[190:191], v[174:175] op_sel_hi:[0,1,1] neg_lo:[1,0,0] neg_hi:[1,0,0]
	v_pk_fma_f32 v[176:177], v[166:167], v[192:193], v[176:177] op_sel_hi:[0,1,1] neg_lo:[1,0,0] neg_hi:[1,0,0]
	v_pk_fma_f32 v[178:179], v[166:167], v[194:195], v[178:179] op_sel_hi:[0,1,1] neg_lo:[1,0,0] neg_hi:[1,0,0]
	v_pk_fma_f32 v[180:181], v[166:167], v[196:197], v[180:181] op_sel_hi:[0,1,1] neg_lo:[1,0,0] neg_hi:[1,0,0]
	ds_read_b32 v182, v165 offset:5204
	ds_read_b64 v[184:185], v165 offset:5208
	ds_read_b128 v[186:189], v165 offset:5216
	ds_read_b128 v[190:193], v165 offset:5232
	s_waitcnt lgkmcnt(11)
	v_pk_fma_f32 v[168:169], v[166:167], v[198:199], v[168:169] op_sel:[1,0,0] op_sel_hi:[1,1,1] neg_lo:[1,0,0] neg_hi:[1,0,0]
	v_pk_fma_f32 v[170:171], v[166:167], v[200:201], v[170:171] op_sel:[1,0,0] op_sel_hi:[1,1,1] neg_lo:[1,0,0] neg_hi:[1,0,0]
	v_pk_fma_f32 v[172:173], v[166:167], v[202:203], v[172:173] op_sel:[1,0,0] op_sel_hi:[1,1,1] neg_lo:[1,0,0] neg_hi:[1,0,0]
	v_pk_fma_f32 v[174:175], v[166:167], v[204:205], v[174:175] op_sel:[1,0,0] op_sel_hi:[1,1,1] neg_lo:[1,0,0] neg_hi:[1,0,0]
	v_pk_fma_f32 v[176:177], v[166:167], v[206:207], v[176:177] op_sel:[1,0,0] op_sel_hi:[1,1,1] neg_lo:[1,0,0] neg_hi:[1,0,0]
	v_pk_fma_f32 v[178:179], v[166:167], v[208:209], v[178:179] op_sel:[1,0,0] op_sel_hi:[1,1,1] neg_lo:[1,0,0] neg_hi:[1,0,0]
	v_pk_fma_f32 v[180:181], v[166:167], v[210:211], v[180:181] op_sel:[1,0,0] op_sel_hi:[1,1,1] neg_lo:[1,0,0] neg_hi:[1,0,0]
	ds_read_b64 v[194:195], v165 offset:5464
	ds_read_b128 v[196:199], v165 offset:5472
	ds_read_b128 v[200:203], v165 offset:5488
	s_waitcnt lgkmcnt(10)
	v_fma_f32 v169, -v168, v183, v169
	v_pk_fma_f32 v[170:171], v[168:169], v[212:213], v[170:171] op_sel_hi:[0,1,1] neg_lo:[1,0,0] neg_hi:[1,0,0]
	v_pk_fma_f32 v[172:173], v[168:169], v[214:215], v[172:173] op_sel_hi:[0,1,1] neg_lo:[1,0,0] neg_hi:[1,0,0]
	v_pk_fma_f32 v[174:175], v[168:169], v[216:217], v[174:175] op_sel_hi:[0,1,1] neg_lo:[1,0,0] neg_hi:[1,0,0]
	v_pk_fma_f32 v[176:177], v[168:169], v[218:219], v[176:177] op_sel_hi:[0,1,1] neg_lo:[1,0,0] neg_hi:[1,0,0]
	v_pk_fma_f32 v[178:179], v[168:169], v[220:221], v[178:179] op_sel_hi:[0,1,1] neg_lo:[1,0,0] neg_hi:[1,0,0]
	v_pk_fma_f32 v[180:181], v[168:169], v[222:223], v[180:181] op_sel_hi:[0,1,1] neg_lo:[1,0,0] neg_hi:[1,0,0]
	ds_read_b32 v183, v165 offset:5724
	ds_read_b128 v[204:207], v165 offset:5728
	ds_read_b128 v[208:211], v165 offset:5744
	s_waitcnt lgkmcnt(10)
	v_pk_fma_f32 v[170:171], v[168:169], v[226:227], v[170:171] op_sel:[1,0,0] op_sel_hi:[1,1,1] neg_lo:[1,0,0] neg_hi:[1,0,0]
	v_pk_fma_f32 v[172:173], v[168:169], v[228:229], v[172:173] op_sel:[1,0,0] op_sel_hi:[1,1,1] neg_lo:[1,0,0] neg_hi:[1,0,0]
	v_pk_fma_f32 v[174:175], v[168:169], v[230:231], v[174:175] op_sel:[1,0,0] op_sel_hi:[1,1,1] neg_lo:[1,0,0] neg_hi:[1,0,0]
	v_pk_fma_f32 v[176:177], v[168:169], v[232:233], v[176:177] op_sel:[1,0,0] op_sel_hi:[1,1,1] neg_lo:[1,0,0] neg_hi:[1,0,0]
	v_pk_fma_f32 v[178:179], v[168:169], v[234:235], v[178:179] op_sel:[1,0,0] op_sel_hi:[1,1,1] neg_lo:[1,0,0] neg_hi:[1,0,0]
	v_pk_fma_f32 v[180:181], v[168:169], v[236:237], v[180:181] op_sel:[1,0,0] op_sel_hi:[1,1,1] neg_lo:[1,0,0] neg_hi:[1,0,0]
	ds_read_b128 v[212:215], v165 offset:5984
	ds_read_b128 v[216:219], v165 offset:6000
	s_waitcnt lgkmcnt(8)
	v_fma_f32 v171, -v170, v182, v171
	v_pk_fma_f32 v[172:173], v[170:171], v[184:185], v[172:173] op_sel_hi:[0,1,1] neg_lo:[1,0,0] neg_hi:[1,0,0]
	v_pk_fma_f32 v[174:175], v[170:171], v[186:187], v[174:175] op_sel_hi:[0,1,1] neg_lo:[1,0,0] neg_hi:[1,0,0]
	v_pk_fma_f32 v[176:177], v[170:171], v[188:189], v[176:177] op_sel_hi:[0,1,1] neg_lo:[1,0,0] neg_hi:[1,0,0]
	v_pk_fma_f32 v[178:179], v[170:171], v[190:191], v[178:179] op_sel_hi:[0,1,1] neg_lo:[1,0,0] neg_hi:[1,0,0]
	v_pk_fma_f32 v[180:181], v[170:171], v[192:193], v[180:181] op_sel_hi:[0,1,1] neg_lo:[1,0,0] neg_hi:[1,0,0]
	ds_read_b32 v182, v165 offset:6244
	ds_read_b64 v[184:185], v165 offset:6248
	ds_read_b128 v[186:189], v165 offset:6256
	s_waitcnt lgkmcnt(8)
; __device__ __forceinline__ float delta_prep(const Params& p, int l, int h, bool isP, int grow0, int t0, int nvalid, int bb, char* sm) {
;     ...
;       if (ib > 0) {
;         f32x4 a0 = (f32x4){0.f, 0.f, 0.f, 0.f}, a1 = a0;
;         const bfraw* xb0 = (w < 4) ? XTu + ((2 * w) * 16 + r) * 72 : XTw + ((2 * w - 8) * 16 + r) * 72;
;         const bfraw* xb1 = xb0 + 16 * 72;
; #pragma unroll
;         for (int kk = 0; kk < 2; ++kk) {
;           if (kk * 32 < ib * 16) {
;             bf16x8 am = *(const bf16x8*)(Mb + (ib * 16 + r) * 72 + kk * 32 + q * 8);
;             bf16x8 b0 = *(const bf16x8*)(xb0 + kk * 32 + q * 8);
;             bf16x8 b1 = *(const bf16x8*)(xb1 + kk * 32 + q * 8);
;             a0 = mfma16(am, b0, a0);
;             a1 = mfma16(am, b1, a1);
;           }
;         }
; #pragma unroll
;         for (int g = 0; g < 4; ++g) {
;           float* rp = xs + (ib * 16 + q * 4 + g) * 256 + w * 32 + r;
;           rp[0] -= a0[g];
;           rp[16] -= a1[g];
;         }
;         __syncthreads();
;       }
;       if (tid < 256) {
;         float a[16];
; #pragma unroll
;         for (int ii = 0; ii < 16; ++ii) a[ii] = xs[(ib * 16 + ii) * 256 + tid];
; #pragma unroll
;         for (int j = 0; j < 16; ++j) {
;           const float xj = a[j];
;           const float* mp = MT + (ib * 16 + j) * 64 + ib * 16;
; #pragma unroll
;           for (int ii = j + 1; ii < 16; ++ii) a[ii] -= mp[ii] * xj;
;         }
;         bfraw* dst = (tid < 128) ? XTu + tid * 72 + ib * 16 : XTw + (tid - 128) * 72 + ib * 16;
;         *(uint4*)dst = pack8(a);
;         *(uint4*)(dst + 8) = pack8(a + 8);
;       }
;       __syncthreads();
	v_pk_fma_f32 v[172:173], v[170:171], v[194:195], v[172:173] op_sel:[1,0,0] op_sel_hi:[1,1,1] neg_lo:[1,0,0] neg_hi:[1,0,0]
	v_pk_fma_f32 v[174:175], v[170:171], v[196:197], v[174:175] op_sel:[1,0,0] op_sel_hi:[1,1,1] neg_lo:[1,0,0] neg_hi:[1,0,0]
	v_pk_fma_f32 v[176:177], v[170:171], v[198:199], v[176:177] op_sel:[1,0,0] op_sel_hi:[1,1,1] neg_lo:[1,0,0] neg_hi:[1,0,0]
	v_pk_fma_f32 v[178:179], v[170:171], v[200:201], v[178:179] op_sel:[1,0,0] op_sel_hi:[1,1,1] neg_lo:[1,0,0] neg_hi:[1,0,0]
	v_pk_fma_f32 v[180:181], v[170:171], v[202:203], v[180:181] op_sel:[1,0,0] op_sel_hi:[1,1,1] neg_lo:[1,0,0] neg_hi:[1,0,0]
	ds_read_b64 v[190:191], v165 offset:6504
	ds_read_b128 v[192:195], v165 offset:6512
	s_waitcnt lgkmcnt(7)
	v_fma_f32 v173, -v172, v183, v173
	v_pk_fma_f32 v[174:175], v[172:173], v[204:205], v[174:175] op_sel_hi:[0,1,1] neg_lo:[1,0,0] neg_hi:[1,0,0]
	v_pk_fma_f32 v[176:177], v[172:173], v[206:207], v[176:177] op_sel_hi:[0,1,1] neg_lo:[1,0,0] neg_hi:[1,0,0]
	v_pk_fma_f32 v[178:179], v[172:173], v[208:209], v[178:179] op_sel_hi:[0,1,1] neg_lo:[1,0,0] neg_hi:[1,0,0]
	v_pk_fma_f32 v[180:181], v[172:173], v[210:211], v[180:181] op_sel_hi:[0,1,1] neg_lo:[1,0,0] neg_hi:[1,0,0]
	ds_read_b32 v183, v165 offset:6764
	ds_read_b128 v[196:199], v165 offset:6768
	s_waitcnt lgkmcnt(7)
	v_pk_fma_f32 v[174:175], v[172:173], v[212:213], v[174:175] op_sel:[1,0,0] op_sel_hi:[1,1,1] neg_lo:[1,0,0] neg_hi:[1,0,0]
	v_pk_fma_f32 v[176:177], v[172:173], v[214:215], v[176:177] op_sel:[1,0,0] op_sel_hi:[1,1,1] neg_lo:[1,0,0] neg_hi:[1,0,0]
	v_pk_fma_f32 v[178:179], v[172:173], v[216:217], v[178:179] op_sel:[1,0,0] op_sel_hi:[1,1,1] neg_lo:[1,0,0] neg_hi:[1,0,0]
	v_pk_fma_f32 v[180:181], v[172:173], v[218:219], v[180:181] op_sel:[1,0,0] op_sel_hi:[1,1,1] neg_lo:[1,0,0] neg_hi:[1,0,0]
	ds_read_b128 v[200:203], v165 offset:7024
	s_waitcnt lgkmcnt(5)
	v_fma_f32 v175, -v174, v182, v175
	v_pk_fma_f32 v[176:177], v[174:175], v[184:185], v[176:177] op_sel_hi:[0,1,1] neg_lo:[1,0,0] neg_hi:[1,0,0]
	v_pk_fma_f32 v[178:179], v[174:175], v[186:187], v[178:179] op_sel_hi:[0,1,1] neg_lo:[1,0,0] neg_hi:[1,0,0]
	v_pk_fma_f32 v[180:181], v[174:175], v[188:189], v[180:181] op_sel_hi:[0,1,1] neg_lo:[1,0,0] neg_hi:[1,0,0]
	ds_read_b32 v182, v165 offset:7284
	ds_read_b64 v[184:185], v165 offset:7288
	s_waitcnt lgkmcnt(5)
	v_pk_fma_f32 v[176:177], v[174:175], v[190:191], v[176:177] op_sel:[1,0,0] op_sel_hi:[1,1,1] neg_lo:[1,0,0] neg_hi:[1,0,0]
	v_pk_fma_f32 v[178:179], v[174:175], v[192:193], v[178:179] op_sel:[1,0,0] op_sel_hi:[1,1,1] neg_lo:[1,0,0] neg_hi:[1,0,0]
	v_pk_fma_f32 v[180:181], v[174:175], v[194:195], v[180:181] op_sel:[1,0,0] op_sel_hi:[1,1,1] neg_lo:[1,0,0] neg_hi:[1,0,0]
	ds_read_b64 v[186:187], v165 offset:7544
	s_waitcnt lgkmcnt(4)
	v_fma_f32 v177, -v176, v183, v177
	v_pk_fma_f32 v[178:179], v[176:177], v[196:197], v[178:179] op_sel_hi:[0,1,1] neg_lo:[1,0,0] neg_hi:[1,0,0]
	v_pk_fma_f32 v[180:181], v[176:177], v[198:199], v[180:181] op_sel_hi:[0,1,1] neg_lo:[1,0,0] neg_hi:[1,0,0]
	ds_read_b32 v183, v165 offset:7804
	s_waitcnt lgkmcnt(4)
	v_pk_fma_f32 v[178:179], v[176:177], v[200:201], v[178:179] op_sel:[1,0,0] op_sel_hi:[1,1,1] neg_lo:[1,0,0] neg_hi:[1,0,0]
	v_pk_fma_f32 v[180:181], v[176:177], v[202:203], v[180:181] op_sel:[1,0,0] op_sel_hi:[1,1,1] neg_lo:[1,0,0] neg_hi:[1,0,0]
	s_waitcnt lgkmcnt(2)
	v_fma_f32 v179, -v178, v182, v179
	v_pk_fma_f32 v[180:181], v[178:179], v[184:185], v[180:181] op_sel_hi:[0,1,1] neg_lo:[1,0,0] neg_hi:[1,0,0]
	s_waitcnt lgkmcnt(1)
	v_pk_fma_f32 v[180:181], v[178:179], v[186:187], v[180:181] op_sel:[1,0,0] op_sel_hi:[1,1,1] neg_lo:[1,0,0] neg_hi:[1,0,0]
	s_waitcnt lgkmcnt(0)
	v_fma_f32 v181, -v180, v183, v181
	v_cvt_pk_bf16_f32 v182, v166, v167
	v_cvt_pk_bf16_f32 v183, v168, v169
	v_cvt_pk_bf16_f32 v184, v170, v171
	v_cvt_pk_bf16_f32 v185, v172, v173
	ds_write_b128 v31, v[182:185] offset:32
	v_cvt_pk_bf16_f32 v186, v174, v175
	v_cvt_pk_bf16_f32 v187, v176, v177
	v_cvt_pk_bf16_f32 v188, v178, v179
	v_cvt_pk_bf16_f32 v189, v180, v181
	ds_write_b128 v31, v[186:189] offset:48
	v_readlane_b32 s2, v245, 12
.LBB0_1035:
	s_or_b64 exec, exec, s[0:1]
	v_mad_u32_u24 v0, v37, s88, v19
	s_waitcnt lgkmcnt(0)
	s_barrier
	ds_read_b128 v[0:3], v0 offset:34816
	ds_read_b128 v[4:7], v38
	ds_read_b128 v[20:23], v38 offset:2304
	v_add_u32_e32 v10, 0x8000, v25
	ds_read2_b32 v[8:9], v10 offset1:16
	s_waitcnt lgkmcnt(2)
	v_mfma_f32_16x16x32_bf16 v[4:7], v[0:3], v[4:7], 0
	s_waitcnt lgkmcnt(1)
	v_mfma_f32_16x16x32_bf16 v[0:3], v[0:3], v[20:23], 0
	s_waitcnt lgkmcnt(0)
	s_nop 4
	v_sub_f32_e32 v4, v8, v4
	s_nop 0
	v_sub_f32_e32 v0, v9, v0
	ds_write2_b32 v10, v4, v0 offset1:16
	v_add_u32_e32 v0, 0x8400, v25
	ds_read2_b32 v[8:9], v0 offset1:16
	s_waitcnt lgkmcnt(0)
	v_sub_f32_e32 v4, v8, v5
	v_sub_f32_e32 v1, v9, v1
	ds_write2_b32 v0, v4, v1 offset1:16
	v_add_u32_e32 v4, 0x8800, v25
	ds_read2_b32 v[0:1], v4 offset1:16
	s_waitcnt lgkmcnt(0)
	v_sub_f32_e32 v0, v0, v6
	v_sub_f32_e32 v1, v1, v2
	v_add_u32_e32 v2, 0x8c00, v25
	ds_write2_b32 v4, v0, v1 offset1:16
	ds_read2_b32 v[0:1], v2 offset1:16
	s_waitcnt lgkmcnt(0)
	v_sub_f32_e32 v0, v0, v7
	v_sub_f32_e32 v1, v1, v3
	ds_write2_b32 v2, v0, v1 offset1:16
	s_waitcnt lgkmcnt(0)
	s_barrier
	s_and_saveexec_b64 s[0:1], s[4:5]
	s_cbranch_execz .LBB0_1037
; __device__ __forceinline__ float delta_prep(const Params& p, int l, int h, bool isP, int grow0, int t0, int nvalid, int bb, char* sm) {
;     ...
;       if (ib > 0) {
;         f32x4 a0 = (f32x4){0.f, 0.f, 0.f, 0.f}, a1 = a0;
;         const bfraw* xb0 = (w < 4) ? XTu + ((2 * w) * 16 + r) * 72 : XTw + ((2 * w - 8) * 16 + r) * 72;
;         const bfraw* xb1 = xb0 + 16 * 72;
; #pragma unroll
;         for (int kk = 0; kk < 2; ++kk) {
;           if (kk * 32 < ib * 16) {
;             bf16x8 am = *(const bf16x8*)(Mb + (ib * 16 + r) * 72 + kk * 32 + q * 8);
;             bf16x8 b0 = *(const bf16x8*)(xb0 + kk * 32 + q * 8);
;             bf16x8 b1 = *(const bf16x8*)(xb1 + kk * 32 + q * 8);
;             a0 = mfma16(am, b0, a0);
;             a1 = mfma16(am, b1, a1);
;           }
;         }
; #pragma unroll
;         for (int g = 0; g < 4; ++g) {
;           float* rp = xs + (ib * 16 + q * 4 + g) * 256 + w * 32 + r;
;           rp[0] -= a0[g];
;           rp[16] -= a1[g];
;         }
;         __syncthreads();
;       }
;       if (tid < 256) {
;         float a[16];
; #pragma unroll
;         for (int ii = 0; ii < 16; ++ii) a[ii] = xs[(ib * 16 + ii) * 256 + tid];
; #pragma unroll
;         for (int j = 0; j < 16; ++j) {
;           const float xj = a[j];
;           const float* mp = MT + (ib * 16 + j) * 64 + ib * 16;
; #pragma unroll
;           for (int ii = j + 1; ii < 16; ++ii) a[ii] -= mp[ii] * xj;
;         }
;         bfraw* dst = (tid < 128) ? XTu + tid * 72 + ib * 16 : XTw + (tid - 128) * 72 + ib * 16;
;         *(uint4*)dst = pack8(a);
;         *(uint4*)(dst + 8) = pack8(a + 8);
;       }
;       __syncthreads();
	ds_read2st64_b32 v[166:167], v40 offset0:128 offset1:132
	ds_read2st64_b32 v[168:169], v40 offset0:136 offset1:140
	ds_read2st64_b32 v[170:171], v40 offset0:144 offset1:148
	ds_read2st64_b32 v[172:173], v40 offset0:152 offset1:156
	ds_read2st64_b32 v[174:175], v40 offset0:160 offset1:164
	ds_read2st64_b32 v[176:177], v40 offset0:168 offset1:172
	ds_read2st64_b32 v[178:179], v40 offset0:176 offset1:180
	ds_read2st64_b32 v[180:181], v40 offset0:184 offset1:188
	v_mov_b32_e32 v165, 0x23c00
	ds_read_b32 v182, v165 offset:8324
	ds_read_b64 v[184:185], v165 offset:8328
	ds_read_b128 v[186:189], v165 offset:8336
	ds_read_b128 v[190:193], v165 offset:8352
	ds_read_b128 v[194:197], v165 offset:8368
	ds_read_b64 v[198:199], v165 offset:8584
	ds_read_b128 v[200:203], v165 offset:8592
	ds_read_b128 v[204:207], v165 offset:8608
	ds_read_b128 v[208:211], v165 offset:8624
	ds_read_b32 v183, v165 offset:8844
	ds_read_b128 v[212:215], v165 offset:8848
	ds_read_b128 v[216:219], v165 offset:8864
	ds_read_b128 v[220:223], v165 offset:8880
	s_waitcnt lgkmcnt(13)
	ds_read_b128 v[226:229], v165 offset:9104
	ds_read_b128 v[230:233], v165 offset:9120
	ds_read_b128 v[234:237], v165 offset:9136
	s_waitcnt lgkmcnt(11)
	v_fma_f32 v167, -v166, v182, v167
	v_pk_fma_f32 v[168:169], v[166:167], v[184:185], v[168:169] op_sel_hi:[0,1,1] neg_lo:[1,0,0] neg_hi:[1,0,0]
	v_pk_fma_f32 v[170:171], v[166:167], v[186:187], v[170:171] op_sel_hi:[0,1,1] neg_lo:[1,0,0] neg_hi:[1,0,0]
	v_pk_fma_f32 v[172:173], v[166:167], v[188:189], v[172:173] op_sel_hi:[0,1,1] neg_lo:[1,0,0] neg_hi:[1,0,0]
	v_pk_fma_f32 v[174:175], v[166:167], v[190:191], v[174:175] op_sel_hi:[0,1,1] neg_lo:[1,0,0] neg_hi:[1,0,0]
	v_pk_fma_f32 v[176:177], v[166:167], v[192:193], v[176:177] op_sel_hi:[0,1,1] neg_lo:[1,0,0] neg_hi:[1,0,0]
	v_pk_fma_f32 v[178:179], v[166:167], v[194:195], v[178:179] op_sel_hi:[0,1,1] neg_lo:[1,0,0] neg_hi:[1,0,0]
	v_pk_fma_f32 v[180:181], v[166:167], v[196:197], v[180:181] op_sel_hi:[0,1,1] neg_lo:[1,0,0] neg_hi:[1,0,0]
	ds_read_b32 v182, v165 offset:9364
	ds_read_b64 v[184:185], v165 offset:9368
	ds_read_b128 v[186:189], v165 offset:9376
	ds_read_b128 v[190:193], v165 offset:9392
	s_waitcnt lgkmcnt(11)
	v_pk_fma_f32 v[168:169], v[166:167], v[198:199], v[168:169] op_sel:[1,0,0] op_sel_hi:[1,1,1] neg_lo:[1,0,0] neg_hi:[1,0,0]
	v_pk_fma_f32 v[170:171], v[166:167], v[200:201], v[170:171] op_sel:[1,0,0] op_sel_hi:[1,1,1] neg_lo:[1,0,0] neg_hi:[1,0,0]
	v_pk_fma_f32 v[172:173], v[166:167], v[202:203], v[172:173] op_sel:[1,0,0] op_sel_hi:[1,1,1] neg_lo:[1,0,0] neg_hi:[1,0,0]
	v_pk_fma_f32 v[174:175], v[166:167], v[204:205], v[174:175] op_sel:[1,0,0] op_sel_hi:[1,1,1] neg_lo:[1,0,0] neg_hi:[1,0,0]
	v_pk_fma_f32 v[176:177], v[166:167], v[206:207], v[176:177] op_sel:[1,0,0] op_sel_hi:[1,1,1] neg_lo:[1,0,0] neg_hi:[1,0,0]
	v_pk_fma_f32 v[178:179], v[166:167], v[208:209], v[178:179] op_sel:[1,0,0] op_sel_hi:[1,1,1] neg_lo:[1,0,0] neg_hi:[1,0,0]
	v_pk_fma_f32 v[180:181], v[166:167], v[210:211], v[180:181] op_sel:[1,0,0] op_sel_hi:[1,1,1] neg_lo:[1,0,0] neg_hi:[1,0,0]
	ds_read_b64 v[194:195], v165 offset:9624
	ds_read_b128 v[196:199], v165 offset:9632
	ds_read_b128 v[200:203], v165 offset:9648
	s_waitcnt lgkmcnt(10)
	v_fma_f32 v169, -v168, v183, v169
	v_pk_fma_f32 v[170:171], v[168:169], v[212:213], v[170:171] op_sel_hi:[0,1,1] neg_lo:[1,0,0] neg_hi:[1,0,0]
	v_pk_fma_f32 v[172:173], v[168:169], v[214:215], v[172:173] op_sel_hi:[0,1,1] neg_lo:[1,0,0] neg_hi:[1,0,0]
	v_pk_fma_f32 v[174:175], v[168:169], v[216:217], v[174:175] op_sel_hi:[0,1,1] neg_lo:[1,0,0] neg_hi:[1,0,0]
	v_pk_fma_f32 v[176:177], v[168:169], v[218:219], v[176:177] op_sel_hi:[0,1,1] neg_lo:[1,0,0] neg_hi:[1,0,0]
	v_pk_fma_f32 v[178:179], v[168:169], v[220:221], v[178:179] op_sel_hi:[0,1,1] neg_lo:[1,0,0] neg_hi:[1,0,0]
	v_pk_fma_f32 v[180:181], v[168:169], v[222:223], v[180:181] op_sel_hi:[0,1,1] neg_lo:[1,0,0] neg_hi:[1,0,0]
	ds_read_b32 v183, v165 offset:9884
	ds_read_b128 v[204:207], v165 offset:9888
	ds_read_b128 v[208:211], v165 offset:9904
	s_waitcnt lgkmcnt(10)
	v_pk_fma_f32 v[170:171], v[168:169], v[226:227], v[170:171] op_sel:[1,0,0] op_sel_hi:[1,1,1] neg_lo:[1,0,0] neg_hi:[1,0,0]
	v_pk_fma_f32 v[172:173], v[168:169], v[228:229], v[172:173] op_sel:[1,0,0] op_sel_hi:[1,1,1] neg_lo:[1,0,0] neg_hi:[1,0,0]
	v_pk_fma_f32 v[174:175], v[168:169], v[230:231], v[174:175] op_sel:[1,0,0] op_sel_hi:[1,1,1] neg_lo:[1,0,0] neg_hi:[1,0,0]
	v_pk_fma_f32 v[176:177], v[168:169], v[232:233], v[176:177] op_sel:[1,0,0] op_sel_hi:[1,1,1] neg_lo:[1,0,0] neg_hi:[1,0,0]
	v_pk_fma_f32 v[178:179], v[168:169], v[234:235], v[178:179] op_sel:[1,0,0] op_sel_hi:[1,1,1] neg_lo:[1,0,0] neg_hi:[1,0,0]
	v_pk_fma_f32 v[180:181], v[168:169], v[236:237], v[180:181] op_sel:[1,0,0] op_sel_hi:[1,1,1] neg_lo:[1,0,0] neg_hi:[1,0,0]
	ds_read_b128 v[212:215], v165 offset:10144
	ds_read_b128 v[216:219], v165 offset:10160
	s_waitcnt lgkmcnt(8)
	v_fma_f32 v171, -v170, v182, v171
	v_pk_fma_f32 v[172:173], v[170:171], v[184:185], v[172:173] op_sel_hi:[0,1,1] neg_lo:[1,0,0] neg_hi:[1,0,0]
	v_pk_fma_f32 v[174:175], v[170:171], v[186:187], v[174:175] op_sel_hi:[0,1,1] neg_lo:[1,0,0] neg_hi:[1,0,0]
	v_pk_fma_f32 v[176:177], v[170:171], v[188:189], v[176:177] op_sel_hi:[0,1,1] neg_lo:[1,0,0] neg_hi:[1,0,0]
	v_pk_fma_f32 v[178:179], v[170:171], v[190:191], v[178:179] op_sel_hi:[0,1,1] neg_lo:[1,0,0] neg_hi:[1,0,0]
	v_pk_fma_f32 v[180:181], v[170:171], v[192:193], v[180:181] op_sel_hi:[0,1,1] neg_lo:[1,0,0] neg_hi:[1,0,0]
	ds_read_b32 v182, v165 offset:10404
	ds_read_b64 v[184:185], v165 offset:10408
	ds_read_b128 v[186:189], v165 offset:10416
	s_waitcnt lgkmcnt(8)
; __device__ __forceinline__ float delta_prep(const Params& p, int l, int h, bool isP, int grow0, int t0, int nvalid, int bb, char* sm) {
;     ...
;       if (ib > 0) {
;         f32x4 a0 = (f32x4){0.f, 0.f, 0.f, 0.f}, a1 = a0;
;         const bfraw* xb0 = (w < 4) ? XTu + ((2 * w) * 16 + r) * 72 : XTw + ((2 * w - 8) * 16 + r) * 72;
;         const bfraw* xb1 = xb0 + 16 * 72;
; #pragma unroll
;         for (int kk = 0; kk < 2; ++kk) {
;           if (kk * 32 < ib * 16) {
;             bf16x8 am = *(const bf16x8*)(Mb + (ib * 16 + r) * 72 + kk * 32 + q * 8);
;             bf16x8 b0 = *(const bf16x8*)(xb0 + kk * 32 + q * 8);
;             bf16x8 b1 = *(const bf16x8*)(xb1 + kk * 32 + q * 8);
;             a0 = mfma16(am, b0, a0);
;             a1 = mfma16(am, b1, a1);
;           }
;         }
; #pragma unroll
;         for (int g = 0; g < 4; ++g) {
;           float* rp = xs + (ib * 16 + q * 4 + g) * 256 + w * 32 + r;
;           rp[0] -= a0[g];
;           rp[16] -= a1[g];
;         }
;         __syncthreads();
;       }
;       if (tid < 256) {
;         float a[16];
; #pragma unroll
;         for (int ii = 0; ii < 16; ++ii) a[ii] = xs[(ib * 16 + ii) * 256 + tid];
; #pragma unroll
;         for (int j = 0; j < 16; ++j) {
;           const float xj = a[j];
;           const float* mp = MT + (ib * 16 + j) * 64 + ib * 16;
; #pragma unroll
;           for (int ii = j + 1; ii < 16; ++ii) a[ii] -= mp[ii] * xj;
;         }
;         bfraw* dst = (tid < 128) ? XTu + tid * 72 + ib * 16 : XTw + (tid - 128) * 72 + ib * 16;
;         *(uint4*)dst = pack8(a);
;         *(uint4*)(dst + 8) = pack8(a + 8);
;       }
;       __syncthreads();
	v_pk_fma_f32 v[172:173], v[170:171], v[194:195], v[172:173] op_sel:[1,0,0] op_sel_hi:[1,1,1] neg_lo:[1,0,0] neg_hi:[1,0,0]
	v_pk_fma_f32 v[174:175], v[170:171], v[196:197], v[174:175] op_sel:[1,0,0] op_sel_hi:[1,1,1] neg_lo:[1,0,0] neg_hi:[1,0,0]
	v_pk_fma_f32 v[176:177], v[170:171], v[198:199], v[176:177] op_sel:[1,0,0] op_sel_hi:[1,1,1] neg_lo:[1,0,0] neg_hi:[1,0,0]
	v_pk_fma_f32 v[178:179], v[170:171], v[200:201], v[178:179] op_sel:[1,0,0] op_sel_hi:[1,1,1] neg_lo:[1,0,0] neg_hi:[1,0,0]
	v_pk_fma_f32 v[180:181], v[170:171], v[202:203], v[180:181] op_sel:[1,0,0] op_sel_hi:[1,1,1] neg_lo:[1,0,0] neg_hi:[1,0,0]
	ds_read_b64 v[190:191], v165 offset:10664
	ds_read_b128 v[192:195], v165 offset:10672
	s_waitcnt lgkmcnt(7)
	v_fma_f32 v173, -v172, v183, v173
	v_pk_fma_f32 v[174:175], v[172:173], v[204:205], v[174:175] op_sel_hi:[0,1,1] neg_lo:[1,0,0] neg_hi:[1,0,0]
	v_pk_fma_f32 v[176:177], v[172:173], v[206:207], v[176:177] op_sel_hi:[0,1,1] neg_lo:[1,0,0] neg_hi:[1,0,0]
	v_pk_fma_f32 v[178:179], v[172:173], v[208:209], v[178:179] op_sel_hi:[0,1,1] neg_lo:[1,0,0] neg_hi:[1,0,0]
	v_pk_fma_f32 v[180:181], v[172:173], v[210:211], v[180:181] op_sel_hi:[0,1,1] neg_lo:[1,0,0] neg_hi:[1,0,0]
	ds_read_b32 v183, v165 offset:10924
	ds_read_b128 v[196:199], v165 offset:10928
	s_waitcnt lgkmcnt(7)
	v_pk_fma_f32 v[174:175], v[172:173], v[212:213], v[174:175] op_sel:[1,0,0] op_sel_hi:[1,1,1] neg_lo:[1,0,0] neg_hi:[1,0,0]
	v_pk_fma_f32 v[176:177], v[172:173], v[214:215], v[176:177] op_sel:[1,0,0] op_sel_hi:[1,1,1] neg_lo:[1,0,0] neg_hi:[1,0,0]
	v_pk_fma_f32 v[178:179], v[172:173], v[216:217], v[178:179] op_sel:[1,0,0] op_sel_hi:[1,1,1] neg_lo:[1,0,0] neg_hi:[1,0,0]
	v_pk_fma_f32 v[180:181], v[172:173], v[218:219], v[180:181] op_sel:[1,0,0] op_sel_hi:[1,1,1] neg_lo:[1,0,0] neg_hi:[1,0,0]
	ds_read_b128 v[200:203], v165 offset:11184
	s_waitcnt lgkmcnt(5)
	v_fma_f32 v175, -v174, v182, v175
	v_pk_fma_f32 v[176:177], v[174:175], v[184:185], v[176:177] op_sel_hi:[0,1,1] neg_lo:[1,0,0] neg_hi:[1,0,0]
	v_pk_fma_f32 v[178:179], v[174:175], v[186:187], v[178:179] op_sel_hi:[0,1,1] neg_lo:[1,0,0] neg_hi:[1,0,0]
	v_pk_fma_f32 v[180:181], v[174:175], v[188:189], v[180:181] op_sel_hi:[0,1,1] neg_lo:[1,0,0] neg_hi:[1,0,0]
	ds_read_b32 v182, v165 offset:11444
	ds_read_b64 v[184:185], v165 offset:11448
	s_waitcnt lgkmcnt(5)
	v_pk_fma_f32 v[176:177], v[174:175], v[190:191], v[176:177] op_sel:[1,0,0] op_sel_hi:[1,1,1] neg_lo:[1,0,0] neg_hi:[1,0,0]
	v_pk_fma_f32 v[178:179], v[174:175], v[192:193], v[178:179] op_sel:[1,0,0] op_sel_hi:[1,1,1] neg_lo:[1,0,0] neg_hi:[1,0,0]
	v_pk_fma_f32 v[180:181], v[174:175], v[194:195], v[180:181] op_sel:[1,0,0] op_sel_hi:[1,1,1] neg_lo:[1,0,0] neg_hi:[1,0,0]
	ds_read_b64 v[186:187], v165 offset:11704
	s_waitcnt lgkmcnt(4)
	v_fma_f32 v177, -v176, v183, v177
	v_pk_fma_f32 v[178:179], v[176:177], v[196:197], v[178:179] op_sel_hi:[0,1,1] neg_lo:[1,0,0] neg_hi:[1,0,0]
	v_pk_fma_f32 v[180:181], v[176:177], v[198:199], v[180:181] op_sel_hi:[0,1,1] neg_lo:[1,0,0] neg_hi:[1,0,0]
	ds_read_b32 v183, v165 offset:11964
	s_waitcnt lgkmcnt(4)
	v_pk_fma_f32 v[178:179], v[176:177], v[200:201], v[178:179] op_sel:[1,0,0] op_sel_hi:[1,1,1] neg_lo:[1,0,0] neg_hi:[1,0,0]
	v_pk_fma_f32 v[180:181], v[176:177], v[202:203], v[180:181] op_sel:[1,0,0] op_sel_hi:[1,1,1] neg_lo:[1,0,0] neg_hi:[1,0,0]
	s_waitcnt lgkmcnt(2)
	v_fma_f32 v179, -v178, v182, v179
	v_pk_fma_f32 v[180:181], v[178:179], v[184:185], v[180:181] op_sel_hi:[0,1,1] neg_lo:[1,0,0] neg_hi:[1,0,0]
	s_waitcnt lgkmcnt(1)
	v_pk_fma_f32 v[180:181], v[178:179], v[186:187], v[180:181] op_sel:[1,0,0] op_sel_hi:[1,1,1] neg_lo:[1,0,0] neg_hi:[1,0,0]
	s_waitcnt lgkmcnt(0)
	v_fma_f32 v181, -v180, v183, v181
	v_cvt_pk_bf16_f32 v182, v166, v167
	v_cvt_pk_bf16_f32 v183, v168, v169
	v_cvt_pk_bf16_f32 v184, v170, v171
	v_cvt_pk_bf16_f32 v185, v172, v173
	ds_write_b128 v31, v[182:185] offset:64
	v_cvt_pk_bf16_f32 v186, v174, v175
	v_cvt_pk_bf16_f32 v187, v176, v177
	v_cvt_pk_bf16_f32 v188, v178, v179
	v_cvt_pk_bf16_f32 v189, v180, v181
	ds_write_b128 v31, v[186:189] offset:80
	v_readlane_b32 s2, v245, 52
.LBB0_1037:
	s_or_b64 exec, exec, s[0:1]
	v_mad_u32_u24 v12, v11, s88, v19
	s_waitcnt lgkmcnt(0)
	s_barrier
	ds_read_b128 v[0:3], v12 offset:34816
	ds_read_b128 v[4:7], v38
	ds_read_b128 v[8:11], v38 offset:2304
	s_waitcnt lgkmcnt(1)
	v_mfma_f32_16x16x32_bf16 v[4:7], v[0:3], v[4:7], 0
	s_waitcnt lgkmcnt(0)
	v_mfma_f32_16x16x32_bf16 v[0:3], v[0:3], v[8:11], 0
	ds_read_b128 v[8:11], v12 offset:34880
	ds_read_b128 v[16:19], v38 offset:64
	ds_read_b128 v[20:23], v38 offset:2368
	s_waitcnt lgkmcnt(1)
	v_mfma_f32_16x16x32_bf16 v[4:7], v[8:11], v[16:19], v[4:7]
	s_waitcnt lgkmcnt(0)
	v_mfma_f32_16x16x32_bf16 v[0:3], v[8:11], v[20:23], v[0:3]
	v_add_u32_e32 v10, 0xc000, v25
	ds_read2_b32 v[8:9], v10 offset1:16
	s_waitcnt lgkmcnt(0)
	s_nop 2
	v_sub_f32_e32 v4, v8, v4
	s_nop 0
	v_sub_f32_e32 v0, v9, v0
	ds_write2_b32 v10, v4, v0 offset1:16
	v_add_u32_e32 v0, 0xc400, v25
	ds_read2_b32 v[8:9], v0 offset1:16
	s_waitcnt lgkmcnt(0)
	v_sub_f32_e32 v4, v8, v5
	v_sub_f32_e32 v1, v9, v1
	ds_write2_b32 v0, v4, v1 offset1:16
	v_add_u32_e32 v4, 0xc800, v25
	ds_read2_b32 v[0:1], v4 offset1:16
	s_waitcnt lgkmcnt(0)
	v_sub_f32_e32 v0, v0, v6
	v_sub_f32_e32 v1, v1, v2
	v_add_u32_e32 v2, 0xcc00, v25
	ds_write2_b32 v4, v0, v1 offset1:16
	ds_read2_b32 v[0:1], v2 offset1:16
	s_waitcnt lgkmcnt(0)
	v_sub_f32_e32 v0, v0, v7
	v_sub_f32_e32 v1, v1, v3
	ds_write2_b32 v2, v0, v1 offset1:16
	s_waitcnt lgkmcnt(0)
	s_barrier
	s_and_saveexec_b64 s[0:1], s[4:5]
	s_cbranch_execz .LBB0_1039
; __device__ __forceinline__ float delta_prep(const Params& p, int l, int h, bool isP, int grow0, int t0, int nvalid, int bb, char* sm) {
;     ...
;       if (ib > 0) {
;         f32x4 a0 = (f32x4){0.f, 0.f, 0.f, 0.f}, a1 = a0;
;         const bfraw* xb0 = (w < 4) ? XTu + ((2 * w) * 16 + r) * 72 : XTw + ((2 * w - 8) * 16 + r) * 72;
;         const bfraw* xb1 = xb0 + 16 * 72;
; #pragma unroll
;         for (int kk = 0; kk < 2; ++kk) {
;           if (kk * 32 < ib * 16) {
;             bf16x8 am = *(const bf16x8*)(Mb + (ib * 16 + r) * 72 + kk * 32 + q * 8);
;             bf16x8 b0 = *(const bf16x8*)(xb0 + kk * 32 + q * 8);
;             bf16x8 b1 = *(const bf16x8*)(xb1 + kk * 32 + q * 8);
;             a0 = mfma16(am, b0, a0);
;             a1 = mfma16(am, b1, a1);
;           }
;         }
; #pragma unroll
;         for (int g = 0; g < 4; ++g) {
;           float* rp = xs + (ib * 16 + q * 4 + g) * 256 + w * 32 + r;
;           rp[0] -= a0[g];
;           rp[16] -= a1[g];
;         }
;         __syncthreads();
;       }
;       if (tid < 256) {
;         float a[16];
; #pragma unroll
;         for (int ii = 0; ii < 16; ++ii) a[ii] = xs[(ib * 16 + ii) * 256 + tid];
; #pragma unroll
;         for (int j = 0; j < 16; ++j) {
;           const float xj = a[j];
;           const float* mp = MT + (ib * 16 + j) * 64 + ib * 16;
; #pragma unroll
;           for (int ii = j + 1; ii < 16; ++ii) a[ii] -= mp[ii] * xj;
;         }
;         bfraw* dst = (tid < 128) ? XTu + tid * 72 + ib * 16 : XTw + (tid - 128) * 72 + ib * 16;
;         *(uint4*)dst = pack8(a);
;         *(uint4*)(dst + 8) = pack8(a + 8);
;       }
;       __syncthreads();
	ds_read2st64_b32 v[166:167], v40 offset0:192 offset1:196
	ds_read2st64_b32 v[168:169], v40 offset0:200 offset1:204
	ds_read2st64_b32 v[170:171], v40 offset0:208 offset1:212
	ds_read2st64_b32 v[172:173], v40 offset0:216 offset1:220
	ds_read2st64_b32 v[174:175], v40 offset0:224 offset1:228
	ds_read2st64_b32 v[176:177], v40 offset0:232 offset1:236
	ds_read2st64_b32 v[178:179], v40 offset0:240 offset1:244
	ds_read2st64_b32 v[180:181], v40 offset0:248 offset1:252
	v_mov_b32_e32 v165, 0x23c00
	ds_read_b32 v182, v165 offset:12484
	ds_read_b64 v[184:185], v165 offset:12488
	ds_read_b128 v[186:189], v165 offset:12496
	ds_read_b128 v[190:193], v165 offset:12512
	ds_read_b128 v[194:197], v165 offset:12528
	ds_read_b64 v[198:199], v165 offset:12744
	ds_read_b128 v[200:203], v165 offset:12752
	ds_read_b128 v[204:207], v165 offset:12768
	ds_read_b128 v[208:211], v165 offset:12784
	ds_read_b32 v183, v165 offset:13004
	ds_read_b128 v[212:215], v165 offset:13008
	ds_read_b128 v[216:219], v165 offset:13024
	ds_read_b128 v[220:223], v165 offset:13040
	s_waitcnt lgkmcnt(13)
	ds_read_b128 v[226:229], v165 offset:13264
	ds_read_b128 v[230:233], v165 offset:13280
	ds_read_b128 v[234:237], v165 offset:13296
	s_waitcnt lgkmcnt(11)
	v_fma_f32 v167, -v166, v182, v167
	v_pk_fma_f32 v[168:169], v[166:167], v[184:185], v[168:169] op_sel_hi:[0,1,1] neg_lo:[1,0,0] neg_hi:[1,0,0]
	v_pk_fma_f32 v[170:171], v[166:167], v[186:187], v[170:171] op_sel_hi:[0,1,1] neg_lo:[1,0,0] neg_hi:[1,0,0]
	v_pk_fma_f32 v[172:173], v[166:167], v[188:189], v[172:173] op_sel_hi:[0,1,1] neg_lo:[1,0,0] neg_hi:[1,0,0]
	v_pk_fma_f32 v[174:175], v[166:167], v[190:191], v[174:175] op_sel_hi:[0,1,1] neg_lo:[1,0,0] neg_hi:[1,0,0]
	v_pk_fma_f32 v[176:177], v[166:167], v[192:193], v[176:177] op_sel_hi:[0,1,1] neg_lo:[1,0,0] neg_hi:[1,0,0]
	v_pk_fma_f32 v[178:179], v[166:167], v[194:195], v[178:179] op_sel_hi:[0,1,1] neg_lo:[1,0,0] neg_hi:[1,0,0]
	v_pk_fma_f32 v[180:181], v[166:167], v[196:197], v[180:181] op_sel_hi:[0,1,1] neg_lo:[1,0,0] neg_hi:[1,0,0]
	ds_read_b32 v182, v165 offset:13524
	ds_read_b64 v[184:185], v165 offset:13528
	ds_read_b128 v[186:189], v165 offset:13536
	ds_read_b128 v[190:193], v165 offset:13552
	s_waitcnt lgkmcnt(11)
	v_pk_fma_f32 v[168:169], v[166:167], v[198:199], v[168:169] op_sel:[1,0,0] op_sel_hi:[1,1,1] neg_lo:[1,0,0] neg_hi:[1,0,0]
	v_pk_fma_f32 v[170:171], v[166:167], v[200:201], v[170:171] op_sel:[1,0,0] op_sel_hi:[1,1,1] neg_lo:[1,0,0] neg_hi:[1,0,0]
	v_pk_fma_f32 v[172:173], v[166:167], v[202:203], v[172:173] op_sel:[1,0,0] op_sel_hi:[1,1,1] neg_lo:[1,0,0] neg_hi:[1,0,0]
	v_pk_fma_f32 v[174:175], v[166:167], v[204:205], v[174:175] op_sel:[1,0,0] op_sel_hi:[1,1,1] neg_lo:[1,0,0] neg_hi:[1,0,0]
	v_pk_fma_f32 v[176:177], v[166:167], v[206:207], v[176:177] op_sel:[1,0,0] op_sel_hi:[1,1,1] neg_lo:[1,0,0] neg_hi:[1,0,0]
	v_pk_fma_f32 v[178:179], v[166:167], v[208:209], v[178:179] op_sel:[1,0,0] op_sel_hi:[1,1,1] neg_lo:[1,0,0] neg_hi:[1,0,0]
	v_pk_fma_f32 v[180:181], v[166:167], v[210:211], v[180:181] op_sel:[1,0,0] op_sel_hi:[1,1,1] neg_lo:[1,0,0] neg_hi:[1,0,0]
	ds_read_b64 v[194:195], v165 offset:13784
	ds_read_b128 v[196:199], v165 offset:13792
	ds_read_b128 v[200:203], v165 offset:13808
	s_waitcnt lgkmcnt(10)
	v_fma_f32 v169, -v168, v183, v169
	v_pk_fma_f32 v[170:171], v[168:169], v[212:213], v[170:171] op_sel_hi:[0,1,1] neg_lo:[1,0,0] neg_hi:[1,0,0]
	v_pk_fma_f32 v[172:173], v[168:169], v[214:215], v[172:173] op_sel_hi:[0,1,1] neg_lo:[1,0,0] neg_hi:[1,0,0]
	v_pk_fma_f32 v[174:175], v[168:169], v[216:217], v[174:175] op_sel_hi:[0,1,1] neg_lo:[1,0,0] neg_hi:[1,0,0]
	v_pk_fma_f32 v[176:177], v[168:169], v[218:219], v[176:177] op_sel_hi:[0,1,1] neg_lo:[1,0,0] neg_hi:[1,0,0]
	v_pk_fma_f32 v[178:179], v[168:169], v[220:221], v[178:179] op_sel_hi:[0,1,1] neg_lo:[1,0,0] neg_hi:[1,0,0]
	v_pk_fma_f32 v[180:181], v[168:169], v[222:223], v[180:181] op_sel_hi:[0,1,1] neg_lo:[1,0,0] neg_hi:[1,0,0]
	ds_read_b32 v183, v165 offset:14044
	ds_read_b128 v[204:207], v165 offset:14048
	ds_read_b128 v[208:211], v165 offset:14064
	s_waitcnt lgkmcnt(10)
	v_pk_fma_f32 v[170:171], v[168:169], v[226:227], v[170:171] op_sel:[1,0,0] op_sel_hi:[1,1,1] neg_lo:[1,0,0] neg_hi:[1,0,0]
	v_pk_fma_f32 v[172:173], v[168:169], v[228:229], v[172:173] op_sel:[1,0,0] op_sel_hi:[1,1,1] neg_lo:[1,0,0] neg_hi:[1,0,0]
	v_pk_fma_f32 v[174:175], v[168:169], v[230:231], v[174:175] op_sel:[1,0,0] op_sel_hi:[1,1,1] neg_lo:[1,0,0] neg_hi:[1,0,0]
	v_pk_fma_f32 v[176:177], v[168:169], v[232:233], v[176:177] op_sel:[1,0,0] op_sel_hi:[1,1,1] neg_lo:[1,0,0] neg_hi:[1,0,0]
	v_pk_fma_f32 v[178:179], v[168:169], v[234:235], v[178:179] op_sel:[1,0,0] op_sel_hi:[1,1,1] neg_lo:[1,0,0] neg_hi:[1,0,0]
	v_pk_fma_f32 v[180:181], v[168:169], v[236:237], v[180:181] op_sel:[1,0,0] op_sel_hi:[1,1,1] neg_lo:[1,0,0] neg_hi:[1,0,0]
	ds_read_b128 v[212:215], v165 offset:14304
	ds_read_b128 v[216:219], v165 offset:14320
	s_waitcnt lgkmcnt(8)
; __device__ __forceinline__ float delta_prep(const Params& p, int l, int h, bool isP, int grow0, int t0, int nvalid, int bb, char* sm) {
;     ...
;       if (ib > 0) {
;         f32x4 a0 = (f32x4){0.f, 0.f, 0.f, 0.f}, a1 = a0;
;         const bfraw* xb0 = (w < 4) ? XTu + ((2 * w) * 16 + r) * 72 : XTw + ((2 * w - 8) * 16 + r) * 72;
;         const bfraw* xb1 = xb0 + 16 * 72;
; #pragma unroll
;         for (int kk = 0; kk < 2; ++kk) {
;           if (kk * 32 < ib * 16) {
;             bf16x8 am = *(const bf16x8*)(Mb + (ib * 16 + r) * 72 + kk * 32 + q * 8);
;             bf16x8 b0 = *(const bf16x8*)(xb0 + kk * 32 + q * 8);
;             bf16x8 b1 = *(const bf16x8*)(xb1 + kk * 32 + q * 8);
;             a0 = mfma16(am, b0, a0);
;             a1 = mfma16(am, b1, a1);
;           }
;         }
; #pragma unroll
;         for (int g = 0; g < 4; ++g) {
;           float* rp = xs + (ib * 16 + q * 4 + g) * 256 + w * 32 + r;
;           rp[0] -= a0[g];
;           rp[16] -= a1[g];
;         }
;         __syncthreads();
;       }
;       if (tid < 256) {
;         float a[16];
; #pragma unroll
;         for (int ii = 0; ii < 16; ++ii) a[ii] = xs[(ib * 16 + ii) * 256 + tid];
; #pragma unroll
;         for (int j = 0; j < 16; ++j) {
;           const float xj = a[j];
;           const float* mp = MT + (ib * 16 + j) * 64 + ib * 16;
; #pragma unroll
;           for (int ii = j + 1; ii < 16; ++ii) a[ii] -= mp[ii] * xj;
;         }
;         bfraw* dst = (tid < 128) ? XTu + tid * 72 + ib * 16 : XTw + (tid - 128) * 72 + ib * 16;
;         *(uint4*)dst = pack8(a);
;         *(uint4*)(dst + 8) = pack8(a + 8);
;       }
;       __syncthreads();
	v_fma_f32 v171, -v170, v182, v171
	v_pk_fma_f32 v[172:173], v[170:171], v[184:185], v[172:173] op_sel_hi:[0,1,1] neg_lo:[1,0,0] neg_hi:[1,0,0]
	v_pk_fma_f32 v[174:175], v[170:171], v[186:187], v[174:175] op_sel_hi:[0,1,1] neg_lo:[1,0,0] neg_hi:[1,0,0]
	v_pk_fma_f32 v[176:177], v[170:171], v[188:189], v[176:177] op_sel_hi:[0,1,1] neg_lo:[1,0,0] neg_hi:[1,0,0]
	v_pk_fma_f32 v[178:179], v[170:171], v[190:191], v[178:179] op_sel_hi:[0,1,1] neg_lo:[1,0,0] neg_hi:[1,0,0]
	v_pk_fma_f32 v[180:181], v[170:171], v[192:193], v[180:181] op_sel_hi:[0,1,1] neg_lo:[1,0,0] neg_hi:[1,0,0]
	ds_read_b32 v182, v165 offset:14564
	ds_read_b64 v[184:185], v165 offset:14568
	ds_read_b128 v[186:189], v165 offset:14576
	s_waitcnt lgkmcnt(8)
	v_pk_fma_f32 v[172:173], v[170:171], v[194:195], v[172:173] op_sel:[1,0,0] op_sel_hi:[1,1,1] neg_lo:[1,0,0] neg_hi:[1,0,0]
	v_pk_fma_f32 v[174:175], v[170:171], v[196:197], v[174:175] op_sel:[1,0,0] op_sel_hi:[1,1,1] neg_lo:[1,0,0] neg_hi:[1,0,0]
	v_pk_fma_f32 v[176:177], v[170:171], v[198:199], v[176:177] op_sel:[1,0,0] op_sel_hi:[1,1,1] neg_lo:[1,0,0] neg_hi:[1,0,0]
	v_pk_fma_f32 v[178:179], v[170:171], v[200:201], v[178:179] op_sel:[1,0,0] op_sel_hi:[1,1,1] neg_lo:[1,0,0] neg_hi:[1,0,0]
	v_pk_fma_f32 v[180:181], v[170:171], v[202:203], v[180:181] op_sel:[1,0,0] op_sel_hi:[1,1,1] neg_lo:[1,0,0] neg_hi:[1,0,0]
	ds_read_b64 v[190:191], v165 offset:14824
	ds_read_b128 v[192:195], v165 offset:14832
	s_waitcnt lgkmcnt(7)
	v_fma_f32 v173, -v172, v183, v173
	v_pk_fma_f32 v[174:175], v[172:173], v[204:205], v[174:175] op_sel_hi:[0,1,1] neg_lo:[1,0,0] neg_hi:[1,0,0]
	v_pk_fma_f32 v[176:177], v[172:173], v[206:207], v[176:177] op_sel_hi:[0,1,1] neg_lo:[1,0,0] neg_hi:[1,0,0]
	v_pk_fma_f32 v[178:179], v[172:173], v[208:209], v[178:179] op_sel_hi:[0,1,1] neg_lo:[1,0,0] neg_hi:[1,0,0]
	v_pk_fma_f32 v[180:181], v[172:173], v[210:211], v[180:181] op_sel_hi:[0,1,1] neg_lo:[1,0,0] neg_hi:[1,0,0]
	ds_read_b32 v183, v165 offset:15084
	ds_read_b128 v[196:199], v165 offset:15088
	s_waitcnt lgkmcnt(7)
	v_pk_fma_f32 v[174:175], v[172:173], v[212:213], v[174:175] op_sel:[1,0,0] op_sel_hi:[1,1,1] neg_lo:[1,0,0] neg_hi:[1,0,0]
	v_pk_fma_f32 v[176:177], v[172:173], v[214:215], v[176:177] op_sel:[1,0,0] op_sel_hi:[1,1,1] neg_lo:[1,0,0] neg_hi:[1,0,0]
	v_pk_fma_f32 v[178:179], v[172:173], v[216:217], v[178:179] op_sel:[1,0,0] op_sel_hi:[1,1,1] neg_lo:[1,0,0] neg_hi:[1,0,0]
	v_pk_fma_f32 v[180:181], v[172:173], v[218:219], v[180:181] op_sel:[1,0,0] op_sel_hi:[1,1,1] neg_lo:[1,0,0] neg_hi:[1,0,0]
	ds_read_b128 v[200:203], v165 offset:15344
	s_waitcnt lgkmcnt(5)
	v_fma_f32 v175, -v174, v182, v175
	v_pk_fma_f32 v[176:177], v[174:175], v[184:185], v[176:177] op_sel_hi:[0,1,1] neg_lo:[1,0,0] neg_hi:[1,0,0]
	v_pk_fma_f32 v[178:179], v[174:175], v[186:187], v[178:179] op_sel_hi:[0,1,1] neg_lo:[1,0,0] neg_hi:[1,0,0]
	v_pk_fma_f32 v[180:181], v[174:175], v[188:189], v[180:181] op_sel_hi:[0,1,1] neg_lo:[1,0,0] neg_hi:[1,0,0]
	ds_read_b32 v182, v165 offset:15604
	ds_read_b64 v[184:185], v165 offset:15608
	s_waitcnt lgkmcnt(5)
	v_pk_fma_f32 v[176:177], v[174:175], v[190:191], v[176:177] op_sel:[1,0,0] op_sel_hi:[1,1,1] neg_lo:[1,0,0] neg_hi:[1,0,0]
	v_pk_fma_f32 v[178:179], v[174:175], v[192:193], v[178:179] op_sel:[1,0,0] op_sel_hi:[1,1,1] neg_lo:[1,0,0] neg_hi:[1,0,0]
	v_pk_fma_f32 v[180:181], v[174:175], v[194:195], v[180:181] op_sel:[1,0,0] op_sel_hi:[1,1,1] neg_lo:[1,0,0] neg_hi:[1,0,0]
	ds_read_b64 v[186:187], v165 offset:15864
	s_waitcnt lgkmcnt(4)
	v_fma_f32 v177, -v176, v183, v177
	v_pk_fma_f32 v[178:179], v[176:177], v[196:197], v[178:179] op_sel_hi:[0,1,1] neg_lo:[1,0,0] neg_hi:[1,0,0]
	v_pk_fma_f32 v[180:181], v[176:177], v[198:199], v[180:181] op_sel_hi:[0,1,1] neg_lo:[1,0,0] neg_hi:[1,0,0]
	ds_read_b32 v183, v165 offset:16124
	s_waitcnt lgkmcnt(4)
	v_pk_fma_f32 v[178:179], v[176:177], v[200:201], v[178:179] op_sel:[1,0,0] op_sel_hi:[1,1,1] neg_lo:[1,0,0] neg_hi:[1,0,0]
	v_pk_fma_f32 v[180:181], v[176:177], v[202:203], v[180:181] op_sel:[1,0,0] op_sel_hi:[1,1,1] neg_lo:[1,0,0] neg_hi:[1,0,0]
	s_waitcnt lgkmcnt(2)
	v_fma_f32 v179, -v178, v182, v179
	v_pk_fma_f32 v[180:181], v[178:179], v[184:185], v[180:181] op_sel_hi:[0,1,1] neg_lo:[1,0,0] neg_hi:[1,0,0]
	s_waitcnt lgkmcnt(1)
	v_pk_fma_f32 v[180:181], v[178:179], v[186:187], v[180:181] op_sel:[1,0,0] op_sel_hi:[1,1,1] neg_lo:[1,0,0] neg_hi:[1,0,0]
	s_waitcnt lgkmcnt(0)
	v_fma_f32 v181, -v180, v183, v181
	v_cvt_pk_bf16_f32 v182, v166, v167
	v_cvt_pk_bf16_f32 v183, v168, v169
	v_cvt_pk_bf16_f32 v184, v170, v171
	v_cvt_pk_bf16_f32 v185, v172, v173
	ds_write_b128 v31, v[182:185] offset:96
	v_cvt_pk_bf16_f32 v186, v174, v175
	v_cvt_pk_bf16_f32 v187, v176, v177
	v_cvt_pk_bf16_f32 v188, v178, v179
	v_cvt_pk_bf16_f32 v189, v180, v181
	ds_write_b128 v31, v[186:189] offset:112
	v_readlane_b32 s2, v244, 28

; __device__ __forceinline__ int opq(int x) { asm volatile("" : "+v"(x)); return x; }
; __device__ __forceinline__ void state_copies(const Params& p, int l, int bid, int nb) {
;   const bfraw* B1 = (const bfraw*)(p.ws + WS_B1);
;   const bfraw* B2 = (const bfraw*)(p.ws + WS_B2);
;   constexpr int N0 = 4 * 15 * 512, N1 = 4 * 3 * 1536, N2 = 128 * 15 * 512, N3 = 128 * 3 * 1536, N4 = 4 * 128 * 128, N5 = 128 * 128 * 128;
;   constexpr int TOT = N0 + N1 + N2 + N3 + 2 * N4 + 2 * N5;
; #pragma unroll 4
;   for (int i = (bid * NTHR + opq(threadIdx.x)) * 4; i < TOT; i += nb * NTHR * 4) {
;     int e = i;
;     float4 v; float* dst;
;     if (e < N0) { int b = e / (15 * 512), rem = e % (15 * 512), j = rem >> 9, c = rem & 511;
.LBB0_1061:
	v_readlane_b32 s54, v247, 62
	v_mov_b32_e32 v0, v224
	s_lshl_b32 s0, s54, 11
	s_nop 0
	v_lshl_add_u32 v4, v0, 2, s0
	s_mov_b32 s0, 0x1ac000
	v_cmp_gt_i32_e32 vcc, s0, v4
	s_and_saveexec_b64 s[4:5], vcc
	v_readlane_b32 s94, v247, 58
	v_readlane_b32 s96, v247, 60
	v_readlane_b32 s95, v247, 59
	v_readlane_b32 s97, v247, 61
	s_cbranch_execz .LBB0_1209
	s_load_dword s1, s[80:81], 0x10
	s_load_dword s10, s[80:81], 0x0
	v_readlane_b32 s16, v247, 0
	v_readlane_b32 s18, v247, 2
	v_readlane_b32 s19, v247, 3
	s_waitcnt lgkmcnt(0)
	s_lshr_b32 s1, s1, 16
	s_add_u32 s6, s96, 0x6420000
	s_addc_u32 s7, s97, 0
	s_add_u32 s8, s96, 0xe920000
	s_addc_u32 s9, s97, 0
	s_cmp_lg_u32 s1, 0
	s_cselect_b64 s[2:3], -1, 0
	s_cmp_lg_u64 s[2:3], 0
	s_addc_u32 s33, s10, 0
	s_lshl_b32 s20, s33, 11
	v_cvt_f32_u32_e32 v1, s20
	s_add_u32 s10, s18, 0x8ee0000
	s_addc_u32 s11, s19, 0
	s_add_u32 s12, s18, 0x8760000
	v_rcp_iflag_f32_e32 v1, v1
	s_addc_u32 s13, s19, 0
	v_add_u32_e32 v0, s20, v4
	s_add_u32 s14, s18, 0x843c000
	v_mul_f32_e32 v1, 0x4f7ffffe, v1
	v_cvt_u32_f32_e32 v1, v1
	s_addc_u32 s15, s19, 0
	v_cmp_gt_i32_e32 vcc, s0, v0
	v_readlane_b32 s17, v247, 1
	s_add_u32 s16, s18, 0x8400000
	v_cndmask_b32_e64 v3, 0, 1, vcc
	s_addc_u32 s17, s19, 0
	v_max_i32_e32 v2, 0x1ac000, v0
	v_or_b32_e32 v0, v0, v3
	s_sub_i32 s0, 0, s20
	v_sub_u32_e32 v0, v2, v0
	v_mul_lo_u32 v2, s0, v1
	v_mul_hi_u32 v2, v1, v2
	v_add_u32_e32 v1, v1, v2
	v_mul_hi_u32 v1, v0, v1
	v_mul_lo_u32 v2, v1, s20
	v_sub_u32_e32 v0, v0, v2
	v_add_u32_e32 v2, 1, v1
	v_cmp_le_u32_e64 s[0:1], s20, v0
	s_nop 1
	v_cndmask_b32_e64 v1, v1, v2, s[0:1]
	v_subrev_u32_e32 v2, s20, v0
	v_cndmask_b32_e64 v0, v0, v2, s[0:1]
	v_add_u32_e32 v2, 1, v1
	v_cmp_le_u32_e64 s[0:1], s20, v0
	s_nop 1
	v_cndmask_b32_e64 v0, v1, v2, s[0:1]
	v_addc_co_u32_e32 v10, vcc, 0, v0, vcc
	v_and_b32_e32 v0, 3, v10
	v_cmp_ne_u32_e32 vcc, 3, v0
	s_and_saveexec_b64 s[0:1], vcc
	s_cbranch_execz .LBB0_1094
	v_add_u32_e32 v0, 1, v10
	v_and_b32_e32 v11, 3, v0
	s_mov_b64 s[18:19], 0
	v_mov_b32_e32 v7, 0
	s_mov_b32 s21, 0x88888889
	v_mov_b32_e32 v12, 0xe360000
	v_mov_b32_e32 v13, 0xd360000
	v_mov_b32_e32 v14, 0x13ba000
	v_mov_b32_e32 v15, 8
	v_mov_b32_e32 v16, 0x86e0000
	v_mov_b32_e32 v17, 0x8660000
	s_branch .LBB0_1065

; __device__ __forceinline__ float4 ld4bf(const bfraw* s) { uint2 v = *(const uint2*)s; return make_float4(lo2f(v.x), hi2f(v.x), lo2f(v.y), hi2f(v.y)); }
; __device__ __forceinline__ void state_copies(const Params& p, int l, int bid, int nb) {
;     ...
;     else { e -= 2 * N4; int kv = e / N5, e2 = e % N5; int b = e2 >> 14, j = (e2 >> 7) & 127, c = e2 & 127;
;       const float* cache = kv ? p.cache_v : p.cache_k;
;       if (j < 120) v = *(const float4*)(cache + ((size_t)(l * NBS + b) * 128 + j + 8) * 128 + c);
;       else v = ld4bf(B2 + (size_t)(ROWS_P + b * TS + j - 120) * LD2 + 1024 + kv * 128 + c);
;       dst = p.out + (kv ? O_VS : O_KS) + (size_t)l * N5 + e2; }
;     *(float4*)dst = v;
.LBB0_1209:
	s_or_b64 exec, exec, s[4:5]
	v_readlane_b32 s2, v247, 62
	v_readfirstlane_b32 s0, v224
	v_and_b32_e32 v0, 63, v224
	v_lshlrev_b32_e32 v2, 4, v0
	v_mov_b32_e32 v3, 0
	v_lshrrev_b32_e32 v4, 5, v0
	v_mul_u32_u24_e32 v4, 0xa00, v4
	v_and_b32_e32 v1, 31, v0
	v_lshl_add_u32 v4, v1, 3, v4
	v_mov_b32_e32 v5, 0
	v_readlane_b32 s98, v247, 2
	v_readlane_b32 s99, v247, 3
	s_nop 3
	v_lshl_add_u64 v[6:7], s[98:99], 0, v[2:3]
	v_readlane_b32 s98, v247, 17
	v_readlane_b32 s99, v247, 18
	s_add_u32 s98, s98, 0x1000
	s_addc_u32 s99, s99, 0
	v_lshl_add_u64 v[8:9], s[98:99], 0, v[2:3]
	v_readlane_b32 s98, v247, 19
	v_readlane_b32 s99, v247, 20
	s_add_u32 s98, s98, 0x1000
	s_addc_u32 s99, s99, 0
	v_lshl_add_u64 v[10:11], s[98:99], 0, v[2:3]
	v_readlane_b32 s98, v247, 60
	v_readlane_b32 s99, v247, 61
	s_add_u32 s98, s98, 0x138fd800
	s_addc_u32 s99, s99, 0
	v_lshl_add_u64 v[12:13], s[98:99], 0, v[4:5]
	s_waitcnt lgkmcnt(0)
	s_lshl_b32 s1, s84, 9
	s_lshl_b32 s2, s2, 9
	s_add_u32 s0, s0, s2
	s_mov_b32 s101, 0
	s_cmp_lt_u32 s0, 0x100000
	s_cbranch_scc0 .Lsc0_done
.Lsc0_loop:
	s_mov_b32 s3, 0
	s_mov_b32 s2, s0
	s_lshr_b32 s98, s2, 19
	s_and_b32 s99, s2, 0x7ffff
	s_lshl_b32 s99, s99, 4
	s_lshl_b32 s100, s98, 24
	s_add_u32 s100, s100, s99
	s_add_u32 s100, s100, 0xd360000
	v_lshl_add_u64 v[20:21], s[100:101], 0, v[6:7]
	s_bfe_u32 s100, s2, 0x70005
	s_cmp_ge_u32 s100, 0x78
	s_cbranch_scc1 .Lsc0_b0
	s_mov_b32 s100, s99
	s_cmp_eq_u32 s98, 0
	s_cbranch_scc0 .Lsc0_v0
	v_lshl_add_u64 v[30:31], s[100:101], 0, v[8:9]
	s_branch .Lsc0_la0
.Lsc0_v0:
	v_lshl_add_u64 v[30:31], s[100:101], 0, v[10:11]
.Lsc0_la0:
	global_load_dwordx4 v[40:43], v[30:31], off
	s_branch .Lsc0_e0
.Lsc0_b0:
	s_bfe_u32 s99, s2, 0x7000c
	s_lshl_b32 s99, s99, 3
	s_add_u32 s99, s99, s100
	s_mul_i32 s99, s99, 0xa00
	s_lshl_b32 s100, s98, 8
	s_add_u32 s100, s100, s99
	v_lshl_add_u64 v[30:31], s[100:101], 0, v[12:13]
	global_load_dwordx2 v[40:41], v[30:31], off
	s_bitset1_b32 s3, 0
.Lsc0_e0:
	s_mul_i32 s2, s1, 1
	s_add_u32 s2, s2, s0
	s_cmp_lt_u32 s2, 0x100000
	s_cselect_b32 s2, s2, s0
	s_lshr_b32 s98, s2, 19
	s_and_b32 s99, s2, 0x7ffff
	s_lshl_b32 s99, s99, 4
	s_lshl_b32 s100, s98, 24
	s_add_u32 s100, s100, s99
	s_add_u32 s100, s100, 0xd360000
	v_lshl_add_u64 v[22:23], s[100:101], 0, v[6:7]
	s_bfe_u32 s100, s2, 0x70005
	s_cmp_ge_u32 s100, 0x78
	s_cbranch_scc1 .Lsc0_b1
	s_mov_b32 s100, s99
	s_cmp_eq_u32 s98, 0
	s_cbranch_scc0 .Lsc0_v1
	v_lshl_add_u64 v[32:33], s[100:101], 0, v[8:9]
	s_branch .Lsc0_la1
.Lsc0_v1:
	v_lshl_add_u64 v[32:33], s[100:101], 0, v[10:11]
.Lsc0_la1:
	global_load_dwordx4 v[44:47], v[32:33], off
	s_branch .Lsc0_e1
.Lsc0_b1:
	s_bfe_u32 s99, s2, 0x7000c
	s_lshl_b32 s99, s99, 3
	s_add_u32 s99, s99, s100
	s_mul_i32 s99, s99, 0xa00
	s_lshl_b32 s100, s98, 8
	s_add_u32 s100, s100, s99
	v_lshl_add_u64 v[32:33], s[100:101], 0, v[12:13]
	global_load_dwordx2 v[44:45], v[32:33], off
	s_bitset1_b32 s3, 1
.Lsc0_e1:
	s_mul_i32 s2, s1, 2
	s_add_u32 s2, s2, s0
	s_cmp_lt_u32 s2, 0x100000
	s_cselect_b32 s2, s2, s0
	s_lshr_b32 s98, s2, 19
	s_and_b32 s99, s2, 0x7ffff
	s_lshl_b32 s99, s99, 4
	s_lshl_b32 s100, s98, 24
	s_add_u32 s100, s100, s99
	s_add_u32 s100, s100, 0xd360000
	v_lshl_add_u64 v[24:25], s[100:101], 0, v[6:7]
	s_bfe_u32 s100, s2, 0x70005
	s_cmp_ge_u32 s100, 0x78
	s_cbranch_scc1 .Lsc0_b2
	s_mov_b32 s100, s99
	s_cmp_eq_u32 s98, 0
	s_cbranch_scc0 .Lsc0_v2
	v_lshl_add_u64 v[34:35], s[100:101], 0, v[8:9]
	s_branch .Lsc0_la2
.Lsc0_v2:
	v_lshl_add_u64 v[34:35], s[100:101], 0, v[10:11]
.Lsc0_la2:
	global_load_dwordx4 v[48:51], v[34:35], off
	s_branch .Lsc0_e2
.Lsc0_b2:
	s_bfe_u32 s99, s2, 0x7000c
	s_lshl_b32 s99, s99, 3
	s_add_u32 s99, s99, s100
	s_mul_i32 s99, s99, 0xa00
	s_lshl_b32 s100, s98, 8
	s_add_u32 s100, s100, s99
	v_lshl_add_u64 v[34:35], s[100:101], 0, v[12:13]
	global_load_dwordx2 v[48:49], v[34:35], off
	s_bitset1_b32 s3, 2
; __device__ __forceinline__ unsigned xb_add(unsigned* p, unsigned v) { return __hip_atomic_fetch_add(p, v, __ATOMIC_RELAXED, __HIP_MEMORY_SCOPE_AGENT); }
; __device__ __forceinline__ float4 ld4bf(const bfraw* s) { uint2 v = *(const uint2*)s; return make_float4(lo2f(v.x), hi2f(v.x), lo2f(v.y), hi2f(v.y)); }
; __device__ __forceinline__ void xcd_barrier(const XcdBarrier& b) {
;     asm volatile("s_waitcnt vmcnt(0)" ::: "memory");
;     __syncthreads();
;     if (threadIdx.x == 0) {
;         unsigned* bar = b.bar;
;         __builtin_amdgcn_s_waitcnt(0);
;         unsigned nloc = b.st[0], nx = b.st[1];
;         if (nloc == 0u) { xcd_barrier_complete(bar, b.x, nloc, nx); b.st[0] = nloc; b.st[1] = nx; }
;         const unsigned old = xb_add(&bar[XB_XSUB(b.x)], 1u);
; __device__ __forceinline__ void state_copies(const Params& p, int l, int bid, int nb) {
;     ...
;     else { e -= 2 * N4; int kv = e / N5, e2 = e % N5; int b = e2 >> 14, j = (e2 >> 7) & 127, c = e2 & 127;
;       const float* cache = kv ? p.cache_v : p.cache_k;
;       if (j < 120) v = *(const float4*)(cache + ((size_t)(l * NBS + b) * 128 + j + 8) * 128 + c);
;       else v = ld4bf(B2 + (size_t)(ROWS_P + b * TS + j - 120) * LD2 + 1024 + kv * 128 + c);
;       dst = p.out + (kv ? O_VS : O_KS) + (size_t)l * N5 + e2; }
;     *(float4*)dst = v;
.Lsc0_e2:
	s_mul_i32 s2, s1, 3
	s_add_u32 s2, s2, s0
	s_cmp_lt_u32 s2, 0x100000
	s_cselect_b32 s2, s2, s0
	s_lshr_b32 s98, s2, 19
	s_and_b32 s99, s2, 0x7ffff
	s_lshl_b32 s99, s99, 4
	s_lshl_b32 s100, s98, 24
	s_add_u32 s100, s100, s99
	s_add_u32 s100, s100, 0xd360000
	v_lshl_add_u64 v[26:27], s[100:101], 0, v[6:7]
	s_bfe_u32 s100, s2, 0x70005
	s_cmp_ge_u32 s100, 0x78
	s_cbranch_scc1 .Lsc0_b3
	s_mov_b32 s100, s99
	s_cmp_eq_u32 s98, 0
	s_cbranch_scc0 .Lsc0_v3
	v_lshl_add_u64 v[36:37], s[100:101], 0, v[8:9]
	s_branch .Lsc0_la3
.Lsc0_v3:
	v_lshl_add_u64 v[36:37], s[100:101], 0, v[10:11]
.Lsc0_la3:
	global_load_dwordx4 v[52:55], v[36:37], off
	s_branch .Lsc0_e3
.Lsc0_b3:
	s_bfe_u32 s99, s2, 0x7000c
	s_lshl_b32 s99, s99, 3
	s_add_u32 s99, s99, s100
	s_mul_i32 s99, s99, 0xa00
	s_lshl_b32 s100, s98, 8
	s_add_u32 s100, s100, s99
	v_lshl_add_u64 v[36:37], s[100:101], 0, v[12:13]
	global_load_dwordx2 v[52:53], v[36:37], off
	s_bitset1_b32 s3, 3
.Lsc0_e3:
	s_waitcnt vmcnt(0)
	s_bitcmp1_b32 s3, 0
	s_cbranch_scc0 .Lsc0_s0
	v_and_b32_e32 v43, 0xffff0000, v41
	v_lshlrev_b32_e32 v42, 16, v41
	v_and_b32_e32 v41, 0xffff0000, v40
	v_lshlrev_b32_e32 v40, 16, v40
.Lsc0_s0:
	global_store_dwordx4 v[20:21], v[40:43], off
	s_bitcmp1_b32 s3, 1
	s_cbranch_scc0 .Lsc0_s1
	v_and_b32_e32 v47, 0xffff0000, v45
	v_lshlrev_b32_e32 v46, 16, v45
	v_and_b32_e32 v45, 0xffff0000, v44
	v_lshlrev_b32_e32 v44, 16, v44
.Lsc0_s1:
	global_store_dwordx4 v[22:23], v[44:47], off
	s_bitcmp1_b32 s3, 2
	s_cbranch_scc0 .Lsc0_s2
	v_and_b32_e32 v51, 0xffff0000, v49
	v_lshlrev_b32_e32 v50, 16, v49
	v_and_b32_e32 v49, 0xffff0000, v48
	v_lshlrev_b32_e32 v48, 16, v48
.Lsc0_s2:
	global_store_dwordx4 v[24:25], v[48:51], off
	s_bitcmp1_b32 s3, 3
	s_cbranch_scc0 .Lsc0_s3
	v_and_b32_e32 v55, 0xffff0000, v53
	v_lshlrev_b32_e32 v54, 16, v53
	v_and_b32_e32 v53, 0xffff0000, v52
	v_lshlrev_b32_e32 v52, 16, v52
.Lsc0_s3:
	global_store_dwordx4 v[26:27], v[52:55], off
	s_lshl_b32 s2, s1, 2
	s_add_u32 s0, s0, s2
	s_cmp_lt_u32 s0, 0x100000
	s_cbranch_scc1 .Lsc0_loop
.Lsc0_done:
	v_readlane_b32 s92, v247, 56
	v_readlane_b32 s93, v247, 57
	s_cmp_lt_i32 s95, 4
	s_cbranch_scc1 .LBB0_1263
	s_waitcnt vmcnt(0)
	s_waitcnt vmcnt(0) lgkmcnt(0)
	s_barrier
	s_mov_b64 s[0:1], exec
	v_readlane_b32 s2, v247, 5
	v_readlane_b32 s3, v247, 6
	s_and_b64 s[2:3], s[0:1], s[2:3]
	s_mov_b64 exec, s[2:3]
	s_cbranch_execz .LBB0_1262
	s_add_i32 s2, 0, 0x27ff0
	v_mov_b32_e32 v0, s2
	s_waitcnt vmcnt(0) expcnt(0) lgkmcnt(0)
	ds_read_b32 v2, v0
	s_add_i32 s2, 0, 0x27ff4
	v_mov_b32_e32 v0, s2
	ds_read_b32 v0, v0
	s_waitcnt lgkmcnt(1)
	v_cmp_ne_u32_e32 vcc, 0, v2
	s_cbranch_vccnz .LBB0_1226
	v_readlane_b32 s2, v247, 4
	s_mul_i32 s20, s85, s2
	s_add_u32 s2, s96, 0x1f1ede00
	s_addc_u32 s3, s97, 0
	s_add_u32 s4, s96, 0x1f1ee000
	s_addc_u32 s5, s97, 0
	s_add_u32 s6, s96, 0x1f1ee100
	s_addc_u32 s7, s97, 0
	s_add_u32 s8, s96, 0x1f1ee200
	s_addc_u32 s9, s97, 0
	s_add_u32 s10, s96, 0x1f1ee300
	s_addc_u32 s11, s97, 0
	s_add_u32 s12, s96, 0x1f1ee400
	s_addc_u32 s13, s97, 0
	s_add_u32 s14, s96, 0x1f1ee500
	s_addc_u32 s15, s97, 0
	s_add_u32 s16, s96, 0x1f1ee600
	s_addc_u32 s17, s97, 0
	s_add_u32 s18, s96, 0x1f1ee700
	s_addc_u32 s19, s97, 0
	s_add_u32 s28, s96, 0x1f1ee800
	s_addc_u32 s29, s97, 0
	s_add_u32 s30, s96, 0x1f1ee900
	s_addc_u32 s31, s97, 0
	s_add_u32 s34, s96, 0x1f1eea00
	s_addc_u32 s35, s97, 0
	s_add_u32 s36, s96, 0x1f1eeb00
	s_addc_u32 s37, s97, 0
	s_add_u32 s38, s96, 0x1f1eec00
	s_addc_u32 s39, s97, 0
	s_add_u32 s40, s96, 0x1f1eed00
	s_addc_u32 s41, s97, 0
	s_add_u32 s42, s96, 0x1f1eee00
	s_addc_u32 s43, s97, 0
	s_add_u32 s44, s96, 0x1f1eef00
	s_mul_i32 s20, s20, s84
	s_addc_u32 s45, s97, 0
	s_mov_b32 s21, 1
	v_mov_b32_e32 v16, 0
	s_branch .LBB0_1214

; __device__ __forceinline__ float delta_prep(const Params& p, int l, int h, bool isP, int grow0, int t0, int nvalid, int bb, char* sm) {
;     ...
;       if (tid < 256) {
;         float a[16];
; #pragma unroll
;         for (int ii = 0; ii < 16; ++ii) a[ii] = xs[(ib * 16 + ii) * 256 + tid];
; #pragma unroll
;         for (int j = 0; j < 16; ++j) {
;           const float xj = a[j];
;           const float* mp = MT + (ib * 16 + j) * 64 + ib * 16;
; #pragma unroll
;           for (int ii = j + 1; ii < 16; ++ii) a[ii] -= mp[ii] * xj;
;         }
;         bfraw* dst = (tid < 128) ? XTu + tid * 72 + ib * 16 : XTw + (tid - 128) * 72 + ib * 16;
;         *(uint4*)dst = pack8(a);
;         *(uint4*)(dst + 8) = pack8(a + 8);
;       }
;       __syncthreads();
.LBB0_1461:
	s_or_b64 exec, exec, s[0:1]
	v_mul_lo_u32 v1, v0, s43
	s_movk_i32 s0, 0x100
	v_add_u32_e32 v1, 0, v1
	v_cmp_gt_i32_e32 vcc, s0, v0
	v_add_u32_e32 v15, 0xffffb800, v1
	s_waitcnt lgkmcnt(0)
	s_barrier
	s_and_saveexec_b64 s[0:1], vcc
	s_cbranch_execz .LBB0_1463
	v_lshl_add_u32 v4, v0, 2, 0
	v_add_u32_e32 v6, 0x13c00, v4
	v_add_u32_e32 v19, 0xf400, v1
	v_cmp_gt_i32_e32 vcc, s97, v0
	v_cndmask_b32_e32 v11, v15, v19, vcc
	ds_read2st64_b32 v[168:169], v6 offset1:4
	ds_read2st64_b32 v[170:171], v6 offset0:8 offset1:12
	ds_read2st64_b32 v[172:173], v6 offset0:16 offset1:20
	ds_read2st64_b32 v[174:175], v6 offset0:24 offset1:28
	ds_read2st64_b32 v[176:177], v6 offset0:32 offset1:36
	ds_read2st64_b32 v[178:179], v6 offset0:40 offset1:44
	ds_read2st64_b32 v[180:181], v6 offset0:48 offset1:52
	ds_read2st64_b32 v[182:183], v6 offset0:56 offset1:60
	v_mov_b32_e32 v167, 0x23c00
	ds_read_b32 v184, v167 offset:4
	ds_read_b64 v[186:187], v167 offset:8
	ds_read_b128 v[188:191], v167 offset:16
	ds_read_b128 v[192:195], v167 offset:32
	ds_read_b128 v[196:199], v167 offset:48
	ds_read_b64 v[200:201], v167 offset:264
	ds_read_b128 v[202:205], v167 offset:272
	ds_read_b128 v[206:209], v167 offset:288
	ds_read_b128 v[210:213], v167 offset:304
	ds_read_b32 v185, v167 offset:524
	ds_read_b128 v[214:217], v167 offset:528
	ds_read_b128 v[218:221], v167 offset:544
	ds_read_b128 v[226:229], v167 offset:560
	s_waitcnt lgkmcnt(13)
	ds_read_b128 v[230:233], v167 offset:784
	ds_read_b128 v[234:237], v167 offset:800
	ds_read_b128 v[238:241], v167 offset:816
	s_waitcnt lgkmcnt(11)
	v_fma_f32 v169, -v168, v184, v169
	v_pk_fma_f32 v[170:171], v[168:169], v[186:187], v[170:171] op_sel_hi:[0,1,1] neg_lo:[1,0,0] neg_hi:[1,0,0]
	v_pk_fma_f32 v[172:173], v[168:169], v[188:189], v[172:173] op_sel_hi:[0,1,1] neg_lo:[1,0,0] neg_hi:[1,0,0]
	v_pk_fma_f32 v[174:175], v[168:169], v[190:191], v[174:175] op_sel_hi:[0,1,1] neg_lo:[1,0,0] neg_hi:[1,0,0]
	v_pk_fma_f32 v[176:177], v[168:169], v[192:193], v[176:177] op_sel_hi:[0,1,1] neg_lo:[1,0,0] neg_hi:[1,0,0]
	v_pk_fma_f32 v[178:179], v[168:169], v[194:195], v[178:179] op_sel_hi:[0,1,1] neg_lo:[1,0,0] neg_hi:[1,0,0]
	v_pk_fma_f32 v[180:181], v[168:169], v[196:197], v[180:181] op_sel_hi:[0,1,1] neg_lo:[1,0,0] neg_hi:[1,0,0]
	v_pk_fma_f32 v[182:183], v[168:169], v[198:199], v[182:183] op_sel_hi:[0,1,1] neg_lo:[1,0,0] neg_hi:[1,0,0]
	ds_read_b32 v184, v167 offset:1044
	ds_read_b64 v[186:187], v167 offset:1048
	ds_read_b128 v[188:191], v167 offset:1056
	ds_read_b128 v[192:195], v167 offset:1072
	s_waitcnt lgkmcnt(11)
	v_pk_fma_f32 v[170:171], v[168:169], v[200:201], v[170:171] op_sel:[1,0,0] op_sel_hi:[1,1,1] neg_lo:[1,0,0] neg_hi:[1,0,0]
	v_pk_fma_f32 v[172:173], v[168:169], v[202:203], v[172:173] op_sel:[1,0,0] op_sel_hi:[1,1,1] neg_lo:[1,0,0] neg_hi:[1,0,0]
	v_pk_fma_f32 v[174:175], v[168:169], v[204:205], v[174:175] op_sel:[1,0,0] op_sel_hi:[1,1,1] neg_lo:[1,0,0] neg_hi:[1,0,0]
	v_pk_fma_f32 v[176:177], v[168:169], v[206:207], v[176:177] op_sel:[1,0,0] op_sel_hi:[1,1,1] neg_lo:[1,0,0] neg_hi:[1,0,0]
	v_pk_fma_f32 v[178:179], v[168:169], v[208:209], v[178:179] op_sel:[1,0,0] op_sel_hi:[1,1,1] neg_lo:[1,0,0] neg_hi:[1,0,0]
	v_pk_fma_f32 v[180:181], v[168:169], v[210:211], v[180:181] op_sel:[1,0,0] op_sel_hi:[1,1,1] neg_lo:[1,0,0] neg_hi:[1,0,0]
	v_pk_fma_f32 v[182:183], v[168:169], v[212:213], v[182:183] op_sel:[1,0,0] op_sel_hi:[1,1,1] neg_lo:[1,0,0] neg_hi:[1,0,0]
	ds_read_b64 v[196:197], v167 offset:1304
	ds_read_b128 v[198:201], v167 offset:1312
	ds_read_b128 v[202:205], v167 offset:1328
	s_waitcnt lgkmcnt(10)
	v_fma_f32 v171, -v170, v185, v171
	v_pk_fma_f32 v[172:173], v[170:171], v[214:215], v[172:173] op_sel_hi:[0,1,1] neg_lo:[1,0,0] neg_hi:[1,0,0]
	v_pk_fma_f32 v[174:175], v[170:171], v[216:217], v[174:175] op_sel_hi:[0,1,1] neg_lo:[1,0,0] neg_hi:[1,0,0]
	v_pk_fma_f32 v[176:177], v[170:171], v[218:219], v[176:177] op_sel_hi:[0,1,1] neg_lo:[1,0,0] neg_hi:[1,0,0]
	v_pk_fma_f32 v[178:179], v[170:171], v[220:221], v[178:179] op_sel_hi:[0,1,1] neg_lo:[1,0,0] neg_hi:[1,0,0]
	v_pk_fma_f32 v[180:181], v[170:171], v[226:227], v[180:181] op_sel_hi:[0,1,1] neg_lo:[1,0,0] neg_hi:[1,0,0]
	v_pk_fma_f32 v[182:183], v[170:171], v[228:229], v[182:183] op_sel_hi:[0,1,1] neg_lo:[1,0,0] neg_hi:[1,0,0]
	ds_read_b32 v185, v167 offset:1564
	ds_read_b128 v[206:209], v167 offset:1568
	ds_read_b128 v[210:213], v167 offset:1584
	s_waitcnt lgkmcnt(10)
	v_pk_fma_f32 v[172:173], v[170:171], v[230:231], v[172:173] op_sel:[1,0,0] op_sel_hi:[1,1,1] neg_lo:[1,0,0] neg_hi:[1,0,0]
	v_pk_fma_f32 v[174:175], v[170:171], v[232:233], v[174:175] op_sel:[1,0,0] op_sel_hi:[1,1,1] neg_lo:[1,0,0] neg_hi:[1,0,0]
	v_pk_fma_f32 v[176:177], v[170:171], v[234:235], v[176:177] op_sel:[1,0,0] op_sel_hi:[1,1,1] neg_lo:[1,0,0] neg_hi:[1,0,0]
	v_pk_fma_f32 v[178:179], v[170:171], v[236:237], v[178:179] op_sel:[1,0,0] op_sel_hi:[1,1,1] neg_lo:[1,0,0] neg_hi:[1,0,0]
	v_pk_fma_f32 v[180:181], v[170:171], v[238:239], v[180:181] op_sel:[1,0,0] op_sel_hi:[1,1,1] neg_lo:[1,0,0] neg_hi:[1,0,0]
	v_pk_fma_f32 v[182:183], v[170:171], v[240:241], v[182:183] op_sel:[1,0,0] op_sel_hi:[1,1,1] neg_lo:[1,0,0] neg_hi:[1,0,0]
	ds_read_b128 v[214:217], v167 offset:1824
	ds_read_b128 v[218:221], v167 offset:1840
	s_waitcnt lgkmcnt(8)
; __device__ __forceinline__ float delta_prep(const Params& p, int l, int h, bool isP, int grow0, int t0, int nvalid, int bb, char* sm) {
;     ...
;       if (tid < 256) {
;         float a[16];
; #pragma unroll
;         for (int ii = 0; ii < 16; ++ii) a[ii] = xs[(ib * 16 + ii) * 256 + tid];
; #pragma unroll
;         for (int j = 0; j < 16; ++j) {
;           const float xj = a[j];
;           const float* mp = MT + (ib * 16 + j) * 64 + ib * 16;
; #pragma unroll
;           for (int ii = j + 1; ii < 16; ++ii) a[ii] -= mp[ii] * xj;
;         }
;         bfraw* dst = (tid < 128) ? XTu + tid * 72 + ib * 16 : XTw + (tid - 128) * 72 + ib * 16;
;         *(uint4*)dst = pack8(a);
;         *(uint4*)(dst + 8) = pack8(a + 8);
;       }
;       __syncthreads();
	v_fma_f32 v173, -v172, v184, v173
	v_pk_fma_f32 v[174:175], v[172:173], v[186:187], v[174:175] op_sel_hi:[0,1,1] neg_lo:[1,0,0] neg_hi:[1,0,0]
	v_pk_fma_f32 v[176:177], v[172:173], v[188:189], v[176:177] op_sel_hi:[0,1,1] neg_lo:[1,0,0] neg_hi:[1,0,0]
	v_pk_fma_f32 v[178:179], v[172:173], v[190:191], v[178:179] op_sel_hi:[0,1,1] neg_lo:[1,0,0] neg_hi:[1,0,0]
	v_pk_fma_f32 v[180:181], v[172:173], v[192:193], v[180:181] op_sel_hi:[0,1,1] neg_lo:[1,0,0] neg_hi:[1,0,0]
	v_pk_fma_f32 v[182:183], v[172:173], v[194:195], v[182:183] op_sel_hi:[0,1,1] neg_lo:[1,0,0] neg_hi:[1,0,0]
	ds_read_b32 v184, v167 offset:2084
	ds_read_b64 v[186:187], v167 offset:2088
	ds_read_b128 v[188:191], v167 offset:2096
	s_waitcnt lgkmcnt(8)
	v_pk_fma_f32 v[174:175], v[172:173], v[196:197], v[174:175] op_sel:[1,0,0] op_sel_hi:[1,1,1] neg_lo:[1,0,0] neg_hi:[1,0,0]
	v_pk_fma_f32 v[176:177], v[172:173], v[198:199], v[176:177] op_sel:[1,0,0] op_sel_hi:[1,1,1] neg_lo:[1,0,0] neg_hi:[1,0,0]
	v_pk_fma_f32 v[178:179], v[172:173], v[200:201], v[178:179] op_sel:[1,0,0] op_sel_hi:[1,1,1] neg_lo:[1,0,0] neg_hi:[1,0,0]
	v_pk_fma_f32 v[180:181], v[172:173], v[202:203], v[180:181] op_sel:[1,0,0] op_sel_hi:[1,1,1] neg_lo:[1,0,0] neg_hi:[1,0,0]
	v_pk_fma_f32 v[182:183], v[172:173], v[204:205], v[182:183] op_sel:[1,0,0] op_sel_hi:[1,1,1] neg_lo:[1,0,0] neg_hi:[1,0,0]
	ds_read_b64 v[192:193], v167 offset:2344
	ds_read_b128 v[194:197], v167 offset:2352
	s_waitcnt lgkmcnt(7)
	v_fma_f32 v175, -v174, v185, v175
	v_pk_fma_f32 v[176:177], v[174:175], v[206:207], v[176:177] op_sel_hi:[0,1,1] neg_lo:[1,0,0] neg_hi:[1,0,0]
	v_pk_fma_f32 v[178:179], v[174:175], v[208:209], v[178:179] op_sel_hi:[0,1,1] neg_lo:[1,0,0] neg_hi:[1,0,0]
	v_pk_fma_f32 v[180:181], v[174:175], v[210:211], v[180:181] op_sel_hi:[0,1,1] neg_lo:[1,0,0] neg_hi:[1,0,0]
	v_pk_fma_f32 v[182:183], v[174:175], v[212:213], v[182:183] op_sel_hi:[0,1,1] neg_lo:[1,0,0] neg_hi:[1,0,0]
	ds_read_b32 v185, v167 offset:2604
	ds_read_b128 v[198:201], v167 offset:2608
	s_waitcnt lgkmcnt(7)
	v_pk_fma_f32 v[176:177], v[174:175], v[214:215], v[176:177] op_sel:[1,0,0] op_sel_hi:[1,1,1] neg_lo:[1,0,0] neg_hi:[1,0,0]
	v_pk_fma_f32 v[178:179], v[174:175], v[216:217], v[178:179] op_sel:[1,0,0] op_sel_hi:[1,1,1] neg_lo:[1,0,0] neg_hi:[1,0,0]
	v_pk_fma_f32 v[180:181], v[174:175], v[218:219], v[180:181] op_sel:[1,0,0] op_sel_hi:[1,1,1] neg_lo:[1,0,0] neg_hi:[1,0,0]
	v_pk_fma_f32 v[182:183], v[174:175], v[220:221], v[182:183] op_sel:[1,0,0] op_sel_hi:[1,1,1] neg_lo:[1,0,0] neg_hi:[1,0,0]
	ds_read_b128 v[202:205], v167 offset:2864
	s_waitcnt lgkmcnt(5)
	v_fma_f32 v177, -v176, v184, v177
	v_pk_fma_f32 v[178:179], v[176:177], v[186:187], v[178:179] op_sel_hi:[0,1,1] neg_lo:[1,0,0] neg_hi:[1,0,0]
	v_pk_fma_f32 v[180:181], v[176:177], v[188:189], v[180:181] op_sel_hi:[0,1,1] neg_lo:[1,0,0] neg_hi:[1,0,0]
	v_pk_fma_f32 v[182:183], v[176:177], v[190:191], v[182:183] op_sel_hi:[0,1,1] neg_lo:[1,0,0] neg_hi:[1,0,0]
	ds_read_b32 v184, v167 offset:3124
	ds_read_b64 v[186:187], v167 offset:3128
	s_waitcnt lgkmcnt(5)
	v_pk_fma_f32 v[178:179], v[176:177], v[192:193], v[178:179] op_sel:[1,0,0] op_sel_hi:[1,1,1] neg_lo:[1,0,0] neg_hi:[1,0,0]
	v_pk_fma_f32 v[180:181], v[176:177], v[194:195], v[180:181] op_sel:[1,0,0] op_sel_hi:[1,1,1] neg_lo:[1,0,0] neg_hi:[1,0,0]
	v_pk_fma_f32 v[182:183], v[176:177], v[196:197], v[182:183] op_sel:[1,0,0] op_sel_hi:[1,1,1] neg_lo:[1,0,0] neg_hi:[1,0,0]
	ds_read_b64 v[188:189], v167 offset:3384
	s_waitcnt lgkmcnt(4)
	v_fma_f32 v179, -v178, v185, v179
	v_pk_fma_f32 v[180:181], v[178:179], v[198:199], v[180:181] op_sel_hi:[0,1,1] neg_lo:[1,0,0] neg_hi:[1,0,0]
	v_pk_fma_f32 v[182:183], v[178:179], v[200:201], v[182:183] op_sel_hi:[0,1,1] neg_lo:[1,0,0] neg_hi:[1,0,0]
	ds_read_b32 v185, v167 offset:3644
	s_waitcnt lgkmcnt(4)
	v_pk_fma_f32 v[180:181], v[178:179], v[202:203], v[180:181] op_sel:[1,0,0] op_sel_hi:[1,1,1] neg_lo:[1,0,0] neg_hi:[1,0,0]
	v_pk_fma_f32 v[182:183], v[178:179], v[204:205], v[182:183] op_sel:[1,0,0] op_sel_hi:[1,1,1] neg_lo:[1,0,0] neg_hi:[1,0,0]
	s_waitcnt lgkmcnt(2)
	v_fma_f32 v181, -v180, v184, v181
	v_pk_fma_f32 v[182:183], v[180:181], v[186:187], v[182:183] op_sel_hi:[0,1,1] neg_lo:[1,0,0] neg_hi:[1,0,0]
	s_waitcnt lgkmcnt(1)
	v_pk_fma_f32 v[182:183], v[180:181], v[188:189], v[182:183] op_sel:[1,0,0] op_sel_hi:[1,1,1] neg_lo:[1,0,0] neg_hi:[1,0,0]
	s_waitcnt lgkmcnt(0)
	v_fma_f32 v183, -v182, v185, v183
	v_cvt_pk_bf16_f32 v184, v168, v169
	v_cvt_pk_bf16_f32 v185, v170, v171
	v_cvt_pk_bf16_f32 v186, v172, v173
	v_cvt_pk_bf16_f32 v187, v174, v175
	ds_write_b128 v11, v[184:187]
	v_cvt_pk_bf16_f32 v188, v176, v177
	v_cvt_pk_bf16_f32 v189, v178, v179
	v_cvt_pk_bf16_f32 v190, v180, v181
	v_cvt_pk_bf16_f32 v191, v182, v183
	ds_write_b128 v11, v[188:191] offset:16
	v_readlane_b32 s2, v246, 33

; __device__ __forceinline__ float delta_prep(const Params& p, int l, int h, bool isP, int grow0, int t0, int nvalid, int bb, char* sm) {
;     ...
;         for (int ii = 0; ii < 16; ++ii) a[ii] = xs[(ib * 16 + ii) * 256 + tid];
; #pragma unroll
;         for (int j = 0; j < 16; ++j) {
;           const float xj = a[j];
;           const float* mp = MT + (ib * 16 + j) * 64 + ib * 16;
; #pragma unroll
;           for (int ii = j + 1; ii < 16; ++ii) a[ii] -= mp[ii] * xj;
;         }
; __device__ __forceinline__ void phase_f1(const Params& p, int l, char* sm) {
;   constexpr int NPOOL = (NBP * NCH + 16) * 4;
;   for (int it = blockIdx.x; it < NUNIT_P + NPOOL; it += gridDim.x) {
;     if (it < NUNIT_P) f1_unit(p, l, it, sm);
.LBB0_3493:
	s_cmp_gt_i32 s94, 13
	s_cselect_b64 s[0:1], -1, 0
	s_cmp_lt_i32 s95, 14
	s_cselect_b64 s[2:3], -1, 0
	s_or_b64 s[0:1], s[0:1], s[2:3]
	s_and_b64 vcc, exec, s[0:1]
	s_cbranch_vccnz .LBB0_4021
	s_cmpk_gt_i32 s54, 0x105f
	s_cbranch_scc1 .LBB0_3819
	v_readlane_b32 s16, v247, 60
	v_readlane_b32 s17, v247, 61
	s_add_u32 s38, s16, 0x6420000
	s_addc_u32 s39, s17, 0
	s_add_u32 s34, s16, 0x13c40000
	s_addc_u32 s35, s17, 0
	s_add_u32 s36, s16, 0xc80000
	s_addc_u32 s37, s17, 0
	s_add_u32 s24, s16, 0x1eea0000
	v_readlane_b32 s0, v247, 23
	s_addc_u32 s25, s17, 0
	v_readlane_b32 s8, v247, 31
	v_readlane_b32 s9, v247, 32
	s_add_u32 s46, s8, 0x6000
	s_addc_u32 s47, s9, 0
	s_add_u32 s26, s16, 0x1efaa000
	s_addc_u32 s27, s17, 0
	s_add_u32 s54, s16, 0x15d80000
	s_addc_u32 s66, s17, 0
	s_add_i32 s0, 0, 0x23c28
	v_readlane_b32 s1, v247, 24
	v_readlane_b32 s2, v247, 25
	v_readlane_b32 s3, v247, 26
	v_readlane_b32 s4, v247, 27
	v_readlane_b32 s5, v247, 28
	v_readlane_b32 s6, v247, 29
	v_readlane_b32 s7, v247, 30
	v_readlane_b32 s10, v247, 33
	v_readlane_b32 s11, v247, 34
	v_readlane_b32 s12, v247, 35
	v_readlane_b32 s13, v247, 36
	v_readlane_b32 s14, v247, 37
	v_readlane_b32 s15, v247, 38
	v_writelane_b32 v247, s0, 63
	s_add_i32 s0, 0, 0x23c08
	v_writelane_b32 v246, s0, 0
	s_add_i32 s0, 0, 0x23d08
	v_writelane_b32 v246, s0, 1
	s_add_i32 s0, 0, 0x23c38
	v_writelane_b32 v246, s0, 2
	s_add_i32 s0, 0, 0x23d38
	v_writelane_b32 v246, s0, 3
	s_add_i32 s0, 0, 0x23e0c
	v_writelane_b32 v246, s0, 4
	s_add_i32 s0, 0, 0x23e30
	v_writelane_b32 v246, s0, 5
	s_add_i32 s0, 0, 0x23e10
	v_writelane_b32 v246, s0, 6
	s_add_i32 s0, 0, 0x23f10
	v_writelane_b32 v246, s0, 7
	s_add_i32 s0, 0, 0x24014
	v_writelane_b32 v246, s0, 8
	s_add_i32 s0, 0, 0x23c18
	v_writelane_b32 v246, s0, 9
	s_add_i32 s0, 0, 0x23d18
	v_writelane_b32 v246, s0, 10
	s_add_i32 s0, 0, 0x24018
	v_writelane_b32 v246, s0, 11
	s_add_i32 s0, 0, 0x24118
	v_writelane_b32 v246, s0, 12
	s_add_i32 s0, 0, 0x2421c
	v_writelane_b32 v246, s0, 13
	s_add_i32 s0, 0, 0x23e20
	v_writelane_b32 v246, s0, 14
	s_add_i32 s0, 0, 0x23f20
	v_writelane_b32 v246, s0, 15
	s_add_i32 s0, 0, 0x24220
	v_writelane_b32 v246, s0, 16
	s_add_i32 s0, 0, 0x24320
	v_writelane_b32 v246, s0, 17
	s_add_i32 s0, 0, 0x24424
	v_writelane_b32 v246, s0, 18
	s_add_i32 s0, 0, 0x23d28
	v_writelane_b32 v246, s0, 19
	s_add_i32 s0, 0, 0x24028
	v_writelane_b32 v246, s0, 20
	s_add_i32 s0, 0, 0x24128
	v_writelane_b32 v246, s0, 21
	s_add_i32 s0, 0, 0x24428
	v_writelane_b32 v246, s0, 22
	s_add_i32 s0, 0, 0x24528
	v_writelane_b32 v246, s0, 23
	s_add_i32 s0, 0, 0x2462c
	v_writelane_b32 v246, s0, 24
	s_add_i32 s0, 0, 0x24c44
	v_writelane_b32 v246, s0, 25
	s_add_i32 s0, 0, 0x24c68
	v_writelane_b32 v246, s0, 26
	s_add_i32 s0, 0, 0x24c48
	v_writelane_b32 v246, s0, 27
	s_add_i32 s0, 0, 0x24d48
	v_writelane_b32 v246, s0, 28
	s_add_i32 s0, 0, 0x24c78
	v_writelane_b32 v246, s0, 29
	s_add_i32 s0, 0, 0x24d78
	v_writelane_b32 v246, s0, 30
	s_add_i32 s0, 0, 0x24e4c
	v_writelane_b32 v246, s0, 31
	s_add_i32 s0, 0, 0x24e70
	v_writelane_b32 v246, s0, 32
	s_add_i32 s0, 0, 0x24e50
	v_writelane_b32 v246, s0, 33
	s_add_i32 s0, 0, 0x24f50
	v_writelane_b32 v246, s0, 34
	s_add_i32 s0, 0, 0x25054
	v_writelane_b32 v246, s0, 35
	s_add_i32 s0, 0, 0x24c58
	v_writelane_b32 v246, s0, 36
	s_add_i32 s0, 0, 0x24d58
	v_writelane_b32 v246, s0, 37
	s_add_i32 s0, 0, 0x25058
	v_writelane_b32 v246, s0, 38
	s_add_i32 s0, 0, 0x25158
	v_writelane_b32 v246, s0, 39
	s_add_i32 s0, 0, 0x2525c
	v_writelane_b32 v246, s0, 40
	s_add_i32 s0, 0, 0x24e60
	v_writelane_b32 v246, s0, 41
	s_add_i32 s0, 0, 0x24f60
	v_writelane_b32 v246, s0, 42
	s_add_i32 s0, 0, 0x25260
	v_writelane_b32 v246, s0, 43
	s_add_i32 s0, 0, 0x25360
	v_writelane_b32 v246, s0, 44
	s_add_i32 s0, 0, 0x25464
	v_writelane_b32 v246, s0, 45
	s_add_i32 s0, 0, 0x24d68
	v_writelane_b32 v246, s0, 47
	s_add_i32 s0, 0, 0x25068
	v_writelane_b32 v246, s0, 48
	s_add_i32 s0, 0, 0x25168
	v_writelane_b32 v246, s0, 49
	s_add_i32 s0, 0, 0x25468
	v_writelane_b32 v246, s0, 50
	s_add_i32 s0, 0, 0x25568
	v_writelane_b32 v246, s0, 51
	s_add_i32 s0, 0, 0x2566c
	v_writelane_b32 v246, s0, 52
	s_add_i32 s0, 0, 0x24f70
	v_writelane_b32 v246, s0, 53
	s_add_i32 s0, 0, 0x25270
	v_writelane_b32 v246, s0, 54
	s_add_i32 s0, 0, 0x25370
	v_writelane_b32 v246, s0, 55
	s_add_i32 s0, 0, 0x25670
	v_writelane_b32 v246, s0, 56
	s_add_i32 s0, 0, 0x25770
	v_writelane_b32 v246, s0, 57
	s_add_i32 s0, 0, 0x25874
	v_writelane_b32 v246, s0, 58
	s_add_i32 s0, 0, 0x25078
	v_writelane_b32 v246, s0, 59
	s_add_i32 s0, 0, 0x25178
	v_writelane_b32 v246, s0, 60
	s_add_i32 s0, 0, 0x25478
	v_writelane_b32 v246, s0, 61
	s_add_i32 s0, 0, 0x25578
	v_writelane_b32 v246, s0, 62
	s_add_i32 s0, 0, 0x25878
	v_writelane_b32 v246, s0, 63
	s_add_i32 s0, 0, 0x25978
	v_writelane_b32 v245, s0, 0
	s_add_i32 s0, 0, 0x25a7c
	v_writelane_b32 v245, s0, 1
	s_add_i32 s0, 0, 0x25c84
	v_writelane_b32 v245, s0, 2
	s_add_i32 s0, 0, 0x25ca8
	v_writelane_b32 v245, s0, 3
	s_add_i32 s0, 0, 0x25c88
	v_writelane_b32 v245, s0, 4
	s_add_i32 s0, 0, 0x25d88
	v_writelane_b32 v245, s0, 5
	s_add_i32 s0, 0, 0x25cb8
	v_writelane_b32 v245, s0, 6
	s_add_i32 s0, 0, 0x25db8
	v_writelane_b32 v245, s0, 7
	s_add_i32 s0, 0, 0x25e8c
	v_writelane_b32 v245, s0, 8
	s_add_i32 s0, 0, 0x25eb0
	v_writelane_b32 v245, s0, 9
	s_add_i32 s0, 0, 0x25e90
	v_writelane_b32 v245, s0, 10
	s_add_i32 s0, 0, 0x25f90
	v_writelane_b32 v245, s0, 11
; __device__ __forceinline__ float delta_prep(const Params& p, int l, int h, bool isP, int grow0, int t0, int nvalid, int bb, char* sm) {
;     ...
;         for (int ii = 0; ii < 16; ++ii) a[ii] = xs[(ib * 16 + ii) * 256 + tid];
; #pragma unroll
;         for (int j = 0; j < 16; ++j) {
;           const float xj = a[j];
;           const float* mp = MT + (ib * 16 + j) * 64 + ib * 16;
; #pragma unroll
;           for (int ii = j + 1; ii < 16; ++ii) a[ii] -= mp[ii] * xj;
;         }
; __device__ __forceinline__ void phase_f1(const Params& p, int l, char* sm) {
;   constexpr int NPOOL = (NBP * NCH + 16) * 4;
;   for (int it = blockIdx.x; it < NUNIT_P + NPOOL; it += gridDim.x) {
;     if (it < NUNIT_P) f1_unit(p, l, it, sm);
	s_add_i32 s0, 0, 0x26094
	v_writelane_b32 v245, s0, 12
	s_add_i32 s0, 0, 0x25c98
	v_writelane_b32 v245, s0, 13
	s_add_i32 s0, 0, 0x25d98
	v_writelane_b32 v245, s0, 14
	s_add_i32 s0, 0, 0x26098
	v_writelane_b32 v245, s0, 15
	s_add_i32 s0, 0, 0x26198
	v_writelane_b32 v245, s0, 16
	s_add_i32 s0, 0, 0x2629c
	v_writelane_b32 v245, s0, 17
	s_add_i32 s0, 0, 0x25ea0
	v_writelane_b32 v245, s0, 18
	s_add_i32 s0, 0, 0x25fa0
	v_writelane_b32 v245, s0, 19
	s_add_i32 s0, 0, 0x262a0
	v_writelane_b32 v245, s0, 20
	s_add_i32 s0, 0, 0x263a0
	v_writelane_b32 v245, s0, 21
	s_add_i32 s0, 0, 0x264a4
	v_writelane_b32 v245, s0, 22
	s_add_i32 s0, 0, 0x25da8
	v_writelane_b32 v245, s0, 23
	s_add_i32 s0, 0, 0x260a8
	v_writelane_b32 v245, s0, 24
	s_add_i32 s0, 0, 0x261a8
	v_writelane_b32 v245, s0, 25
	s_add_i32 s0, 0, 0x264a8
	v_writelane_b32 v245, s0, 26
	s_add_i32 s0, 0, 0x265a8
	v_writelane_b32 v245, s0, 27
	s_add_i32 s0, 0, 0x266ac
	v_writelane_b32 v245, s0, 28
	s_add_i32 s0, 0, 0x25fb0
	v_writelane_b32 v245, s0, 29
	s_add_i32 s0, 0, 0x262b0
	v_writelane_b32 v245, s0, 30
	s_add_i32 s0, 0, 0x263b0
	v_writelane_b32 v245, s0, 31
	s_add_i32 s0, 0, 0x266b0
	v_writelane_b32 v245, s0, 32
	s_add_i32 s0, 0, 0x267b0
	v_writelane_b32 v245, s0, 33
	s_add_i32 s0, 0, 0x268b4
	v_writelane_b32 v245, s0, 34
	s_add_i32 s0, 0, 0x260b8
	v_writelane_b32 v245, s0, 35
	s_add_i32 s0, 0, 0x261b8
	v_writelane_b32 v245, s0, 36
	s_add_i32 s0, 0, 0x264b8
	v_writelane_b32 v245, s0, 37
	s_add_i32 s0, 0, 0x265b8
	v_writelane_b32 v245, s0, 38
	s_add_i32 s0, 0, 0x268b8
	v_writelane_b32 v245, s0, 39
	s_add_i32 s0, 0, 0x269b8
	v_writelane_b32 v245, s0, 40
	s_add_i32 s0, 0, 0x26abc
	v_writelane_b32 v245, s0, 41
	s_add_i32 s0, 0, 0x26cc4
	v_writelane_b32 v245, s0, 42
	s_add_i32 s0, 0, 0x26ce8
	v_writelane_b32 v245, s0, 43
	s_add_i32 s0, 0, 0x26cc8
	v_writelane_b32 v245, s0, 44
	s_add_i32 s0, 0, 0x26dc8
	v_writelane_b32 v245, s0, 45
	s_add_i32 s0, 0, 0x26cf8
	v_writelane_b32 v245, s0, 46
	s_add_i32 s0, 0, 0x26df8
	v_writelane_b32 v245, s0, 47
	s_add_i32 s0, 0, 0x26ecc
	v_writelane_b32 v245, s0, 48
	s_add_i32 s0, 0, 0x26ef0
	v_writelane_b32 v245, s0, 49
	s_add_i32 s0, 0, 0x26ed0
	v_writelane_b32 v245, s0, 50
	s_add_i32 s0, 0, 0x26fd0
	v_writelane_b32 v245, s0, 51
	s_add_i32 s0, 0, 0x270d4
	v_writelane_b32 v245, s0, 52
	s_add_i32 s0, 0, 0x26cd8
	v_writelane_b32 v245, s0, 53
	s_add_i32 s0, 0, 0x26dd8
	v_writelane_b32 v245, s0, 54
	s_add_i32 s0, 0, 0x270d8
	v_writelane_b32 v245, s0, 55
	s_add_i32 s0, 0, 0x271d8
	v_writelane_b32 v245, s0, 56
	s_add_i32 s0, 0, 0x272dc
	v_writelane_b32 v245, s0, 57
	s_add_i32 s0, 0, 0x26ee0
	v_writelane_b32 v245, s0, 58
	s_add_i32 s0, 0, 0x26fe0
	v_writelane_b32 v245, s0, 59
	s_add_i32 s0, 0, 0x272e0
	v_writelane_b32 v245, s0, 60
	s_add_i32 s0, 0, 0x273e0
	v_writelane_b32 v245, s0, 61
	s_add_i32 s0, 0, 0x274e4
	v_writelane_b32 v245, s0, 62
	s_add_i32 s0, 0, 0x26de8
	v_writelane_b32 v245, s0, 63
	s_add_i32 s0, 0, 0x270e8
	v_writelane_b32 v244, s0, 0
	s_add_i32 s0, 0, 0x271e8
	v_writelane_b32 v244, s0, 1
	s_add_i32 s0, 0, 0x274e8
	v_writelane_b32 v244, s0, 2
	s_add_i32 s0, 0, 0x275e8
	v_writelane_b32 v244, s0, 3
	s_add_i32 s0, 0, 0x276ec
	v_writelane_b32 v244, s0, 4
	s_add_i32 s0, 0, 0x26ff0
	v_writelane_b32 v244, s0, 5
	s_add_i32 s0, 0, 0x272f0
	v_writelane_b32 v244, s0, 6
	s_add_i32 s0, 0, 0x273f0
	v_writelane_b32 v244, s0, 7
	s_add_i32 s0, 0, 0x276f0
	v_writelane_b32 v244, s0, 8
	s_add_i32 s0, 0, 0x277f0
	v_writelane_b32 v244, s0, 9
	s_add_i32 s0, 0, 0x278f4
	v_writelane_b32 v244, s0, 10
	s_add_i32 s0, 0, 0x270f8
	v_writelane_b32 v244, s0, 11
	s_add_i32 s0, 0, 0x271f8
	v_writelane_b32 v244, s0, 12
	s_add_i32 s0, 0, 0x274f8
	v_writelane_b32 v244, s0, 13
	s_add_i32 s0, 0, 0x275f8
	v_writelane_b32 v244, s0, 14
	s_add_i32 s0, 0, 0x278f8
	v_writelane_b32 v244, s0, 15
	s_add_i32 s0, 0, 0x279f8
	v_writelane_b32 v244, s0, 16
	s_add_i32 s0, 0, 0x27afc
	s_waitcnt vmcnt(0)
	v_mbcnt_lo_u32_b32 v0, -1, 0
	v_writelane_b32 v244, s0, 17
	v_readlane_b32 s0, v247, 62
	s_movk_i32 s52, 0x2010
	v_mov_b32_e32 v61, 0
	s_mov_b32 s53, 0xb21642c9
	s_movk_i32 s20, 0xffe9
	s_mov_b32 s67, 0x8031
	s_movk_i32 s56, 0x80
	s_movk_i32 s57, 0x110
	s_movk_i32 s72, 0x1000
	s_movk_i32 s73, 0x2000
	s_movk_i32 s74, 0x3000
	s_add_i32 s71, 0, 0xc9e0
	s_mov_b32 s82, 0x5040100
	s_mov_b32 s83, 0x7a44c6b
	s_movk_i32 s86, 0xfbd0
	s_movk_i32 s87, 0x90
	s_add_i32 s88, 0, 0x13c00
	s_movk_i32 s89, 0x43
	s_mov_b32 s75, 0xbfb8aa3b
	v_mov_b32_e32 v156, 0x3ecc95a3
	s_mov_b32 s91, 0x3fb8aa3b
	s_mov_b32 s92, 0xc2ce8ed0
	s_mov_b32 s93, 0x42b17218
	s_add_i32 s94, 0, 0x27c00
	s_movk_i32 s76, 0x4000
	s_mov_b32 s77, 0x800000
	s_movk_i32 s78, 0x5000
	s_add_i32 s97, 0, 0x4400
	s_add_i32 s90, 0, 0x23c00
	s_add_i32 s79, 0, 0x23c04
	v_mov_b32_e32 v157, 0x7f800000
	v_mov_b32_e32 v62, 0x3f317218
	v_mbcnt_hi_u32_b32 v158, -1, v0
	v_mov_b32_e32 v159, 0xffffb800
	v_mov_b32_e32 v160, 0xf400
	v_mov_b32_e32 v161, 0x4400
	s_add_i32 s51, 0, 0x23f30
	s_add_i32 s33, 0, 0x24230
	s_add_i32 s55, 0, 0x24330
	s_add_i32 s40, 0, 0x24630
	s_add_i32 s41, 0, 0x24730
	s_add_i32 s68, 0, 0x24834
	s_add_i32 s69, 0, 0x24038
	s_add_i32 s70, 0, 0x24138
	s_add_i32 s95, 0, 0x24438
	s_add_i32 s96, 0, 0x24538
	s_add_i32 s21, 0, 0x24838
	s_add_i32 s48, 0, 0x24938
	s_add_i32 s49, 0, 0x24a3c
	s_add_i32 s50, 0, 0x27cfc
	s_mov_b64 s[42:43], 0x2000
	s_mov_b32 s44, s0
	s_mov_b32 s28, 0
	s_mov_b32 s101, 0
	s_branch .LBB0_3498

; __device__ __forceinline__ void phase_f1(const Params& p, int l, char* sm) {
;     ...
;   for (int it = blockIdx.x; it < NUNIT_P + NPOOL; it += gridDim.x) {
;     if (it < NUNIT_P) f1_unit(p, l, it, sm);
;     else pool_item(p, l, it - NUNIT_P, sm);
.LBB0_3497:
	s_add_i32 s44, s44, s84
	s_cmpk_lg_u32 s84, 0x100
	s_cbranch_scc1 .Lf1bal1_std
	v_readlane_b32 s100, v247, 62
	s_nop 1
	s_cmp_lt_u32 s100, 16
	s_cbranch_scc0 .Lf1bal1_hi
	s_cmpk_lt_i32 s44, 0xe00
	s_cbranch_scc1 .Lf1bal1_cont
	s_branch .Lf1bal1_exit
.Lf1bal1_hi:
	s_cmpk_gt_i32 s44, 0x105f
	s_cbranch_scc0 .Lf1bal1_cont
	s_cmp_lg_u32 s101, 0
	s_cbranch_scc1 .Lf1bal1_exit
	s_sub_u32 s100, s100, 0x60
	s_cmp_lt_u32 s100, 48
	s_cbranch_scc0 .Lf1bal1_exit
	s_mov_b32 s101, 1
	s_lshr_b32 s44, s100, 4
	s_add_u32 s44, s44, 14
	s_lshl_b32 s44, s44, 8
	s_and_b32 s100, s100, 15
	s_add_u32 s44, s44, s100
	s_branch .Lf1bal1_cont
.Lf1bal1_std:
	s_cmpk_gt_i32 s44, 0x105f
	s_cbranch_scc0 .Lf1bal1_cont

; __device__ __forceinline__ void phase_f1(const Params& p, int l, char* sm) {
;     ...
;   for (int it = blockIdx.x; it < NUNIT_P + NPOOL; it += gridDim.x) {
;     if (it < NUNIT_P) f1_unit(p, l, it, sm);
;     else pool_item(p, l, it - NUNIT_P, sm);
.Lf1bal1_cont:
	s_waitcnt lgkmcnt(0)
.LBB0_3498:
	s_ashr_i32 s45, s44, 31
	s_cmpk_gt_i32 s44, 0x80f
	s_mov_b64 s[0:1], -1
	s_cbranch_scc0 .LBB0_3624
	s_add_i32 s6, s44, 0xfffff7f0
	s_lshr_b32 s7, s6, 2
	s_cmpk_lt_u32 s6, 0x810
	s_cselect_b64 s[2:3], -1, 0
	s_cmpk_gt_u32 s6, 0x80f
	s_cselect_b64 s[0:1], -1, 0
	v_mov_b32_e32 v35, v224
	s_mov_b64 s[4:5], -1
	s_and_b64 vcc, exec, s[0:1]
	s_cbranch_vccz .LBB0_3501
	s_lshl_b32 s4, s7, 6
	s_add_i32 s29, s4, 0xffffff40
	s_mov_b64 s[4:5], 0

; __device__ __forceinline__ void pool_item(const Params& p, int l, int it, char* smem_c) {
;     ...
;   const int rt = it >> 2, g = it & 3;
;   int grow0, nrows, t0 = 0;
;   const bool isP = rt < NBP * NCH;
;   if (isP) { int b = rt / NCH, i = rt - b * NCH; t0 = i * 64; nrows = min(64, TP - t0); grow0 = b * TP + t0; }
;   else { grow0 = ROWS_P + (rt - NBP * NCH) * 64; nrows = 64; }
;   const int wnd = 2 << g;
;   {
;     uint4 sv[6];
;     const int nch = isP ? 79 * 16 : 184 * 16;
; #pragma unroll
;     for (int i = 0; i < 6; ++i) {
;       const int c = tid + i * NTHR;
;       uint4 v = make_uint4(0u, 0u, 0u, 0u);
;       if (c < nch) {
;         const int rr = c >> 4, ch = c & 15;
;         if (isP) {
;           const int t = t0 - 15 + rr;
;           if (t >= 0 && t < TP) v = *(const uint4*)(B1 + (size_t)(grow0 - 15 + rr) * LD1 + g * 128 + ch * 8);
;         } else {
;           const int sg = rr / 23, pp = rr - sg * 23;
;           const int bb = ((grow0 - ROWS_P) >> 3) + sg;
;           if (pp < 15) {
;             const float* s = p.state_pool + ((size_t)(l * NBS + bb) * 15 + pp) * 512 + g * 128 + ch * 8;
;             float4 f0 = *(const float4*)s, f1 = *(const float4*)(s + 4);
;             v.x = pack2(f0.x, f0.y); v.y = pack2(f0.z, f0.w); v.z = pack2(f1.x, f1.y); v.w = pack2(f1.z, f1.w);
;           } else v = *(const uint4*)(B1 + (size_t)(ROWS_P + bb * TS + pp - 15) * LD1 + g * 128 + ch * 8);
;         }
.LBB0_3504:
	s_add_i32 s58, s44, 0xfffff7f0
	s_lshr_b32 s58, s58, 8
	s_add_i32 s58, s58, s44
	s_and_b32 s58, s58, 3
	s_add_i32 s4, s29, 0xffff7fc0
	s_ashr_i32 s61, s4, 3
	s_lshl_b32 s4, s58, 8
	v_and_b32_e32 v34, 15, v35
	s_add_u32 s4, s38, s4
	s_addc_u32 s5, s39, 0
	v_lshlrev_b32_e32 v60, 4, v34
	s_waitcnt lgkmcnt(0)
	v_lshl_add_u64 v[24:25], s[4:5], 0, v[60:61]
	v_readlane_b32 s4, v247, 7
	s_lshl_b32 s22, s58, 9
	v_readlane_b32 s8, v247, 11
	v_readlane_b32 s5, v247, 8
	v_readlane_b32 s9, v247, 12
	s_add_u32 s4, s8, s22
	s_addc_u32 s5, s9, 0
	v_lshlrev_b32_e32 v60, 5, v34
	v_readlane_b32 s6, v247, 9
	v_readlane_b32 s7, v247, 10
	v_lshl_add_u64 v[26:27], s[4:5], 0, v[60:61]
	s_add_i32 s60, s31, -15
	s_add_i32 s59, s29, -15
	v_cmp_gt_i32_e64 s[4:5], s62, v35
	v_mov_b32_e32 v0, 0
	v_mov_b32_e32 v4, 0
	v_mov_b32_e32 v5, 0
	v_mov_b32_e32 v6, 0
	v_mov_b32_e32 v7, 0
	v_readlane_b32 s10, v247, 13
	v_readlane_b32 s11, v247, 14
	v_readlane_b32 s12, v247, 15
	v_readlane_b32 s13, v247, 16
	v_readlane_b32 s14, v247, 17
	v_readlane_b32 s15, v247, 18
	v_readlane_b32 s16, v247, 19
	v_readlane_b32 s17, v247, 20
	v_readlane_b32 s18, v247, 21
	v_readlane_b32 s19, v247, 22
	s_and_saveexec_b64 s[6:7], s[4:5]
	s_cbranch_execz .LBB0_3515
	v_ashrrev_i32_e32 v1, 4, v35
	s_mov_b64 s[8:9], -1
	s_and_b64 vcc, exec, s[0:1]
	s_cbranch_vccz .LBB0_3511
	v_mul_hi_i32 v2, v1, s53
	v_add_u32_e32 v2, v2, v1
	v_lshrrev_b32_e32 v3, 31, v2
	v_ashrrev_i32_e32 v2, 4, v2
	v_add_u32_e32 v3, v2, v3
	v_mad_i32_i24 v2, v3, s20, v1
	v_add_u32_e32 v3, s61, v3
	v_cmp_lt_i32_e32 vcc, 14, v2
	s_and_saveexec_b64 s[8:9], vcc
	s_xor_b64 s[8:9], exec, s[8:9]
	s_cbranch_execz .LBB0_3508
	v_lshlrev_b32_e32 v3, 3, v3
	v_add3_u32 v2, v2, v3, s67
	v_ashrrev_i32_e32 v3, 31, v2
	v_lshlrev_b64 v[2:3], 12, v[2:3]
	v_lshl_add_u64 v[2:3], v[24:25], 0, v[2:3]
	global_load_dwordx4 v[4:7], v[2:3], off

; __device__ __forceinline__ float delta_prep(const Params& p, int l, int h, bool isP, int grow0, int t0, int nvalid, int bb, char* sm) {
;     ...
; #pragma unroll
;     for (int ib = 0; ib < 4; ++ib) {
;       if (ib * 16 >= nvalid) break;
;       if (ib > 0) {
;         f32x4 a0 = (f32x4){0.f, 0.f, 0.f, 0.f}, a1 = a0;
;         const bfraw* xb0 = (w < 4) ? XTu + ((2 * w) * 16 + r) * 72 : XTw + ((2 * w - 8) * 16 + r) * 72;
;         const bfraw* xb1 = xb0 + 16 * 72;
; #pragma unroll
;         for (int kk = 0; kk < 2; ++kk) {
;           if (kk * 32 < ib * 16) {
;             bf16x8 am = *(const bf16x8*)(Mb + (ib * 16 + r) * 72 + kk * 32 + q * 8);
;             bf16x8 b0 = *(const bf16x8*)(xb0 + kk * 32 + q * 8);
;             bf16x8 b1 = *(const bf16x8*)(xb1 + kk * 32 + q * 8);
;             a0 = mfma16(am, b0, a0);
;             a1 = mfma16(am, b1, a1);
;           }
;         }
; #pragma unroll
;         for (int g = 0; g < 4; ++g) {
;           float* rp = xs + (ib * 16 + q * 4 + g) * 256 + w * 32 + r;
;           rp[0] -= a0[g];
;           rp[16] -= a1[g];
;         }
;         __syncthreads();
;       }
;       if (tid < 256) {
;         float a[16];
; #pragma unroll
;         for (int ii = 0; ii < 16; ++ii) a[ii] = xs[(ib * 16 + ii) * 256 + tid];
; #pragma unroll
;         for (int j = 0; j < 16; ++j) {
;           const float xj = a[j];
;           const float* mp = MT + (ib * 16 + j) * 64 + ib * 16;
; #pragma unroll
;           for (int ii = j + 1; ii < 16; ++ii) a[ii] -= mp[ii] * xj;
;         }
;         bfraw* dst = (tid < 128) ? XTu + tid * 72 + ib * 16 : XTw + (tid - 128) * 72 + ib * 16;
;         *(uint4*)dst = pack8(a);
;         *(uint4*)(dst + 8) = pack8(a + 8);
;       }
;       __syncthreads();
.LBB0_3788:
	s_or_b64 exec, exec, s[0:1]
	v_mul_lo_u32 v0, v64, s87
	v_add_u32_e32 v36, 0, v0
	s_movk_i32 s0, 0x100
	v_add_u32_e32 v15, 0xffffb800, v36
	v_add_u32_e32 v0, 0xf400, v36
	v_cmp_gt_i32_e32 vcc, s56, v64
	v_cmp_gt_i32_e64 s[4:5], s0, v64
	v_lshl_add_u32 v40, v64, 2, s88
	v_cndmask_b32_e32 v31, v15, v0, vcc
	s_waitcnt lgkmcnt(0)
	s_barrier
	s_and_saveexec_b64 s[0:1], s[4:5]
	s_cbranch_execz .LBB0_3790
	ds_read2st64_b32 v[166:167], v40 offset1:4
	ds_read2st64_b32 v[168:169], v40 offset0:8 offset1:12
	ds_read2st64_b32 v[170:171], v40 offset0:16 offset1:20
	ds_read2st64_b32 v[172:173], v40 offset0:24 offset1:28
	ds_read2st64_b32 v[174:175], v40 offset0:32 offset1:36
	ds_read2st64_b32 v[176:177], v40 offset0:40 offset1:44
	ds_read2st64_b32 v[178:179], v40 offset0:48 offset1:52
	ds_read2st64_b32 v[180:181], v40 offset0:56 offset1:60
	v_mov_b32_e32 v165, 0x23c00
	ds_read_b32 v182, v165 offset:4
	ds_read_b64 v[184:185], v165 offset:8
	ds_read_b128 v[186:189], v165 offset:16
	ds_read_b128 v[190:193], v165 offset:32
	ds_read_b128 v[194:197], v165 offset:48
	ds_read_b64 v[198:199], v165 offset:264
	ds_read_b128 v[200:203], v165 offset:272
	ds_read_b128 v[204:207], v165 offset:288
	ds_read_b128 v[208:211], v165 offset:304
	ds_read_b32 v183, v165 offset:524
	ds_read_b128 v[212:215], v165 offset:528
	ds_read_b128 v[216:219], v165 offset:544
	ds_read_b128 v[220:223], v165 offset:560
	s_waitcnt lgkmcnt(13)
	ds_read_b128 v[226:229], v165 offset:784
	ds_read_b128 v[230:233], v165 offset:800
	ds_read_b128 v[234:237], v165 offset:816
	s_waitcnt lgkmcnt(11)
	v_fma_f32 v167, -v166, v182, v167
	v_pk_fma_f32 v[168:169], v[166:167], v[184:185], v[168:169] op_sel_hi:[0,1,1] neg_lo:[1,0,0] neg_hi:[1,0,0]
	v_pk_fma_f32 v[170:171], v[166:167], v[186:187], v[170:171] op_sel_hi:[0,1,1] neg_lo:[1,0,0] neg_hi:[1,0,0]
	v_pk_fma_f32 v[172:173], v[166:167], v[188:189], v[172:173] op_sel_hi:[0,1,1] neg_lo:[1,0,0] neg_hi:[1,0,0]
	v_pk_fma_f32 v[174:175], v[166:167], v[190:191], v[174:175] op_sel_hi:[0,1,1] neg_lo:[1,0,0] neg_hi:[1,0,0]
	v_pk_fma_f32 v[176:177], v[166:167], v[192:193], v[176:177] op_sel_hi:[0,1,1] neg_lo:[1,0,0] neg_hi:[1,0,0]
	v_pk_fma_f32 v[178:179], v[166:167], v[194:195], v[178:179] op_sel_hi:[0,1,1] neg_lo:[1,0,0] neg_hi:[1,0,0]
	v_pk_fma_f32 v[180:181], v[166:167], v[196:197], v[180:181] op_sel_hi:[0,1,1] neg_lo:[1,0,0] neg_hi:[1,0,0]
	ds_read_b32 v182, v165 offset:1044
	ds_read_b64 v[184:185], v165 offset:1048
	ds_read_b128 v[186:189], v165 offset:1056
	ds_read_b128 v[190:193], v165 offset:1072
	s_waitcnt lgkmcnt(11)
	v_pk_fma_f32 v[168:169], v[166:167], v[198:199], v[168:169] op_sel:[1,0,0] op_sel_hi:[1,1,1] neg_lo:[1,0,0] neg_hi:[1,0,0]
	v_pk_fma_f32 v[170:171], v[166:167], v[200:201], v[170:171] op_sel:[1,0,0] op_sel_hi:[1,1,1] neg_lo:[1,0,0] neg_hi:[1,0,0]
	v_pk_fma_f32 v[172:173], v[166:167], v[202:203], v[172:173] op_sel:[1,0,0] op_sel_hi:[1,1,1] neg_lo:[1,0,0] neg_hi:[1,0,0]
	v_pk_fma_f32 v[174:175], v[166:167], v[204:205], v[174:175] op_sel:[1,0,0] op_sel_hi:[1,1,1] neg_lo:[1,0,0] neg_hi:[1,0,0]
	v_pk_fma_f32 v[176:177], v[166:167], v[206:207], v[176:177] op_sel:[1,0,0] op_sel_hi:[1,1,1] neg_lo:[1,0,0] neg_hi:[1,0,0]
	v_pk_fma_f32 v[178:179], v[166:167], v[208:209], v[178:179] op_sel:[1,0,0] op_sel_hi:[1,1,1] neg_lo:[1,0,0] neg_hi:[1,0,0]
	v_pk_fma_f32 v[180:181], v[166:167], v[210:211], v[180:181] op_sel:[1,0,0] op_sel_hi:[1,1,1] neg_lo:[1,0,0] neg_hi:[1,0,0]
	ds_read_b64 v[194:195], v165 offset:1304
	ds_read_b128 v[196:199], v165 offset:1312
	ds_read_b128 v[200:203], v165 offset:1328
	s_waitcnt lgkmcnt(10)
	v_fma_f32 v169, -v168, v183, v169
	v_pk_fma_f32 v[170:171], v[168:169], v[212:213], v[170:171] op_sel_hi:[0,1,1] neg_lo:[1,0,0] neg_hi:[1,0,0]
	v_pk_fma_f32 v[172:173], v[168:169], v[214:215], v[172:173] op_sel_hi:[0,1,1] neg_lo:[1,0,0] neg_hi:[1,0,0]
	v_pk_fma_f32 v[174:175], v[168:169], v[216:217], v[174:175] op_sel_hi:[0,1,1] neg_lo:[1,0,0] neg_hi:[1,0,0]
	v_pk_fma_f32 v[176:177], v[168:169], v[218:219], v[176:177] op_sel_hi:[0,1,1] neg_lo:[1,0,0] neg_hi:[1,0,0]
	v_pk_fma_f32 v[178:179], v[168:169], v[220:221], v[178:179] op_sel_hi:[0,1,1] neg_lo:[1,0,0] neg_hi:[1,0,0]
	v_pk_fma_f32 v[180:181], v[168:169], v[222:223], v[180:181] op_sel_hi:[0,1,1] neg_lo:[1,0,0] neg_hi:[1,0,0]
	ds_read_b32 v183, v165 offset:1564
	ds_read_b128 v[204:207], v165 offset:1568
	ds_read_b128 v[208:211], v165 offset:1584
	s_waitcnt lgkmcnt(10)
	v_pk_fma_f32 v[170:171], v[168:169], v[226:227], v[170:171] op_sel:[1,0,0] op_sel_hi:[1,1,1] neg_lo:[1,0,0] neg_hi:[1,0,0]
	v_pk_fma_f32 v[172:173], v[168:169], v[228:229], v[172:173] op_sel:[1,0,0] op_sel_hi:[1,1,1] neg_lo:[1,0,0] neg_hi:[1,0,0]
	v_pk_fma_f32 v[174:175], v[168:169], v[230:231], v[174:175] op_sel:[1,0,0] op_sel_hi:[1,1,1] neg_lo:[1,0,0] neg_hi:[1,0,0]
	v_pk_fma_f32 v[176:177], v[168:169], v[232:233], v[176:177] op_sel:[1,0,0] op_sel_hi:[1,1,1] neg_lo:[1,0,0] neg_hi:[1,0,0]
	v_pk_fma_f32 v[178:179], v[168:169], v[234:235], v[178:179] op_sel:[1,0,0] op_sel_hi:[1,1,1] neg_lo:[1,0,0] neg_hi:[1,0,0]
	v_pk_fma_f32 v[180:181], v[168:169], v[236:237], v[180:181] op_sel:[1,0,0] op_sel_hi:[1,1,1] neg_lo:[1,0,0] neg_hi:[1,0,0]
	ds_read_b128 v[212:215], v165 offset:1824
	ds_read_b128 v[216:219], v165 offset:1840
	s_waitcnt lgkmcnt(8)
	v_fma_f32 v171, -v170, v182, v171
	v_pk_fma_f32 v[172:173], v[170:171], v[184:185], v[172:173] op_sel_hi:[0,1,1] neg_lo:[1,0,0] neg_hi:[1,0,0]
	v_pk_fma_f32 v[174:175], v[170:171], v[186:187], v[174:175] op_sel_hi:[0,1,1] neg_lo:[1,0,0] neg_hi:[1,0,0]
	v_pk_fma_f32 v[176:177], v[170:171], v[188:189], v[176:177] op_sel_hi:[0,1,1] neg_lo:[1,0,0] neg_hi:[1,0,0]
	v_pk_fma_f32 v[178:179], v[170:171], v[190:191], v[178:179] op_sel_hi:[0,1,1] neg_lo:[1,0,0] neg_hi:[1,0,0]
	v_pk_fma_f32 v[180:181], v[170:171], v[192:193], v[180:181] op_sel_hi:[0,1,1] neg_lo:[1,0,0] neg_hi:[1,0,0]
	ds_read_b32 v182, v165 offset:2084
	ds_read_b64 v[184:185], v165 offset:2088
	ds_read_b128 v[186:189], v165 offset:2096
	s_waitcnt lgkmcnt(8)
; __device__ __forceinline__ float delta_prep(const Params& p, int l, int h, bool isP, int grow0, int t0, int nvalid, int bb, char* sm) {
;     ...
;       if (ib > 0) {
;         f32x4 a0 = (f32x4){0.f, 0.f, 0.f, 0.f}, a1 = a0;
;         const bfraw* xb0 = (w < 4) ? XTu + ((2 * w) * 16 + r) * 72 : XTw + ((2 * w - 8) * 16 + r) * 72;
;         const bfraw* xb1 = xb0 + 16 * 72;
; #pragma unroll
;         for (int kk = 0; kk < 2; ++kk) {
;           if (kk * 32 < ib * 16) {
;             bf16x8 am = *(const bf16x8*)(Mb + (ib * 16 + r) * 72 + kk * 32 + q * 8);
;             bf16x8 b0 = *(const bf16x8*)(xb0 + kk * 32 + q * 8);
;             bf16x8 b1 = *(const bf16x8*)(xb1 + kk * 32 + q * 8);
;             a0 = mfma16(am, b0, a0);
;             a1 = mfma16(am, b1, a1);
;           }
;         }
; #pragma unroll
;         for (int g = 0; g < 4; ++g) {
;           float* rp = xs + (ib * 16 + q * 4 + g) * 256 + w * 32 + r;
;           rp[0] -= a0[g];
;           rp[16] -= a1[g];
;         }
;         __syncthreads();
;       }
;       if (tid < 256) {
;         float a[16];
; #pragma unroll
;         for (int ii = 0; ii < 16; ++ii) a[ii] = xs[(ib * 16 + ii) * 256 + tid];
; #pragma unroll
;         for (int j = 0; j < 16; ++j) {
;           const float xj = a[j];
;           const float* mp = MT + (ib * 16 + j) * 64 + ib * 16;
; #pragma unroll
;           for (int ii = j + 1; ii < 16; ++ii) a[ii] -= mp[ii] * xj;
;         }
;         bfraw* dst = (tid < 128) ? XTu + tid * 72 + ib * 16 : XTw + (tid - 128) * 72 + ib * 16;
;         *(uint4*)dst = pack8(a);
;         *(uint4*)(dst + 8) = pack8(a + 8);
;       }
;       __syncthreads();
	v_pk_fma_f32 v[172:173], v[170:171], v[194:195], v[172:173] op_sel:[1,0,0] op_sel_hi:[1,1,1] neg_lo:[1,0,0] neg_hi:[1,0,0]
	v_pk_fma_f32 v[174:175], v[170:171], v[196:197], v[174:175] op_sel:[1,0,0] op_sel_hi:[1,1,1] neg_lo:[1,0,0] neg_hi:[1,0,0]
	v_pk_fma_f32 v[176:177], v[170:171], v[198:199], v[176:177] op_sel:[1,0,0] op_sel_hi:[1,1,1] neg_lo:[1,0,0] neg_hi:[1,0,0]
	v_pk_fma_f32 v[178:179], v[170:171], v[200:201], v[178:179] op_sel:[1,0,0] op_sel_hi:[1,1,1] neg_lo:[1,0,0] neg_hi:[1,0,0]
	v_pk_fma_f32 v[180:181], v[170:171], v[202:203], v[180:181] op_sel:[1,0,0] op_sel_hi:[1,1,1] neg_lo:[1,0,0] neg_hi:[1,0,0]
	ds_read_b64 v[190:191], v165 offset:2344
	ds_read_b128 v[192:195], v165 offset:2352
	s_waitcnt lgkmcnt(7)
	v_fma_f32 v173, -v172, v183, v173
	v_pk_fma_f32 v[174:175], v[172:173], v[204:205], v[174:175] op_sel_hi:[0,1,1] neg_lo:[1,0,0] neg_hi:[1,0,0]
	v_pk_fma_f32 v[176:177], v[172:173], v[206:207], v[176:177] op_sel_hi:[0,1,1] neg_lo:[1,0,0] neg_hi:[1,0,0]
	v_pk_fma_f32 v[178:179], v[172:173], v[208:209], v[178:179] op_sel_hi:[0,1,1] neg_lo:[1,0,0] neg_hi:[1,0,0]
	v_pk_fma_f32 v[180:181], v[172:173], v[210:211], v[180:181] op_sel_hi:[0,1,1] neg_lo:[1,0,0] neg_hi:[1,0,0]
	ds_read_b32 v183, v165 offset:2604
	ds_read_b128 v[196:199], v165 offset:2608
	s_waitcnt lgkmcnt(7)
	v_pk_fma_f32 v[174:175], v[172:173], v[212:213], v[174:175] op_sel:[1,0,0] op_sel_hi:[1,1,1] neg_lo:[1,0,0] neg_hi:[1,0,0]
	v_pk_fma_f32 v[176:177], v[172:173], v[214:215], v[176:177] op_sel:[1,0,0] op_sel_hi:[1,1,1] neg_lo:[1,0,0] neg_hi:[1,0,0]
	v_pk_fma_f32 v[178:179], v[172:173], v[216:217], v[178:179] op_sel:[1,0,0] op_sel_hi:[1,1,1] neg_lo:[1,0,0] neg_hi:[1,0,0]
	v_pk_fma_f32 v[180:181], v[172:173], v[218:219], v[180:181] op_sel:[1,0,0] op_sel_hi:[1,1,1] neg_lo:[1,0,0] neg_hi:[1,0,0]
	ds_read_b128 v[200:203], v165 offset:2864
	s_waitcnt lgkmcnt(5)
	v_fma_f32 v175, -v174, v182, v175
	v_pk_fma_f32 v[176:177], v[174:175], v[184:185], v[176:177] op_sel_hi:[0,1,1] neg_lo:[1,0,0] neg_hi:[1,0,0]
	v_pk_fma_f32 v[178:179], v[174:175], v[186:187], v[178:179] op_sel_hi:[0,1,1] neg_lo:[1,0,0] neg_hi:[1,0,0]
	v_pk_fma_f32 v[180:181], v[174:175], v[188:189], v[180:181] op_sel_hi:[0,1,1] neg_lo:[1,0,0] neg_hi:[1,0,0]
	ds_read_b32 v182, v165 offset:3124
	ds_read_b64 v[184:185], v165 offset:3128
	s_waitcnt lgkmcnt(5)
	v_pk_fma_f32 v[176:177], v[174:175], v[190:191], v[176:177] op_sel:[1,0,0] op_sel_hi:[1,1,1] neg_lo:[1,0,0] neg_hi:[1,0,0]
	v_pk_fma_f32 v[178:179], v[174:175], v[192:193], v[178:179] op_sel:[1,0,0] op_sel_hi:[1,1,1] neg_lo:[1,0,0] neg_hi:[1,0,0]
	v_pk_fma_f32 v[180:181], v[174:175], v[194:195], v[180:181] op_sel:[1,0,0] op_sel_hi:[1,1,1] neg_lo:[1,0,0] neg_hi:[1,0,0]
	ds_read_b64 v[186:187], v165 offset:3384
	s_waitcnt lgkmcnt(4)
	v_fma_f32 v177, -v176, v183, v177
	v_pk_fma_f32 v[178:179], v[176:177], v[196:197], v[178:179] op_sel_hi:[0,1,1] neg_lo:[1,0,0] neg_hi:[1,0,0]
	v_pk_fma_f32 v[180:181], v[176:177], v[198:199], v[180:181] op_sel_hi:[0,1,1] neg_lo:[1,0,0] neg_hi:[1,0,0]
	ds_read_b32 v183, v165 offset:3644
	s_waitcnt lgkmcnt(4)
	v_pk_fma_f32 v[178:179], v[176:177], v[200:201], v[178:179] op_sel:[1,0,0] op_sel_hi:[1,1,1] neg_lo:[1,0,0] neg_hi:[1,0,0]
	v_pk_fma_f32 v[180:181], v[176:177], v[202:203], v[180:181] op_sel:[1,0,0] op_sel_hi:[1,1,1] neg_lo:[1,0,0] neg_hi:[1,0,0]
	s_waitcnt lgkmcnt(2)
	v_fma_f32 v179, -v178, v182, v179
	v_pk_fma_f32 v[180:181], v[178:179], v[184:185], v[180:181] op_sel_hi:[0,1,1] neg_lo:[1,0,0] neg_hi:[1,0,0]
	s_waitcnt lgkmcnt(1)
	v_pk_fma_f32 v[180:181], v[178:179], v[186:187], v[180:181] op_sel:[1,0,0] op_sel_hi:[1,1,1] neg_lo:[1,0,0] neg_hi:[1,0,0]
	s_waitcnt lgkmcnt(0)
	v_fma_f32 v181, -v180, v183, v181
	v_cvt_pk_bf16_f32 v182, v166, v167
	v_cvt_pk_bf16_f32 v183, v168, v169
	v_cvt_pk_bf16_f32 v184, v170, v171
	v_cvt_pk_bf16_f32 v185, v172, v173
	ds_write_b128 v31, v[182:185]
	v_cvt_pk_bf16_f32 v186, v174, v175
	v_cvt_pk_bf16_f32 v187, v176, v177
	v_cvt_pk_bf16_f32 v188, v178, v179
	v_cvt_pk_bf16_f32 v189, v180, v181
	ds_write_b128 v31, v[186:189] offset:16
	v_readlane_b32 s6, v246, 24
.LBB0_3790:
	s_or_b64 exec, exec, s[0:1]
	s_andn2_b64 vcc, exec, s[16:17]
	s_waitcnt lgkmcnt(0)
	s_barrier
	s_cbranch_vccnz .LBB0_3798
	v_lshl_or_b32 v1, v38, 5, v39
	v_lshlrev_b32_e32 v0, 2, v39
	v_mul_lo_u32 v1, v1, s87
	v_lshlrev_b32_e32 v2, 7, v38
	v_add_u32_e32 v1, 0, v1
	v_add3_u32 v8, s88, v0, v2
	v_cndmask_b32_e64 v0, v159, v160, s[2:3]
	v_lshlrev_b32_e32 v2, 1, v41
	v_add3_u32 v38, v1, v0, v2
	v_mad_u32_u24 v0, v42, s87, v19
	ds_read_b128 v[0:3], v0 offset:34816
	ds_read_b128 v[4:7], v38
	ds_read_b128 v[20:23], v38 offset:2304
	v_lshlrev_b32_e32 v9, 12, v27
	v_add_u32_e32 v25, v8, v9
	v_add_u32_e32 v10, 0x4000, v25
	ds_read2_b32 v[8:9], v10 offset1:16
	s_waitcnt lgkmcnt(2)
	v_mfma_f32_16x16x32_bf16 v[4:7], v[0:3], v[4:7], 0
	s_waitcnt lgkmcnt(1)
	v_mfma_f32_16x16x32_bf16 v[0:3], v[0:3], v[20:23], 0
	s_waitcnt lgkmcnt(0)
	s_nop 4
	v_sub_f32_e32 v4, v8, v4
	s_nop 0
	v_sub_f32_e32 v0, v9, v0
	ds_write2_b32 v10, v4, v0 offset1:16
	v_add_u32_e32 v0, 0x4400, v25
	ds_read2_b32 v[8:9], v0 offset1:16
	s_waitcnt lgkmcnt(0)
	v_sub_f32_e32 v4, v8, v5
	v_sub_f32_e32 v1, v9, v1
	ds_write2_b32 v0, v4, v1 offset1:16
	v_add_u32_e32 v4, 0x4800, v25
	ds_read2_b32 v[0:1], v4 offset1:16
	s_waitcnt lgkmcnt(0)
	v_sub_f32_e32 v0, v0, v6
	v_sub_f32_e32 v1, v1, v2
	v_add_u32_e32 v2, 0x4c00, v25
	ds_write2_b32 v4, v0, v1 offset1:16
	ds_read2_b32 v[0:1], v2 offset1:16
	s_waitcnt lgkmcnt(0)
	v_sub_f32_e32 v0, v0, v7
	v_sub_f32_e32 v1, v1, v3
	ds_write2_b32 v2, v0, v1 offset1:16
	s_waitcnt lgkmcnt(0)
	s_barrier
	s_and_saveexec_b64 s[0:1], s[4:5]
	s_cbranch_execz .LBB0_3793
; __device__ __forceinline__ float delta_prep(const Params& p, int l, int h, bool isP, int grow0, int t0, int nvalid, int bb, char* sm) {
;     ...
;       if (tid < 256) {
;         float a[16];
; #pragma unroll
;         for (int ii = 0; ii < 16; ++ii) a[ii] = xs[(ib * 16 + ii) * 256 + tid];
; #pragma unroll
;         for (int j = 0; j < 16; ++j) {
;           const float xj = a[j];
;           const float* mp = MT + (ib * 16 + j) * 64 + ib * 16;
; #pragma unroll
;           for (int ii = j + 1; ii < 16; ++ii) a[ii] -= mp[ii] * xj;
;         }
;         bfraw* dst = (tid < 128) ? XTu + tid * 72 + ib * 16 : XTw + (tid - 128) * 72 + ib * 16;
;         *(uint4*)dst = pack8(a);
;         *(uint4*)(dst + 8) = pack8(a + 8);
;       }
	ds_read2st64_b32 v[166:167], v40 offset0:64 offset1:68
	ds_read2st64_b32 v[168:169], v40 offset0:72 offset1:76
	ds_read2st64_b32 v[170:171], v40 offset0:80 offset1:84
	ds_read2st64_b32 v[172:173], v40 offset0:88 offset1:92
	ds_read2st64_b32 v[174:175], v40 offset0:96 offset1:100
	ds_read2st64_b32 v[176:177], v40 offset0:104 offset1:108
	ds_read2st64_b32 v[178:179], v40 offset0:112 offset1:116
	ds_read2st64_b32 v[180:181], v40 offset0:120 offset1:124
	v_mov_b32_e32 v165, 0x23c00
	ds_read_b32 v182, v165 offset:4164
	ds_read_b64 v[184:185], v165 offset:4168
	ds_read_b128 v[186:189], v165 offset:4176
	ds_read_b128 v[190:193], v165 offset:4192
	ds_read_b128 v[194:197], v165 offset:4208
	ds_read_b64 v[198:199], v165 offset:4424
	ds_read_b128 v[200:203], v165 offset:4432
	ds_read_b128 v[204:207], v165 offset:4448
	ds_read_b128 v[208:211], v165 offset:4464
	ds_read_b32 v183, v165 offset:4684
	ds_read_b128 v[212:215], v165 offset:4688
	ds_read_b128 v[216:219], v165 offset:4704
	ds_read_b128 v[220:223], v165 offset:4720
	s_waitcnt lgkmcnt(13)
	ds_read_b128 v[226:229], v165 offset:4944
	ds_read_b128 v[230:233], v165 offset:4960
	ds_read_b128 v[234:237], v165 offset:4976
	s_waitcnt lgkmcnt(11)
	v_fma_f32 v167, -v166, v182, v167
	v_pk_fma_f32 v[168:169], v[166:167], v[184:185], v[168:169] op_sel_hi:[0,1,1] neg_lo:[1,0,0] neg_hi:[1,0,0]
	v_pk_fma_f32 v[170:171], v[166:167], v[186:187], v[170:171] op_sel_hi:[0,1,1] neg_lo:[1,0,0] neg_hi:[1,0,0]
	v_pk_fma_f32 v[172:173], v[166:167], v[188:189], v[172:173] op_sel_hi:[0,1,1] neg_lo:[1,0,0] neg_hi:[1,0,0]
	v_pk_fma_f32 v[174:175], v[166:167], v[190:191], v[174:175] op_sel_hi:[0,1,1] neg_lo:[1,0,0] neg_hi:[1,0,0]
	v_pk_fma_f32 v[176:177], v[166:167], v[192:193], v[176:177] op_sel_hi:[0,1,1] neg_lo:[1,0,0] neg_hi:[1,0,0]
	v_pk_fma_f32 v[178:179], v[166:167], v[194:195], v[178:179] op_sel_hi:[0,1,1] neg_lo:[1,0,0] neg_hi:[1,0,0]
	v_pk_fma_f32 v[180:181], v[166:167], v[196:197], v[180:181] op_sel_hi:[0,1,1] neg_lo:[1,0,0] neg_hi:[1,0,0]
	ds_read_b32 v182, v165 offset:5204
	ds_read_b64 v[184:185], v165 offset:5208
	ds_read_b128 v[186:189], v165 offset:5216
	ds_read_b128 v[190:193], v165 offset:5232
	s_waitcnt lgkmcnt(11)
	v_pk_fma_f32 v[168:169], v[166:167], v[198:199], v[168:169] op_sel:[1,0,0] op_sel_hi:[1,1,1] neg_lo:[1,0,0] neg_hi:[1,0,0]
	v_pk_fma_f32 v[170:171], v[166:167], v[200:201], v[170:171] op_sel:[1,0,0] op_sel_hi:[1,1,1] neg_lo:[1,0,0] neg_hi:[1,0,0]
	v_pk_fma_f32 v[172:173], v[166:167], v[202:203], v[172:173] op_sel:[1,0,0] op_sel_hi:[1,1,1] neg_lo:[1,0,0] neg_hi:[1,0,0]
	v_pk_fma_f32 v[174:175], v[166:167], v[204:205], v[174:175] op_sel:[1,0,0] op_sel_hi:[1,1,1] neg_lo:[1,0,0] neg_hi:[1,0,0]
	v_pk_fma_f32 v[176:177], v[166:167], v[206:207], v[176:177] op_sel:[1,0,0] op_sel_hi:[1,1,1] neg_lo:[1,0,0] neg_hi:[1,0,0]
	v_pk_fma_f32 v[178:179], v[166:167], v[208:209], v[178:179] op_sel:[1,0,0] op_sel_hi:[1,1,1] neg_lo:[1,0,0] neg_hi:[1,0,0]
	v_pk_fma_f32 v[180:181], v[166:167], v[210:211], v[180:181] op_sel:[1,0,0] op_sel_hi:[1,1,1] neg_lo:[1,0,0] neg_hi:[1,0,0]
	ds_read_b64 v[194:195], v165 offset:5464
	ds_read_b128 v[196:199], v165 offset:5472
	ds_read_b128 v[200:203], v165 offset:5488
	s_waitcnt lgkmcnt(10)
	v_fma_f32 v169, -v168, v183, v169
	v_pk_fma_f32 v[170:171], v[168:169], v[212:213], v[170:171] op_sel_hi:[0,1,1] neg_lo:[1,0,0] neg_hi:[1,0,0]
	v_pk_fma_f32 v[172:173], v[168:169], v[214:215], v[172:173] op_sel_hi:[0,1,1] neg_lo:[1,0,0] neg_hi:[1,0,0]
	v_pk_fma_f32 v[174:175], v[168:169], v[216:217], v[174:175] op_sel_hi:[0,1,1] neg_lo:[1,0,0] neg_hi:[1,0,0]
	v_pk_fma_f32 v[176:177], v[168:169], v[218:219], v[176:177] op_sel_hi:[0,1,1] neg_lo:[1,0,0] neg_hi:[1,0,0]
	v_pk_fma_f32 v[178:179], v[168:169], v[220:221], v[178:179] op_sel_hi:[0,1,1] neg_lo:[1,0,0] neg_hi:[1,0,0]
	v_pk_fma_f32 v[180:181], v[168:169], v[222:223], v[180:181] op_sel_hi:[0,1,1] neg_lo:[1,0,0] neg_hi:[1,0,0]
	ds_read_b32 v183, v165 offset:5724
	ds_read_b128 v[204:207], v165 offset:5728
	ds_read_b128 v[208:211], v165 offset:5744
	s_waitcnt lgkmcnt(10)
	v_pk_fma_f32 v[170:171], v[168:169], v[226:227], v[170:171] op_sel:[1,0,0] op_sel_hi:[1,1,1] neg_lo:[1,0,0] neg_hi:[1,0,0]
	v_pk_fma_f32 v[172:173], v[168:169], v[228:229], v[172:173] op_sel:[1,0,0] op_sel_hi:[1,1,1] neg_lo:[1,0,0] neg_hi:[1,0,0]
	v_pk_fma_f32 v[174:175], v[168:169], v[230:231], v[174:175] op_sel:[1,0,0] op_sel_hi:[1,1,1] neg_lo:[1,0,0] neg_hi:[1,0,0]
	v_pk_fma_f32 v[176:177], v[168:169], v[232:233], v[176:177] op_sel:[1,0,0] op_sel_hi:[1,1,1] neg_lo:[1,0,0] neg_hi:[1,0,0]
	v_pk_fma_f32 v[178:179], v[168:169], v[234:235], v[178:179] op_sel:[1,0,0] op_sel_hi:[1,1,1] neg_lo:[1,0,0] neg_hi:[1,0,0]
	v_pk_fma_f32 v[180:181], v[168:169], v[236:237], v[180:181] op_sel:[1,0,0] op_sel_hi:[1,1,1] neg_lo:[1,0,0] neg_hi:[1,0,0]
	ds_read_b128 v[212:215], v165 offset:5984
	ds_read_b128 v[216:219], v165 offset:6000
	s_waitcnt lgkmcnt(8)
	v_fma_f32 v171, -v170, v182, v171
	v_pk_fma_f32 v[172:173], v[170:171], v[184:185], v[172:173] op_sel_hi:[0,1,1] neg_lo:[1,0,0] neg_hi:[1,0,0]
	v_pk_fma_f32 v[174:175], v[170:171], v[186:187], v[174:175] op_sel_hi:[0,1,1] neg_lo:[1,0,0] neg_hi:[1,0,0]
	v_pk_fma_f32 v[176:177], v[170:171], v[188:189], v[176:177] op_sel_hi:[0,1,1] neg_lo:[1,0,0] neg_hi:[1,0,0]
	v_pk_fma_f32 v[178:179], v[170:171], v[190:191], v[178:179] op_sel_hi:[0,1,1] neg_lo:[1,0,0] neg_hi:[1,0,0]
	v_pk_fma_f32 v[180:181], v[170:171], v[192:193], v[180:181] op_sel_hi:[0,1,1] neg_lo:[1,0,0] neg_hi:[1,0,0]
	ds_read_b32 v182, v165 offset:6244
	ds_read_b64 v[184:185], v165 offset:6248
	ds_read_b128 v[186:189], v165 offset:6256
	s_waitcnt lgkmcnt(8)
; __device__ __forceinline__ float delta_prep(const Params& p, int l, int h, bool isP, int grow0, int t0, int nvalid, int bb, char* sm) {
;     ...
;       if (ib > 0) {
;         f32x4 a0 = (f32x4){0.f, 0.f, 0.f, 0.f}, a1 = a0;
;         const bfraw* xb0 = (w < 4) ? XTu + ((2 * w) * 16 + r) * 72 : XTw + ((2 * w - 8) * 16 + r) * 72;
;         const bfraw* xb1 = xb0 + 16 * 72;
; #pragma unroll
;         for (int kk = 0; kk < 2; ++kk) {
;           if (kk * 32 < ib * 16) {
;             bf16x8 am = *(const bf16x8*)(Mb + (ib * 16 + r) * 72 + kk * 32 + q * 8);
;             bf16x8 b0 = *(const bf16x8*)(xb0 + kk * 32 + q * 8);
;             bf16x8 b1 = *(const bf16x8*)(xb1 + kk * 32 + q * 8);
;             a0 = mfma16(am, b0, a0);
;             a1 = mfma16(am, b1, a1);
;           }
;         }
; #pragma unroll
;         for (int g = 0; g < 4; ++g) {
;           float* rp = xs + (ib * 16 + q * 4 + g) * 256 + w * 32 + r;
;           rp[0] -= a0[g];
;           rp[16] -= a1[g];
;         }
;         __syncthreads();
;     ...
;       if (tid < 256) {
;         float a[16];
; #pragma unroll
;         for (int ii = 0; ii < 16; ++ii) a[ii] = xs[(ib * 16 + ii) * 256 + tid];
; #pragma unroll
;         for (int j = 0; j < 16; ++j) {
;           const float xj = a[j];
;           const float* mp = MT + (ib * 16 + j) * 64 + ib * 16;
; #pragma unroll
;           for (int ii = j + 1; ii < 16; ++ii) a[ii] -= mp[ii] * xj;
;         }
;         bfraw* dst = (tid < 128) ? XTu + tid * 72 + ib * 16 : XTw + (tid - 128) * 72 + ib * 16;
;         *(uint4*)dst = pack8(a);
;         *(uint4*)(dst + 8) = pack8(a + 8);
;       }
	v_pk_fma_f32 v[172:173], v[170:171], v[194:195], v[172:173] op_sel:[1,0,0] op_sel_hi:[1,1,1] neg_lo:[1,0,0] neg_hi:[1,0,0]
	v_pk_fma_f32 v[174:175], v[170:171], v[196:197], v[174:175] op_sel:[1,0,0] op_sel_hi:[1,1,1] neg_lo:[1,0,0] neg_hi:[1,0,0]
	v_pk_fma_f32 v[176:177], v[170:171], v[198:199], v[176:177] op_sel:[1,0,0] op_sel_hi:[1,1,1] neg_lo:[1,0,0] neg_hi:[1,0,0]
	v_pk_fma_f32 v[178:179], v[170:171], v[200:201], v[178:179] op_sel:[1,0,0] op_sel_hi:[1,1,1] neg_lo:[1,0,0] neg_hi:[1,0,0]
	v_pk_fma_f32 v[180:181], v[170:171], v[202:203], v[180:181] op_sel:[1,0,0] op_sel_hi:[1,1,1] neg_lo:[1,0,0] neg_hi:[1,0,0]
	ds_read_b64 v[190:191], v165 offset:6504
	ds_read_b128 v[192:195], v165 offset:6512
	s_waitcnt lgkmcnt(7)
	v_fma_f32 v173, -v172, v183, v173
	v_pk_fma_f32 v[174:175], v[172:173], v[204:205], v[174:175] op_sel_hi:[0,1,1] neg_lo:[1,0,0] neg_hi:[1,0,0]
	v_pk_fma_f32 v[176:177], v[172:173], v[206:207], v[176:177] op_sel_hi:[0,1,1] neg_lo:[1,0,0] neg_hi:[1,0,0]
	v_pk_fma_f32 v[178:179], v[172:173], v[208:209], v[178:179] op_sel_hi:[0,1,1] neg_lo:[1,0,0] neg_hi:[1,0,0]
	v_pk_fma_f32 v[180:181], v[172:173], v[210:211], v[180:181] op_sel_hi:[0,1,1] neg_lo:[1,0,0] neg_hi:[1,0,0]
	ds_read_b32 v183, v165 offset:6764
	ds_read_b128 v[196:199], v165 offset:6768
	s_waitcnt lgkmcnt(7)
	v_pk_fma_f32 v[174:175], v[172:173], v[212:213], v[174:175] op_sel:[1,0,0] op_sel_hi:[1,1,1] neg_lo:[1,0,0] neg_hi:[1,0,0]
	v_pk_fma_f32 v[176:177], v[172:173], v[214:215], v[176:177] op_sel:[1,0,0] op_sel_hi:[1,1,1] neg_lo:[1,0,0] neg_hi:[1,0,0]
	v_pk_fma_f32 v[178:179], v[172:173], v[216:217], v[178:179] op_sel:[1,0,0] op_sel_hi:[1,1,1] neg_lo:[1,0,0] neg_hi:[1,0,0]
	v_pk_fma_f32 v[180:181], v[172:173], v[218:219], v[180:181] op_sel:[1,0,0] op_sel_hi:[1,1,1] neg_lo:[1,0,0] neg_hi:[1,0,0]
	ds_read_b128 v[200:203], v165 offset:7024
	s_waitcnt lgkmcnt(5)
	v_fma_f32 v175, -v174, v182, v175
	v_pk_fma_f32 v[176:177], v[174:175], v[184:185], v[176:177] op_sel_hi:[0,1,1] neg_lo:[1,0,0] neg_hi:[1,0,0]
	v_pk_fma_f32 v[178:179], v[174:175], v[186:187], v[178:179] op_sel_hi:[0,1,1] neg_lo:[1,0,0] neg_hi:[1,0,0]
	v_pk_fma_f32 v[180:181], v[174:175], v[188:189], v[180:181] op_sel_hi:[0,1,1] neg_lo:[1,0,0] neg_hi:[1,0,0]
	ds_read_b32 v182, v165 offset:7284
	ds_read_b64 v[184:185], v165 offset:7288
	s_waitcnt lgkmcnt(5)
	v_pk_fma_f32 v[176:177], v[174:175], v[190:191], v[176:177] op_sel:[1,0,0] op_sel_hi:[1,1,1] neg_lo:[1,0,0] neg_hi:[1,0,0]
	v_pk_fma_f32 v[178:179], v[174:175], v[192:193], v[178:179] op_sel:[1,0,0] op_sel_hi:[1,1,1] neg_lo:[1,0,0] neg_hi:[1,0,0]
	v_pk_fma_f32 v[180:181], v[174:175], v[194:195], v[180:181] op_sel:[1,0,0] op_sel_hi:[1,1,1] neg_lo:[1,0,0] neg_hi:[1,0,0]
	ds_read_b64 v[186:187], v165 offset:7544
	s_waitcnt lgkmcnt(4)
	v_fma_f32 v177, -v176, v183, v177
	v_pk_fma_f32 v[178:179], v[176:177], v[196:197], v[178:179] op_sel_hi:[0,1,1] neg_lo:[1,0,0] neg_hi:[1,0,0]
	v_pk_fma_f32 v[180:181], v[176:177], v[198:199], v[180:181] op_sel_hi:[0,1,1] neg_lo:[1,0,0] neg_hi:[1,0,0]
	ds_read_b32 v183, v165 offset:7804
	s_waitcnt lgkmcnt(4)
	v_pk_fma_f32 v[178:179], v[176:177], v[200:201], v[178:179] op_sel:[1,0,0] op_sel_hi:[1,1,1] neg_lo:[1,0,0] neg_hi:[1,0,0]
	v_pk_fma_f32 v[180:181], v[176:177], v[202:203], v[180:181] op_sel:[1,0,0] op_sel_hi:[1,1,1] neg_lo:[1,0,0] neg_hi:[1,0,0]
	s_waitcnt lgkmcnt(2)
	v_fma_f32 v179, -v178, v182, v179
	v_pk_fma_f32 v[180:181], v[178:179], v[184:185], v[180:181] op_sel_hi:[0,1,1] neg_lo:[1,0,0] neg_hi:[1,0,0]
	s_waitcnt lgkmcnt(1)
	v_pk_fma_f32 v[180:181], v[178:179], v[186:187], v[180:181] op_sel:[1,0,0] op_sel_hi:[1,1,1] neg_lo:[1,0,0] neg_hi:[1,0,0]
	s_waitcnt lgkmcnt(0)
	v_fma_f32 v181, -v180, v183, v181
	v_cvt_pk_bf16_f32 v182, v166, v167
	v_cvt_pk_bf16_f32 v183, v168, v169
	v_cvt_pk_bf16_f32 v184, v170, v171
	v_cvt_pk_bf16_f32 v185, v172, v173
	ds_write_b128 v31, v[182:185] offset:32
	v_cvt_pk_bf16_f32 v186, v174, v175
	v_cvt_pk_bf16_f32 v187, v176, v177
	v_cvt_pk_bf16_f32 v188, v178, v179
	v_cvt_pk_bf16_f32 v189, v180, v181
	ds_write_b128 v31, v[186:189] offset:48
	v_readlane_b32 s2, v245, 1
.LBB0_3793:
	s_or_b64 exec, exec, s[0:1]
	v_mad_u32_u24 v0, v37, s87, v19
	s_waitcnt lgkmcnt(0)
	s_barrier
	ds_read_b128 v[0:3], v0 offset:34816
	ds_read_b128 v[4:7], v38
	ds_read_b128 v[20:23], v38 offset:2304
	v_add_u32_e32 v10, 0x8000, v25
	ds_read2_b32 v[8:9], v10 offset1:16
	s_waitcnt lgkmcnt(2)
	v_mfma_f32_16x16x32_bf16 v[4:7], v[0:3], v[4:7], 0
	s_waitcnt lgkmcnt(1)
	v_mfma_f32_16x16x32_bf16 v[0:3], v[0:3], v[20:23], 0
	s_waitcnt lgkmcnt(0)
	s_nop 4
	v_sub_f32_e32 v4, v8, v4
	s_nop 0
	v_sub_f32_e32 v0, v9, v0
	ds_write2_b32 v10, v4, v0 offset1:16
	v_add_u32_e32 v0, 0x8400, v25
	ds_read2_b32 v[8:9], v0 offset1:16
	s_waitcnt lgkmcnt(0)
	v_sub_f32_e32 v4, v8, v5
	v_sub_f32_e32 v1, v9, v1
	ds_write2_b32 v0, v4, v1 offset1:16
	v_add_u32_e32 v4, 0x8800, v25
	ds_read2_b32 v[0:1], v4 offset1:16
	s_waitcnt lgkmcnt(0)
	v_sub_f32_e32 v0, v0, v6
	v_sub_f32_e32 v1, v1, v2
	v_add_u32_e32 v2, 0x8c00, v25
	ds_write2_b32 v4, v0, v1 offset1:16
	ds_read2_b32 v[0:1], v2 offset1:16
	s_waitcnt lgkmcnt(0)
	v_sub_f32_e32 v0, v0, v7
	v_sub_f32_e32 v1, v1, v3
	ds_write2_b32 v2, v0, v1 offset1:16
	s_waitcnt lgkmcnt(0)
	s_barrier
	s_and_saveexec_b64 s[0:1], s[4:5]
	s_cbranch_execz .LBB0_3795
; __device__ __forceinline__ float delta_prep(const Params& p, int l, int h, bool isP, int grow0, int t0, int nvalid, int bb, char* sm) {
;     ...
;       if (tid < 256) {
;         float a[16];
; #pragma unroll
;         for (int ii = 0; ii < 16; ++ii) a[ii] = xs[(ib * 16 + ii) * 256 + tid];
; #pragma unroll
;         for (int j = 0; j < 16; ++j) {
;           const float xj = a[j];
;           const float* mp = MT + (ib * 16 + j) * 64 + ib * 16;
; #pragma unroll
;           for (int ii = j + 1; ii < 16; ++ii) a[ii] -= mp[ii] * xj;
;         }
;         bfraw* dst = (tid < 128) ? XTu + tid * 72 + ib * 16 : XTw + (tid - 128) * 72 + ib * 16;
;         *(uint4*)dst = pack8(a);
;         *(uint4*)(dst + 8) = pack8(a + 8);
;       }
	ds_read2st64_b32 v[166:167], v40 offset0:128 offset1:132
	ds_read2st64_b32 v[168:169], v40 offset0:136 offset1:140
	ds_read2st64_b32 v[170:171], v40 offset0:144 offset1:148
	ds_read2st64_b32 v[172:173], v40 offset0:152 offset1:156
	ds_read2st64_b32 v[174:175], v40 offset0:160 offset1:164
	ds_read2st64_b32 v[176:177], v40 offset0:168 offset1:172
	ds_read2st64_b32 v[178:179], v40 offset0:176 offset1:180
	ds_read2st64_b32 v[180:181], v40 offset0:184 offset1:188
	v_mov_b32_e32 v165, 0x23c00
	ds_read_b32 v182, v165 offset:8324
	ds_read_b64 v[184:185], v165 offset:8328
	ds_read_b128 v[186:189], v165 offset:8336
	ds_read_b128 v[190:193], v165 offset:8352
	ds_read_b128 v[194:197], v165 offset:8368
	ds_read_b64 v[198:199], v165 offset:8584
	ds_read_b128 v[200:203], v165 offset:8592
	ds_read_b128 v[204:207], v165 offset:8608
	ds_read_b128 v[208:211], v165 offset:8624
	ds_read_b32 v183, v165 offset:8844
	ds_read_b128 v[212:215], v165 offset:8848
	ds_read_b128 v[216:219], v165 offset:8864
	ds_read_b128 v[220:223], v165 offset:8880
	s_waitcnt lgkmcnt(13)
	ds_read_b128 v[226:229], v165 offset:9104
	ds_read_b128 v[230:233], v165 offset:9120
	ds_read_b128 v[234:237], v165 offset:9136
	s_waitcnt lgkmcnt(11)
	v_fma_f32 v167, -v166, v182, v167
	v_pk_fma_f32 v[168:169], v[166:167], v[184:185], v[168:169] op_sel_hi:[0,1,1] neg_lo:[1,0,0] neg_hi:[1,0,0]
	v_pk_fma_f32 v[170:171], v[166:167], v[186:187], v[170:171] op_sel_hi:[0,1,1] neg_lo:[1,0,0] neg_hi:[1,0,0]
	v_pk_fma_f32 v[172:173], v[166:167], v[188:189], v[172:173] op_sel_hi:[0,1,1] neg_lo:[1,0,0] neg_hi:[1,0,0]
	v_pk_fma_f32 v[174:175], v[166:167], v[190:191], v[174:175] op_sel_hi:[0,1,1] neg_lo:[1,0,0] neg_hi:[1,0,0]
	v_pk_fma_f32 v[176:177], v[166:167], v[192:193], v[176:177] op_sel_hi:[0,1,1] neg_lo:[1,0,0] neg_hi:[1,0,0]
	v_pk_fma_f32 v[178:179], v[166:167], v[194:195], v[178:179] op_sel_hi:[0,1,1] neg_lo:[1,0,0] neg_hi:[1,0,0]
	v_pk_fma_f32 v[180:181], v[166:167], v[196:197], v[180:181] op_sel_hi:[0,1,1] neg_lo:[1,0,0] neg_hi:[1,0,0]
	ds_read_b32 v182, v165 offset:9364
	ds_read_b64 v[184:185], v165 offset:9368
	ds_read_b128 v[186:189], v165 offset:9376
	ds_read_b128 v[190:193], v165 offset:9392
	s_waitcnt lgkmcnt(11)
	v_pk_fma_f32 v[168:169], v[166:167], v[198:199], v[168:169] op_sel:[1,0,0] op_sel_hi:[1,1,1] neg_lo:[1,0,0] neg_hi:[1,0,0]
	v_pk_fma_f32 v[170:171], v[166:167], v[200:201], v[170:171] op_sel:[1,0,0] op_sel_hi:[1,1,1] neg_lo:[1,0,0] neg_hi:[1,0,0]
	v_pk_fma_f32 v[172:173], v[166:167], v[202:203], v[172:173] op_sel:[1,0,0] op_sel_hi:[1,1,1] neg_lo:[1,0,0] neg_hi:[1,0,0]
	v_pk_fma_f32 v[174:175], v[166:167], v[204:205], v[174:175] op_sel:[1,0,0] op_sel_hi:[1,1,1] neg_lo:[1,0,0] neg_hi:[1,0,0]
	v_pk_fma_f32 v[176:177], v[166:167], v[206:207], v[176:177] op_sel:[1,0,0] op_sel_hi:[1,1,1] neg_lo:[1,0,0] neg_hi:[1,0,0]
	v_pk_fma_f32 v[178:179], v[166:167], v[208:209], v[178:179] op_sel:[1,0,0] op_sel_hi:[1,1,1] neg_lo:[1,0,0] neg_hi:[1,0,0]
	v_pk_fma_f32 v[180:181], v[166:167], v[210:211], v[180:181] op_sel:[1,0,0] op_sel_hi:[1,1,1] neg_lo:[1,0,0] neg_hi:[1,0,0]
	ds_read_b64 v[194:195], v165 offset:9624
	ds_read_b128 v[196:199], v165 offset:9632
	ds_read_b128 v[200:203], v165 offset:9648
	s_waitcnt lgkmcnt(10)
	v_fma_f32 v169, -v168, v183, v169
	v_pk_fma_f32 v[170:171], v[168:169], v[212:213], v[170:171] op_sel_hi:[0,1,1] neg_lo:[1,0,0] neg_hi:[1,0,0]
	v_pk_fma_f32 v[172:173], v[168:169], v[214:215], v[172:173] op_sel_hi:[0,1,1] neg_lo:[1,0,0] neg_hi:[1,0,0]
	v_pk_fma_f32 v[174:175], v[168:169], v[216:217], v[174:175] op_sel_hi:[0,1,1] neg_lo:[1,0,0] neg_hi:[1,0,0]
	v_pk_fma_f32 v[176:177], v[168:169], v[218:219], v[176:177] op_sel_hi:[0,1,1] neg_lo:[1,0,0] neg_hi:[1,0,0]
	v_pk_fma_f32 v[178:179], v[168:169], v[220:221], v[178:179] op_sel_hi:[0,1,1] neg_lo:[1,0,0] neg_hi:[1,0,0]
	v_pk_fma_f32 v[180:181], v[168:169], v[222:223], v[180:181] op_sel_hi:[0,1,1] neg_lo:[1,0,0] neg_hi:[1,0,0]
	ds_read_b32 v183, v165 offset:9884
	ds_read_b128 v[204:207], v165 offset:9888
	ds_read_b128 v[208:211], v165 offset:9904
	s_waitcnt lgkmcnt(10)
	v_pk_fma_f32 v[170:171], v[168:169], v[226:227], v[170:171] op_sel:[1,0,0] op_sel_hi:[1,1,1] neg_lo:[1,0,0] neg_hi:[1,0,0]
	v_pk_fma_f32 v[172:173], v[168:169], v[228:229], v[172:173] op_sel:[1,0,0] op_sel_hi:[1,1,1] neg_lo:[1,0,0] neg_hi:[1,0,0]
	v_pk_fma_f32 v[174:175], v[168:169], v[230:231], v[174:175] op_sel:[1,0,0] op_sel_hi:[1,1,1] neg_lo:[1,0,0] neg_hi:[1,0,0]
	v_pk_fma_f32 v[176:177], v[168:169], v[232:233], v[176:177] op_sel:[1,0,0] op_sel_hi:[1,1,1] neg_lo:[1,0,0] neg_hi:[1,0,0]
	v_pk_fma_f32 v[178:179], v[168:169], v[234:235], v[178:179] op_sel:[1,0,0] op_sel_hi:[1,1,1] neg_lo:[1,0,0] neg_hi:[1,0,0]
	v_pk_fma_f32 v[180:181], v[168:169], v[236:237], v[180:181] op_sel:[1,0,0] op_sel_hi:[1,1,1] neg_lo:[1,0,0] neg_hi:[1,0,0]
	ds_read_b128 v[212:215], v165 offset:10144
	ds_read_b128 v[216:219], v165 offset:10160
	s_waitcnt lgkmcnt(8)
	v_fma_f32 v171, -v170, v182, v171
	v_pk_fma_f32 v[172:173], v[170:171], v[184:185], v[172:173] op_sel_hi:[0,1,1] neg_lo:[1,0,0] neg_hi:[1,0,0]
	v_pk_fma_f32 v[174:175], v[170:171], v[186:187], v[174:175] op_sel_hi:[0,1,1] neg_lo:[1,0,0] neg_hi:[1,0,0]
	v_pk_fma_f32 v[176:177], v[170:171], v[188:189], v[176:177] op_sel_hi:[0,1,1] neg_lo:[1,0,0] neg_hi:[1,0,0]
	v_pk_fma_f32 v[178:179], v[170:171], v[190:191], v[178:179] op_sel_hi:[0,1,1] neg_lo:[1,0,0] neg_hi:[1,0,0]
	v_pk_fma_f32 v[180:181], v[170:171], v[192:193], v[180:181] op_sel_hi:[0,1,1] neg_lo:[1,0,0] neg_hi:[1,0,0]
	ds_read_b32 v182, v165 offset:10404
	ds_read_b64 v[184:185], v165 offset:10408
	ds_read_b128 v[186:189], v165 offset:10416
	s_waitcnt lgkmcnt(8)
; __device__ __forceinline__ float delta_prep(const Params& p, int l, int h, bool isP, int grow0, int t0, int nvalid, int bb, char* sm) {
;     ...
;       if (ib > 0) {
;         f32x4 a0 = (f32x4){0.f, 0.f, 0.f, 0.f}, a1 = a0;
;         const bfraw* xb0 = (w < 4) ? XTu + ((2 * w) * 16 + r) * 72 : XTw + ((2 * w - 8) * 16 + r) * 72;
;         const bfraw* xb1 = xb0 + 16 * 72;
; #pragma unroll
;         for (int kk = 0; kk < 2; ++kk) {
;           if (kk * 32 < ib * 16) {
;             bf16x8 am = *(const bf16x8*)(Mb + (ib * 16 + r) * 72 + kk * 32 + q * 8);
;             bf16x8 b0 = *(const bf16x8*)(xb0 + kk * 32 + q * 8);
;             bf16x8 b1 = *(const bf16x8*)(xb1 + kk * 32 + q * 8);
;             a0 = mfma16(am, b0, a0);
;             a1 = mfma16(am, b1, a1);
;           }
;         }
; #pragma unroll
;         for (int g = 0; g < 4; ++g) {
;           float* rp = xs + (ib * 16 + q * 4 + g) * 256 + w * 32 + r;
;           rp[0] -= a0[g];
;           rp[16] -= a1[g];
;         }
;         __syncthreads();
;     ...
;       if (tid < 256) {
;         float a[16];
; #pragma unroll
;         for (int ii = 0; ii < 16; ++ii) a[ii] = xs[(ib * 16 + ii) * 256 + tid];
; #pragma unroll
;         for (int j = 0; j < 16; ++j) {
;           const float xj = a[j];
;           const float* mp = MT + (ib * 16 + j) * 64 + ib * 16;
; #pragma unroll
;           for (int ii = j + 1; ii < 16; ++ii) a[ii] -= mp[ii] * xj;
;         }
;         bfraw* dst = (tid < 128) ? XTu + tid * 72 + ib * 16 : XTw + (tid - 128) * 72 + ib * 16;
;         *(uint4*)dst = pack8(a);
;         *(uint4*)(dst + 8) = pack8(a + 8);
;       }
	v_pk_fma_f32 v[172:173], v[170:171], v[194:195], v[172:173] op_sel:[1,0,0] op_sel_hi:[1,1,1] neg_lo:[1,0,0] neg_hi:[1,0,0]
	v_pk_fma_f32 v[174:175], v[170:171], v[196:197], v[174:175] op_sel:[1,0,0] op_sel_hi:[1,1,1] neg_lo:[1,0,0] neg_hi:[1,0,0]
	v_pk_fma_f32 v[176:177], v[170:171], v[198:199], v[176:177] op_sel:[1,0,0] op_sel_hi:[1,1,1] neg_lo:[1,0,0] neg_hi:[1,0,0]
	v_pk_fma_f32 v[178:179], v[170:171], v[200:201], v[178:179] op_sel:[1,0,0] op_sel_hi:[1,1,1] neg_lo:[1,0,0] neg_hi:[1,0,0]
	v_pk_fma_f32 v[180:181], v[170:171], v[202:203], v[180:181] op_sel:[1,0,0] op_sel_hi:[1,1,1] neg_lo:[1,0,0] neg_hi:[1,0,0]
	ds_read_b64 v[190:191], v165 offset:10664
	ds_read_b128 v[192:195], v165 offset:10672
	s_waitcnt lgkmcnt(7)
	v_fma_f32 v173, -v172, v183, v173
	v_pk_fma_f32 v[174:175], v[172:173], v[204:205], v[174:175] op_sel_hi:[0,1,1] neg_lo:[1,0,0] neg_hi:[1,0,0]
	v_pk_fma_f32 v[176:177], v[172:173], v[206:207], v[176:177] op_sel_hi:[0,1,1] neg_lo:[1,0,0] neg_hi:[1,0,0]
	v_pk_fma_f32 v[178:179], v[172:173], v[208:209], v[178:179] op_sel_hi:[0,1,1] neg_lo:[1,0,0] neg_hi:[1,0,0]
	v_pk_fma_f32 v[180:181], v[172:173], v[210:211], v[180:181] op_sel_hi:[0,1,1] neg_lo:[1,0,0] neg_hi:[1,0,0]
	ds_read_b32 v183, v165 offset:10924
	ds_read_b128 v[196:199], v165 offset:10928
	s_waitcnt lgkmcnt(7)
	v_pk_fma_f32 v[174:175], v[172:173], v[212:213], v[174:175] op_sel:[1,0,0] op_sel_hi:[1,1,1] neg_lo:[1,0,0] neg_hi:[1,0,0]
	v_pk_fma_f32 v[176:177], v[172:173], v[214:215], v[176:177] op_sel:[1,0,0] op_sel_hi:[1,1,1] neg_lo:[1,0,0] neg_hi:[1,0,0]
	v_pk_fma_f32 v[178:179], v[172:173], v[216:217], v[178:179] op_sel:[1,0,0] op_sel_hi:[1,1,1] neg_lo:[1,0,0] neg_hi:[1,0,0]
	v_pk_fma_f32 v[180:181], v[172:173], v[218:219], v[180:181] op_sel:[1,0,0] op_sel_hi:[1,1,1] neg_lo:[1,0,0] neg_hi:[1,0,0]
	ds_read_b128 v[200:203], v165 offset:11184
	s_waitcnt lgkmcnt(5)
	v_fma_f32 v175, -v174, v182, v175
	v_pk_fma_f32 v[176:177], v[174:175], v[184:185], v[176:177] op_sel_hi:[0,1,1] neg_lo:[1,0,0] neg_hi:[1,0,0]
	v_pk_fma_f32 v[178:179], v[174:175], v[186:187], v[178:179] op_sel_hi:[0,1,1] neg_lo:[1,0,0] neg_hi:[1,0,0]
	v_pk_fma_f32 v[180:181], v[174:175], v[188:189], v[180:181] op_sel_hi:[0,1,1] neg_lo:[1,0,0] neg_hi:[1,0,0]
	ds_read_b32 v182, v165 offset:11444
	ds_read_b64 v[184:185], v165 offset:11448
	s_waitcnt lgkmcnt(5)
	v_pk_fma_f32 v[176:177], v[174:175], v[190:191], v[176:177] op_sel:[1,0,0] op_sel_hi:[1,1,1] neg_lo:[1,0,0] neg_hi:[1,0,0]
	v_pk_fma_f32 v[178:179], v[174:175], v[192:193], v[178:179] op_sel:[1,0,0] op_sel_hi:[1,1,1] neg_lo:[1,0,0] neg_hi:[1,0,0]
	v_pk_fma_f32 v[180:181], v[174:175], v[194:195], v[180:181] op_sel:[1,0,0] op_sel_hi:[1,1,1] neg_lo:[1,0,0] neg_hi:[1,0,0]
	ds_read_b64 v[186:187], v165 offset:11704
	s_waitcnt lgkmcnt(4)
	v_fma_f32 v177, -v176, v183, v177
	v_pk_fma_f32 v[178:179], v[176:177], v[196:197], v[178:179] op_sel_hi:[0,1,1] neg_lo:[1,0,0] neg_hi:[1,0,0]
	v_pk_fma_f32 v[180:181], v[176:177], v[198:199], v[180:181] op_sel_hi:[0,1,1] neg_lo:[1,0,0] neg_hi:[1,0,0]
	ds_read_b32 v183, v165 offset:11964
	s_waitcnt lgkmcnt(4)
	v_pk_fma_f32 v[178:179], v[176:177], v[200:201], v[178:179] op_sel:[1,0,0] op_sel_hi:[1,1,1] neg_lo:[1,0,0] neg_hi:[1,0,0]
	v_pk_fma_f32 v[180:181], v[176:177], v[202:203], v[180:181] op_sel:[1,0,0] op_sel_hi:[1,1,1] neg_lo:[1,0,0] neg_hi:[1,0,0]
	s_waitcnt lgkmcnt(2)
	v_fma_f32 v179, -v178, v182, v179
	v_pk_fma_f32 v[180:181], v[178:179], v[184:185], v[180:181] op_sel_hi:[0,1,1] neg_lo:[1,0,0] neg_hi:[1,0,0]
	s_waitcnt lgkmcnt(1)
	v_pk_fma_f32 v[180:181], v[178:179], v[186:187], v[180:181] op_sel:[1,0,0] op_sel_hi:[1,1,1] neg_lo:[1,0,0] neg_hi:[1,0,0]
	s_waitcnt lgkmcnt(0)
	v_fma_f32 v181, -v180, v183, v181
	v_cvt_pk_bf16_f32 v182, v166, v167
	v_cvt_pk_bf16_f32 v183, v168, v169
	v_cvt_pk_bf16_f32 v184, v170, v171
	v_cvt_pk_bf16_f32 v185, v172, v173
	ds_write_b128 v31, v[182:185] offset:64
	v_cvt_pk_bf16_f32 v186, v174, v175
	v_cvt_pk_bf16_f32 v187, v176, v177
	v_cvt_pk_bf16_f32 v188, v178, v179
	v_cvt_pk_bf16_f32 v189, v180, v181
	ds_write_b128 v31, v[186:189] offset:80
	v_readlane_b32 s2, v245, 41
.LBB0_3795:
	s_or_b64 exec, exec, s[0:1]
	v_mad_u32_u24 v12, v11, s87, v19
	s_waitcnt lgkmcnt(0)
	s_barrier
	ds_read_b128 v[0:3], v12 offset:34816
	ds_read_b128 v[4:7], v38
	ds_read_b128 v[8:11], v38 offset:2304
	s_waitcnt lgkmcnt(1)
	v_mfma_f32_16x16x32_bf16 v[4:7], v[0:3], v[4:7], 0
	s_waitcnt lgkmcnt(0)
	v_mfma_f32_16x16x32_bf16 v[0:3], v[0:3], v[8:11], 0
	ds_read_b128 v[8:11], v12 offset:34880
	ds_read_b128 v[16:19], v38 offset:64
	ds_read_b128 v[20:23], v38 offset:2368
	s_waitcnt lgkmcnt(1)
	v_mfma_f32_16x16x32_bf16 v[4:7], v[8:11], v[16:19], v[4:7]
	s_waitcnt lgkmcnt(0)
	v_mfma_f32_16x16x32_bf16 v[0:3], v[8:11], v[20:23], v[0:3]
	v_add_u32_e32 v10, 0xc000, v25
	ds_read2_b32 v[8:9], v10 offset1:16
	s_waitcnt lgkmcnt(0)
	s_nop 2
	v_sub_f32_e32 v4, v8, v4
	s_nop 0
	v_sub_f32_e32 v0, v9, v0
	ds_write2_b32 v10, v4, v0 offset1:16
	v_add_u32_e32 v0, 0xc400, v25
	ds_read2_b32 v[8:9], v0 offset1:16
	s_waitcnt lgkmcnt(0)
	v_sub_f32_e32 v4, v8, v5
	v_sub_f32_e32 v1, v9, v1
	ds_write2_b32 v0, v4, v1 offset1:16
	v_add_u32_e32 v4, 0xc800, v25
	ds_read2_b32 v[0:1], v4 offset1:16
	s_waitcnt lgkmcnt(0)
	v_sub_f32_e32 v0, v0, v6
	v_sub_f32_e32 v1, v1, v2
	v_add_u32_e32 v2, 0xcc00, v25
	ds_write2_b32 v4, v0, v1 offset1:16
	ds_read2_b32 v[0:1], v2 offset1:16
	s_waitcnt lgkmcnt(0)
	v_sub_f32_e32 v0, v0, v7
	v_sub_f32_e32 v1, v1, v3
	ds_write2_b32 v2, v0, v1 offset1:16
	s_waitcnt lgkmcnt(0)
	s_barrier
	s_and_saveexec_b64 s[0:1], s[4:5]
	s_cbranch_execz .LBB0_3797
; __device__ __forceinline__ float delta_prep(const Params& p, int l, int h, bool isP, int grow0, int t0, int nvalid, int bb, char* sm) {
;     ...
;       if (tid < 256) {
;         float a[16];
; #pragma unroll
;         for (int ii = 0; ii < 16; ++ii) a[ii] = xs[(ib * 16 + ii) * 256 + tid];
; #pragma unroll
;         for (int j = 0; j < 16; ++j) {
;           const float xj = a[j];
;           const float* mp = MT + (ib * 16 + j) * 64 + ib * 16;
; #pragma unroll
;           for (int ii = j + 1; ii < 16; ++ii) a[ii] -= mp[ii] * xj;
;         }
;         bfraw* dst = (tid < 128) ? XTu + tid * 72 + ib * 16 : XTw + (tid - 128) * 72 + ib * 16;
;         *(uint4*)dst = pack8(a);
;         *(uint4*)(dst + 8) = pack8(a + 8);
;       }
	ds_read2st64_b32 v[166:167], v40 offset0:192 offset1:196
	ds_read2st64_b32 v[168:169], v40 offset0:200 offset1:204
	ds_read2st64_b32 v[170:171], v40 offset0:208 offset1:212
	ds_read2st64_b32 v[172:173], v40 offset0:216 offset1:220
	ds_read2st64_b32 v[174:175], v40 offset0:224 offset1:228
	ds_read2st64_b32 v[176:177], v40 offset0:232 offset1:236
	ds_read2st64_b32 v[178:179], v40 offset0:240 offset1:244
	ds_read2st64_b32 v[180:181], v40 offset0:248 offset1:252
	v_mov_b32_e32 v165, 0x23c00
	ds_read_b32 v182, v165 offset:12484
	ds_read_b64 v[184:185], v165 offset:12488
	ds_read_b128 v[186:189], v165 offset:12496
	ds_read_b128 v[190:193], v165 offset:12512
	ds_read_b128 v[194:197], v165 offset:12528
	ds_read_b64 v[198:199], v165 offset:12744
	ds_read_b128 v[200:203], v165 offset:12752
	ds_read_b128 v[204:207], v165 offset:12768
	ds_read_b128 v[208:211], v165 offset:12784
	ds_read_b32 v183, v165 offset:13004
	ds_read_b128 v[212:215], v165 offset:13008
	ds_read_b128 v[216:219], v165 offset:13024
	ds_read_b128 v[220:223], v165 offset:13040
	s_waitcnt lgkmcnt(13)
	ds_read_b128 v[226:229], v165 offset:13264
	ds_read_b128 v[230:233], v165 offset:13280
	ds_read_b128 v[234:237], v165 offset:13296
	s_waitcnt lgkmcnt(11)
	v_fma_f32 v167, -v166, v182, v167
	v_pk_fma_f32 v[168:169], v[166:167], v[184:185], v[168:169] op_sel_hi:[0,1,1] neg_lo:[1,0,0] neg_hi:[1,0,0]
	v_pk_fma_f32 v[170:171], v[166:167], v[186:187], v[170:171] op_sel_hi:[0,1,1] neg_lo:[1,0,0] neg_hi:[1,0,0]
	v_pk_fma_f32 v[172:173], v[166:167], v[188:189], v[172:173] op_sel_hi:[0,1,1] neg_lo:[1,0,0] neg_hi:[1,0,0]
	v_pk_fma_f32 v[174:175], v[166:167], v[190:191], v[174:175] op_sel_hi:[0,1,1] neg_lo:[1,0,0] neg_hi:[1,0,0]
	v_pk_fma_f32 v[176:177], v[166:167], v[192:193], v[176:177] op_sel_hi:[0,1,1] neg_lo:[1,0,0] neg_hi:[1,0,0]
	v_pk_fma_f32 v[178:179], v[166:167], v[194:195], v[178:179] op_sel_hi:[0,1,1] neg_lo:[1,0,0] neg_hi:[1,0,0]
	v_pk_fma_f32 v[180:181], v[166:167], v[196:197], v[180:181] op_sel_hi:[0,1,1] neg_lo:[1,0,0] neg_hi:[1,0,0]
	ds_read_b32 v182, v165 offset:13524
	ds_read_b64 v[184:185], v165 offset:13528
	ds_read_b128 v[186:189], v165 offset:13536
	ds_read_b128 v[190:193], v165 offset:13552
	s_waitcnt lgkmcnt(11)
	v_pk_fma_f32 v[168:169], v[166:167], v[198:199], v[168:169] op_sel:[1,0,0] op_sel_hi:[1,1,1] neg_lo:[1,0,0] neg_hi:[1,0,0]
	v_pk_fma_f32 v[170:171], v[166:167], v[200:201], v[170:171] op_sel:[1,0,0] op_sel_hi:[1,1,1] neg_lo:[1,0,0] neg_hi:[1,0,0]
	v_pk_fma_f32 v[172:173], v[166:167], v[202:203], v[172:173] op_sel:[1,0,0] op_sel_hi:[1,1,1] neg_lo:[1,0,0] neg_hi:[1,0,0]
	v_pk_fma_f32 v[174:175], v[166:167], v[204:205], v[174:175] op_sel:[1,0,0] op_sel_hi:[1,1,1] neg_lo:[1,0,0] neg_hi:[1,0,0]
	v_pk_fma_f32 v[176:177], v[166:167], v[206:207], v[176:177] op_sel:[1,0,0] op_sel_hi:[1,1,1] neg_lo:[1,0,0] neg_hi:[1,0,0]
	v_pk_fma_f32 v[178:179], v[166:167], v[208:209], v[178:179] op_sel:[1,0,0] op_sel_hi:[1,1,1] neg_lo:[1,0,0] neg_hi:[1,0,0]
	v_pk_fma_f32 v[180:181], v[166:167], v[210:211], v[180:181] op_sel:[1,0,0] op_sel_hi:[1,1,1] neg_lo:[1,0,0] neg_hi:[1,0,0]
	ds_read_b64 v[194:195], v165 offset:13784
	ds_read_b128 v[196:199], v165 offset:13792
	ds_read_b128 v[200:203], v165 offset:13808
	s_waitcnt lgkmcnt(10)
	v_fma_f32 v169, -v168, v183, v169
	v_pk_fma_f32 v[170:171], v[168:169], v[212:213], v[170:171] op_sel_hi:[0,1,1] neg_lo:[1,0,0] neg_hi:[1,0,0]
	v_pk_fma_f32 v[172:173], v[168:169], v[214:215], v[172:173] op_sel_hi:[0,1,1] neg_lo:[1,0,0] neg_hi:[1,0,0]
	v_pk_fma_f32 v[174:175], v[168:169], v[216:217], v[174:175] op_sel_hi:[0,1,1] neg_lo:[1,0,0] neg_hi:[1,0,0]
	v_pk_fma_f32 v[176:177], v[168:169], v[218:219], v[176:177] op_sel_hi:[0,1,1] neg_lo:[1,0,0] neg_hi:[1,0,0]
	v_pk_fma_f32 v[178:179], v[168:169], v[220:221], v[178:179] op_sel_hi:[0,1,1] neg_lo:[1,0,0] neg_hi:[1,0,0]
	v_pk_fma_f32 v[180:181], v[168:169], v[222:223], v[180:181] op_sel_hi:[0,1,1] neg_lo:[1,0,0] neg_hi:[1,0,0]
	ds_read_b32 v183, v165 offset:14044
	ds_read_b128 v[204:207], v165 offset:14048
	ds_read_b128 v[208:211], v165 offset:14064
	s_waitcnt lgkmcnt(10)
	v_pk_fma_f32 v[170:171], v[168:169], v[226:227], v[170:171] op_sel:[1,0,0] op_sel_hi:[1,1,1] neg_lo:[1,0,0] neg_hi:[1,0,0]
	v_pk_fma_f32 v[172:173], v[168:169], v[228:229], v[172:173] op_sel:[1,0,0] op_sel_hi:[1,1,1] neg_lo:[1,0,0] neg_hi:[1,0,0]
	v_pk_fma_f32 v[174:175], v[168:169], v[230:231], v[174:175] op_sel:[1,0,0] op_sel_hi:[1,1,1] neg_lo:[1,0,0] neg_hi:[1,0,0]
	v_pk_fma_f32 v[176:177], v[168:169], v[232:233], v[176:177] op_sel:[1,0,0] op_sel_hi:[1,1,1] neg_lo:[1,0,0] neg_hi:[1,0,0]
	v_pk_fma_f32 v[178:179], v[168:169], v[234:235], v[178:179] op_sel:[1,0,0] op_sel_hi:[1,1,1] neg_lo:[1,0,0] neg_hi:[1,0,0]
	v_pk_fma_f32 v[180:181], v[168:169], v[236:237], v[180:181] op_sel:[1,0,0] op_sel_hi:[1,1,1] neg_lo:[1,0,0] neg_hi:[1,0,0]
	ds_read_b128 v[212:215], v165 offset:14304
	ds_read_b128 v[216:219], v165 offset:14320
	s_waitcnt lgkmcnt(8)
; __device__ __forceinline__ float delta_prep(const Params& p, int l, int h, bool isP, int grow0, int t0, int nvalid, int bb, char* sm) {
;     ...
;       if (tid < 256) {
;         float a[16];
; #pragma unroll
;         for (int ii = 0; ii < 16; ++ii) a[ii] = xs[(ib * 16 + ii) * 256 + tid];
; #pragma unroll
;         for (int j = 0; j < 16; ++j) {
;           const float xj = a[j];
;           const float* mp = MT + (ib * 16 + j) * 64 + ib * 16;
; #pragma unroll
;           for (int ii = j + 1; ii < 16; ++ii) a[ii] -= mp[ii] * xj;
;         }
;         bfraw* dst = (tid < 128) ? XTu + tid * 72 + ib * 16 : XTw + (tid - 128) * 72 + ib * 16;
;         *(uint4*)dst = pack8(a);
;         *(uint4*)(dst + 8) = pack8(a + 8);
;       }
	v_fma_f32 v171, -v170, v182, v171
	v_pk_fma_f32 v[172:173], v[170:171], v[184:185], v[172:173] op_sel_hi:[0,1,1] neg_lo:[1,0,0] neg_hi:[1,0,0]
	v_pk_fma_f32 v[174:175], v[170:171], v[186:187], v[174:175] op_sel_hi:[0,1,1] neg_lo:[1,0,0] neg_hi:[1,0,0]
	v_pk_fma_f32 v[176:177], v[170:171], v[188:189], v[176:177] op_sel_hi:[0,1,1] neg_lo:[1,0,0] neg_hi:[1,0,0]
	v_pk_fma_f32 v[178:179], v[170:171], v[190:191], v[178:179] op_sel_hi:[0,1,1] neg_lo:[1,0,0] neg_hi:[1,0,0]
	v_pk_fma_f32 v[180:181], v[170:171], v[192:193], v[180:181] op_sel_hi:[0,1,1] neg_lo:[1,0,0] neg_hi:[1,0,0]
	ds_read_b32 v182, v165 offset:14564
	ds_read_b64 v[184:185], v165 offset:14568
	ds_read_b128 v[186:189], v165 offset:14576
	s_waitcnt lgkmcnt(8)
	v_pk_fma_f32 v[172:173], v[170:171], v[194:195], v[172:173] op_sel:[1,0,0] op_sel_hi:[1,1,1] neg_lo:[1,0,0] neg_hi:[1,0,0]
	v_pk_fma_f32 v[174:175], v[170:171], v[196:197], v[174:175] op_sel:[1,0,0] op_sel_hi:[1,1,1] neg_lo:[1,0,0] neg_hi:[1,0,0]
	v_pk_fma_f32 v[176:177], v[170:171], v[198:199], v[176:177] op_sel:[1,0,0] op_sel_hi:[1,1,1] neg_lo:[1,0,0] neg_hi:[1,0,0]
	v_pk_fma_f32 v[178:179], v[170:171], v[200:201], v[178:179] op_sel:[1,0,0] op_sel_hi:[1,1,1] neg_lo:[1,0,0] neg_hi:[1,0,0]
	v_pk_fma_f32 v[180:181], v[170:171], v[202:203], v[180:181] op_sel:[1,0,0] op_sel_hi:[1,1,1] neg_lo:[1,0,0] neg_hi:[1,0,0]
	ds_read_b64 v[190:191], v165 offset:14824
	ds_read_b128 v[192:195], v165 offset:14832
	s_waitcnt lgkmcnt(7)
	v_fma_f32 v173, -v172, v183, v173
	v_pk_fma_f32 v[174:175], v[172:173], v[204:205], v[174:175] op_sel_hi:[0,1,1] neg_lo:[1,0,0] neg_hi:[1,0,0]
	v_pk_fma_f32 v[176:177], v[172:173], v[206:207], v[176:177] op_sel_hi:[0,1,1] neg_lo:[1,0,0] neg_hi:[1,0,0]
	v_pk_fma_f32 v[178:179], v[172:173], v[208:209], v[178:179] op_sel_hi:[0,1,1] neg_lo:[1,0,0] neg_hi:[1,0,0]
	v_pk_fma_f32 v[180:181], v[172:173], v[210:211], v[180:181] op_sel_hi:[0,1,1] neg_lo:[1,0,0] neg_hi:[1,0,0]
	ds_read_b32 v183, v165 offset:15084
	ds_read_b128 v[196:199], v165 offset:15088
	s_waitcnt lgkmcnt(7)
	v_pk_fma_f32 v[174:175], v[172:173], v[212:213], v[174:175] op_sel:[1,0,0] op_sel_hi:[1,1,1] neg_lo:[1,0,0] neg_hi:[1,0,0]
	v_pk_fma_f32 v[176:177], v[172:173], v[214:215], v[176:177] op_sel:[1,0,0] op_sel_hi:[1,1,1] neg_lo:[1,0,0] neg_hi:[1,0,0]
	v_pk_fma_f32 v[178:179], v[172:173], v[216:217], v[178:179] op_sel:[1,0,0] op_sel_hi:[1,1,1] neg_lo:[1,0,0] neg_hi:[1,0,0]
	v_pk_fma_f32 v[180:181], v[172:173], v[218:219], v[180:181] op_sel:[1,0,0] op_sel_hi:[1,1,1] neg_lo:[1,0,0] neg_hi:[1,0,0]
	ds_read_b128 v[200:203], v165 offset:15344
	s_waitcnt lgkmcnt(5)
	v_fma_f32 v175, -v174, v182, v175
	v_pk_fma_f32 v[176:177], v[174:175], v[184:185], v[176:177] op_sel_hi:[0,1,1] neg_lo:[1,0,0] neg_hi:[1,0,0]
	v_pk_fma_f32 v[178:179], v[174:175], v[186:187], v[178:179] op_sel_hi:[0,1,1] neg_lo:[1,0,0] neg_hi:[1,0,0]
	v_pk_fma_f32 v[180:181], v[174:175], v[188:189], v[180:181] op_sel_hi:[0,1,1] neg_lo:[1,0,0] neg_hi:[1,0,0]
	ds_read_b32 v182, v165 offset:15604
	ds_read_b64 v[184:185], v165 offset:15608
	s_waitcnt lgkmcnt(5)
	v_pk_fma_f32 v[176:177], v[174:175], v[190:191], v[176:177] op_sel:[1,0,0] op_sel_hi:[1,1,1] neg_lo:[1,0,0] neg_hi:[1,0,0]
	v_pk_fma_f32 v[178:179], v[174:175], v[192:193], v[178:179] op_sel:[1,0,0] op_sel_hi:[1,1,1] neg_lo:[1,0,0] neg_hi:[1,0,0]
	v_pk_fma_f32 v[180:181], v[174:175], v[194:195], v[180:181] op_sel:[1,0,0] op_sel_hi:[1,1,1] neg_lo:[1,0,0] neg_hi:[1,0,0]
	ds_read_b64 v[186:187], v165 offset:15864
	s_waitcnt lgkmcnt(4)
	v_fma_f32 v177, -v176, v183, v177
	v_pk_fma_f32 v[178:179], v[176:177], v[196:197], v[178:179] op_sel_hi:[0,1,1] neg_lo:[1,0,0] neg_hi:[1,0,0]
	v_pk_fma_f32 v[180:181], v[176:177], v[198:199], v[180:181] op_sel_hi:[0,1,1] neg_lo:[1,0,0] neg_hi:[1,0,0]
	ds_read_b32 v183, v165 offset:16124
	s_waitcnt lgkmcnt(4)
	v_pk_fma_f32 v[178:179], v[176:177], v[200:201], v[178:179] op_sel:[1,0,0] op_sel_hi:[1,1,1] neg_lo:[1,0,0] neg_hi:[1,0,0]
	v_pk_fma_f32 v[180:181], v[176:177], v[202:203], v[180:181] op_sel:[1,0,0] op_sel_hi:[1,1,1] neg_lo:[1,0,0] neg_hi:[1,0,0]
	s_waitcnt lgkmcnt(2)
	v_fma_f32 v179, -v178, v182, v179
	v_pk_fma_f32 v[180:181], v[178:179], v[184:185], v[180:181] op_sel_hi:[0,1,1] neg_lo:[1,0,0] neg_hi:[1,0,0]
	s_waitcnt lgkmcnt(1)
	v_pk_fma_f32 v[180:181], v[178:179], v[186:187], v[180:181] op_sel:[1,0,0] op_sel_hi:[1,1,1] neg_lo:[1,0,0] neg_hi:[1,0,0]
	s_waitcnt lgkmcnt(0)
	v_fma_f32 v181, -v180, v183, v181
	v_cvt_pk_bf16_f32 v182, v166, v167
	v_cvt_pk_bf16_f32 v183, v168, v169
	v_cvt_pk_bf16_f32 v184, v170, v171
	v_cvt_pk_bf16_f32 v185, v172, v173
	ds_write_b128 v31, v[182:185] offset:96
	v_cvt_pk_bf16_f32 v186, v174, v175
	v_cvt_pk_bf16_f32 v187, v176, v177
	v_cvt_pk_bf16_f32 v188, v178, v179
	v_cvt_pk_bf16_f32 v189, v180, v181
	ds_write_b128 v31, v[186:189] offset:112
	v_readlane_b32 s2, v244, 17

; __device__ __forceinline__ int opq(int x) { asm volatile("" : "+v"(x)); return x; }
; __device__ __forceinline__ void state_copies(const Params& p, int l, int bid, int nb) {
;   const bfraw* B1 = (const bfraw*)(p.ws + WS_B1);
;   const bfraw* B2 = (const bfraw*)(p.ws + WS_B2);
;   constexpr int N0 = 4 * 15 * 512, N1 = 4 * 3 * 1536, N2 = 128 * 15 * 512, N3 = 128 * 3 * 1536, N4 = 4 * 128 * 128, N5 = 128 * 128 * 128;
;   constexpr int TOT = N0 + N1 + N2 + N3 + 2 * N4 + 2 * N5;
; #pragma unroll 4
;   for (int i = (bid * NTHR + opq(threadIdx.x)) * 4; i < TOT; i += nb * NTHR * 4) {
;     int e = i;
;     float4 v; float* dst;
;     if (e < N0) { int b = e / (15 * 512), rem = e % (15 * 512), j = rem >> 9, c = rem & 511;
.LBB0_3819:
	v_readlane_b32 s54, v247, 62
	s_waitcnt vmcnt(0)
	v_mov_b32_e32 v0, v224
	s_lshl_b32 s0, s54, 11
	s_nop 0
	v_lshl_add_u32 v4, v0, 2, s0
	s_mov_b32 s0, 0x1ac000
	v_cmp_gt_i32_e32 vcc, s0, v4
	s_and_saveexec_b64 s[4:5], vcc
	v_readlane_b32 s94, v247, 58
	v_readlane_b32 s96, v247, 60
	v_readlane_b32 s95, v247, 59
	v_readlane_b32 s97, v247, 61
	s_cbranch_execz .LBB0_3967
	s_load_dword s1, s[80:81], 0x10
	s_load_dword s10, s[80:81], 0x0
	v_readlane_b32 s16, v247, 0
	v_readlane_b32 s18, v247, 2
	v_readlane_b32 s19, v247, 3
	s_waitcnt lgkmcnt(0)
	s_lshr_b32 s1, s1, 16
	s_add_u32 s6, s96, 0x6420000
	s_addc_u32 s7, s97, 0
	s_add_u32 s8, s96, 0xe920000
	s_addc_u32 s9, s97, 0
	s_cmp_lg_u32 s1, 0
	s_cselect_b64 s[2:3], -1, 0
	s_cmp_lg_u64 s[2:3], 0
	s_addc_u32 s33, s10, 0
	s_lshl_b32 s20, s33, 11
	v_cvt_f32_u32_e32 v1, s20
	s_add_u32 s10, s18, 0x9120000
	s_addc_u32 s11, s19, 0
	s_add_u32 s12, s18, 0x8b20000
	v_rcp_iflag_f32_e32 v1, v1
	s_addc_u32 s13, s19, 0
	v_add_u32_e32 v0, s20, v4
	s_add_u32 s14, s18, 0x844e000
	v_mul_f32_e32 v1, 0x4f7ffffe, v1
	v_cvt_u32_f32_e32 v1, v1
	s_addc_u32 s15, s19, 0
	v_cmp_gt_i32_e32 vcc, s0, v0
	v_readlane_b32 s17, v247, 1
	s_add_u32 s16, s18, 0x841e000
	v_cndmask_b32_e64 v3, 0, 1, vcc
	s_addc_u32 s17, s19, 0
	v_max_i32_e32 v2, 0x1ac000, v0
	v_or_b32_e32 v0, v0, v3
	s_sub_i32 s0, 0, s20
	v_sub_u32_e32 v0, v2, v0
	v_mul_lo_u32 v2, s0, v1
	v_mul_hi_u32 v2, v1, v2
	v_add_u32_e32 v1, v1, v2
	v_mul_hi_u32 v1, v0, v1
	v_mul_lo_u32 v2, v1, s20
	v_sub_u32_e32 v0, v0, v2
	v_add_u32_e32 v2, 1, v1
	v_cmp_le_u32_e64 s[0:1], s20, v0
	s_nop 1
	v_cndmask_b32_e64 v1, v1, v2, s[0:1]
	v_subrev_u32_e32 v2, s20, v0
	v_cndmask_b32_e64 v0, v0, v2, s[0:1]
	v_add_u32_e32 v2, 1, v1
	v_cmp_le_u32_e64 s[0:1], s20, v0
	s_nop 1
	v_cndmask_b32_e64 v0, v1, v2, s[0:1]
	v_addc_co_u32_e32 v10, vcc, 0, v0, vcc
	v_and_b32_e32 v0, 3, v10
	v_cmp_ne_u32_e32 vcc, 3, v0
	s_and_saveexec_b64 s[0:1], vcc
	s_cbranch_execz .LBB0_3852
	v_add_u32_e32 v0, 1, v10
	v_and_b32_e32 v11, 3, v0
	s_mov_b64 s[18:19], 0
	s_movk_i32 s21, 0x77ff
	s_mov_b32 s46, 0xbfff
	s_mov_b32 s47, 0xfbfff
	s_mov_b32 s48, 0x18bfff
	s_mov_b32 s49, 0x1abfff
	s_mov_b32 s50, 0x200000
	s_movk_i32 s51, 0x77
	s_mov_b32 s52, 0x8040
	v_mov_b32_e32 v7, 0
	s_mov_b64 s[28:29], 0x800000
	s_movk_i32 s53, 0x2010
	s_movk_i32 s55, 0xa00
	s_mov_b32 s56, 0x10000
	s_mov_b64 s[30:31], 0x40000
	s_mov_b32 s57, 0x38e38e39
	s_mov_b32 s58, 0x8045
	s_mov_b32 s59, 0x88888889
	s_movk_i32 s60, 0xdff
	s_mov_b32 s61, 0x8039
	s_movk_i32 s62, 0x788
	s_mov_b32 s63, 0xe38f
	s_mov_b32 s64, 0x200d000
	s_movk_i32 s65, 0x2001
	v_mov_b32_e32 v12, 0xe360000
	v_mov_b32_e32 v13, 0xd360000
	v_mov_b32_e32 v14, 0x13ba000
	v_mov_b32_e32 v15, 8
	v_mov_b32_e32 v16, 0x86e0000
	v_mov_b32_e32 v17, 0x8660000
	s_branch .LBB0_3823

; __device__ __forceinline__ int opq(int x) { asm volatile("" : "+v"(x)); return x; }
; __device__ __forceinline__ float4 ld4bf(const bfraw* s) { uint2 v = *(const uint2*)s; return make_float4(lo2f(v.x), hi2f(v.x), lo2f(v.y), hi2f(v.y)); }
; __device__ __forceinline__ void state_copies(const Params& p, int l, int bid, int nb) {
;     ...
;   for (int i = (bid * NTHR + opq(threadIdx.x)) * 4; i < TOT; i += nb * NTHR * 4) {
;     int e = i;
;     float4 v; float* dst;
;     if (e < N0) { int b = e / (15 * 512), rem = e % (15 * 512), j = rem >> 9, c = rem & 511;
;       v = ld4bf(B1 + (size_t)(b * TP + 8193 + j) * LD1 + c); dst = p.out + O_POOLP + (size_t)l * N0 + e; }
;     else if ((e -= N0) < N1) { int b = e / (3 * 1536), rem = e % (3 * 1536), j = rem / 1536, c = rem % 1536;
;       v = ld4bf(B1 + (size_t)(b * TP + 8205 + j) * LD1 + 512 + c); dst = p.out + O_CONVP + (size_t)l * N1 + e; }
;     else if ((e -= N1) < N2) { int b = e / (15 * 512), rem = e % (15 * 512), j = rem >> 9, c = rem & 511;
;       if (j < 7) v = *(const float4*)(p.state_pool + ((size_t)(l * NBS + b) * 15 + j + 8) * 512 + c);
;       else v = ld4bf(B1 + (size_t)(ROWS_P + b * TS + j - 7) * LD1 + c);
;       dst = p.out + O_POOLS + (size_t)l * N2 + e; }
;     else if ((e -= N2) < N3) { int b = e / (3 * 1536), rem = e % (3 * 1536), j = rem / 1536, c = rem % 1536;
;       v = ld4bf(B1 + (size_t)(ROWS_P + b * TS + 5 + j) * LD1 + 512 + c); dst = p.out + O_CONVS + (size_t)l * N3 + e; }
;     else if ((e -= N3) < 2 * N4) { int kv = e / N4, e2 = e % N4; int b = e2 >> 14, j = (e2 >> 7) & 127, c = e2 & 127;
;       v = ld4bf(B2 + (size_t)(b * TP + 8080 + j) * LD2 + 1024 + kv * 128 + c); dst = p.out + (kv ? O_VP : O_KP) + (size_t)l * N4 + e2; }
;     else { e -= 2 * N4; int kv = e / N5, e2 = e % N5; int b = e2 >> 14, j = (e2 >> 7) & 127, c = e2 & 127;
;       const float* cache = kv ? p.cache_v : p.cache_k;
;       if (j < 120) v = *(const float4*)(cache + ((size_t)(l * NBS + b) * 128 + j + 8) * 128 + c);
;       else v = ld4bf(B2 + (size_t)(ROWS_P + b * TS + j - 120) * LD2 + 1024 + kv * 128 + c);
;       dst = p.out + (kv ? O_VS : O_KS) + (size_t)l * N5 + e2; }
;     *(float4*)dst = v;
.LBB0_3967:
	s_or_b64 exec, exec, s[4:5]
	v_readlane_b32 s2, v247, 62
	v_readfirstlane_b32 s0, v224
	v_and_b32_e32 v0, 63, v224
	v_lshlrev_b32_e32 v2, 4, v0
	v_mov_b32_e32 v3, 0
	v_lshrrev_b32_e32 v4, 5, v0
	v_mul_u32_u24_e32 v4, 0xa00, v4
	v_and_b32_e32 v1, 31, v0
	v_lshl_add_u32 v4, v1, 3, v4
	v_mov_b32_e32 v5, 0
	v_readlane_b32 s98, v247, 2
	v_readlane_b32 s99, v247, 3
	s_nop 3
	v_lshl_add_u64 v[6:7], s[98:99], 0, v[2:3]
	v_readlane_b32 s98, v247, 17
	v_readlane_b32 s99, v247, 18
	s_add_u32 s98, s98, 0x801000
	s_addc_u32 s99, s99, 0
	v_lshl_add_u64 v[8:9], s[98:99], 0, v[2:3]
	v_readlane_b32 s98, v247, 19
	v_readlane_b32 s99, v247, 20
	s_add_u32 s98, s98, 0x801000
	s_addc_u32 s99, s99, 0
	v_lshl_add_u64 v[10:11], s[98:99], 0, v[2:3]
	v_readlane_b32 s98, v247, 60
	v_readlane_b32 s99, v247, 61
	s_add_u32 s98, s98, 0x138fd800
	s_addc_u32 s99, s99, 0
	v_lshl_add_u64 v[12:13], s[98:99], 0, v[4:5]
	s_waitcnt lgkmcnt(0)
	s_lshl_b32 s1, s84, 9
	s_lshl_b32 s2, s2, 9
	s_add_u32 s0, s0, s2
	s_mov_b32 s101, 0
	s_cmp_lt_u32 s0, 0x100000
	s_cbranch_scc0 .Lsc1_done
.Lsc1_loop:
	s_mov_b32 s3, 0
	s_mov_b32 s2, s0
	s_lshr_b32 s98, s2, 19
	s_and_b32 s99, s2, 0x7ffff
	s_lshl_b32 s99, s99, 4
	s_lshl_b32 s100, s98, 24
	s_add_u32 s100, s100, s99
	s_add_u32 s100, s100, 0xdb60000
	v_lshl_add_u64 v[20:21], s[100:101], 0, v[6:7]
	s_bfe_u32 s100, s2, 0x70005
	s_cmp_ge_u32 s100, 0x78
	s_cbranch_scc1 .Lsc1_b0
	s_mov_b32 s100, s99
	s_cmp_eq_u32 s98, 0
	s_cbranch_scc0 .Lsc1_v0
	v_lshl_add_u64 v[30:31], s[100:101], 0, v[8:9]
	s_branch .Lsc1_la0

; __device__ __forceinline__ float4 ld4bf(const bfraw* s) { uint2 v = *(const uint2*)s; return make_float4(lo2f(v.x), hi2f(v.x), lo2f(v.y), hi2f(v.y)); }
; __device__ __forceinline__ void state_copies(const Params& p, int l, int bid, int nb) {
;     ...
;     else { e -= 2 * N4; int kv = e / N5, e2 = e % N5; int b = e2 >> 14, j = (e2 >> 7) & 127, c = e2 & 127;
;       const float* cache = kv ? p.cache_v : p.cache_k;
;       if (j < 120) v = *(const float4*)(cache + ((size_t)(l * NBS + b) * 128 + j + 8) * 128 + c);
;       else v = ld4bf(B2 + (size_t)(ROWS_P + b * TS + j - 120) * LD2 + 1024 + kv * 128 + c);
;       dst = p.out + (kv ? O_VS : O_KS) + (size_t)l * N5 + e2; }
;     *(float4*)dst = v;
.Lsc1_e0:
	s_mul_i32 s2, s1, 1
	s_add_u32 s2, s2, s0
	s_cmp_lt_u32 s2, 0x100000
	s_cselect_b32 s2, s2, s0
	s_lshr_b32 s98, s2, 19
	s_and_b32 s99, s2, 0x7ffff
	s_lshl_b32 s99, s99, 4
	s_lshl_b32 s100, s98, 24
	s_add_u32 s100, s100, s99
	s_add_u32 s100, s100, 0xdb60000
	v_lshl_add_u64 v[22:23], s[100:101], 0, v[6:7]
	s_bfe_u32 s100, s2, 0x70005
	s_cmp_ge_u32 s100, 0x78
	s_cbranch_scc1 .Lsc1_b1
	s_mov_b32 s100, s99
	s_cmp_eq_u32 s98, 0
	s_cbranch_scc0 .Lsc1_v1
	v_lshl_add_u64 v[32:33], s[100:101], 0, v[8:9]
	s_branch .Lsc1_la1

; __device__ __forceinline__ float4 ld4bf(const bfraw* s) { uint2 v = *(const uint2*)s; return make_float4(lo2f(v.x), hi2f(v.x), lo2f(v.y), hi2f(v.y)); }
; __device__ __forceinline__ void state_copies(const Params& p, int l, int bid, int nb) {
;     ...
;     else { e -= 2 * N4; int kv = e / N5, e2 = e % N5; int b = e2 >> 14, j = (e2 >> 7) & 127, c = e2 & 127;
;       const float* cache = kv ? p.cache_v : p.cache_k;
;       if (j < 120) v = *(const float4*)(cache + ((size_t)(l * NBS + b) * 128 + j + 8) * 128 + c);
;       else v = ld4bf(B2 + (size_t)(ROWS_P + b * TS + j - 120) * LD2 + 1024 + kv * 128 + c);
;       dst = p.out + (kv ? O_VS : O_KS) + (size_t)l * N5 + e2; }
;     *(float4*)dst = v;
.Lsc1_e1:
	s_mul_i32 s2, s1, 2
	s_add_u32 s2, s2, s0
	s_cmp_lt_u32 s2, 0x100000
	s_cselect_b32 s2, s2, s0
	s_lshr_b32 s98, s2, 19
	s_and_b32 s99, s2, 0x7ffff
	s_lshl_b32 s99, s99, 4
	s_lshl_b32 s100, s98, 24
	s_add_u32 s100, s100, s99
	s_add_u32 s100, s100, 0xdb60000
	v_lshl_add_u64 v[24:25], s[100:101], 0, v[6:7]
	s_bfe_u32 s100, s2, 0x70005
	s_cmp_ge_u32 s100, 0x78
	s_cbranch_scc1 .Lsc1_b2
	s_mov_b32 s100, s99
	s_cmp_eq_u32 s98, 0
	s_cbranch_scc0 .Lsc1_v2
	v_lshl_add_u64 v[34:35], s[100:101], 0, v[8:9]
	s_branch .Lsc1_la2

; __device__ __forceinline__ float4 ld4bf(const bfraw* s) { uint2 v = *(const uint2*)s; return make_float4(lo2f(v.x), hi2f(v.x), lo2f(v.y), hi2f(v.y)); }
; __device__ __forceinline__ void state_copies(const Params& p, int l, int bid, int nb) {
;     ...
;     else { e -= 2 * N4; int kv = e / N5, e2 = e % N5; int b = e2 >> 14, j = (e2 >> 7) & 127, c = e2 & 127;
;       const float* cache = kv ? p.cache_v : p.cache_k;
;       if (j < 120) v = *(const float4*)(cache + ((size_t)(l * NBS + b) * 128 + j + 8) * 128 + c);
;       else v = ld4bf(B2 + (size_t)(ROWS_P + b * TS + j - 120) * LD2 + 1024 + kv * 128 + c);
;       dst = p.out + (kv ? O_VS : O_KS) + (size_t)l * N5 + e2; }
;     *(float4*)dst = v;
.Lsc1_e2:
	s_mul_i32 s2, s1, 3
	s_add_u32 s2, s2, s0
	s_cmp_lt_u32 s2, 0x100000
	s_cselect_b32 s2, s2, s0
	s_lshr_b32 s98, s2, 19
	s_and_b32 s99, s2, 0x7ffff
	s_lshl_b32 s99, s99, 4
	s_lshl_b32 s100, s98, 24
	s_add_u32 s100, s100, s99
	s_add_u32 s100, s100, 0xdb60000
	v_lshl_add_u64 v[26:27], s[100:101], 0, v[6:7]
	s_bfe_u32 s100, s2, 0x70005
	s_cmp_ge_u32 s100, 0x78
	s_cbranch_scc1 .Lsc1_b3
	s_mov_b32 s100, s99
	s_cmp_eq_u32 s98, 0
	s_cbranch_scc0 .Lsc1_v3
	v_lshl_add_u64 v[36:37], s[100:101], 0, v[8:9]
	s_branch .Lsc1_la3

; __device__ __forceinline__ unsigned xb_ld(unsigned* p)              { return __hip_atomic_load(p, __ATOMIC_RELAXED, __HIP_MEMORY_SCOPE_AGENT); }
; __device__ __forceinline__ void xcd_barrier_complete(unsigned* bar, unsigned x, unsigned& nloc, unsigned& nx) {
;     const unsigned G = gridDim.x * gridDim.y * gridDim.z;
;     unsigned sum, cnt, mine, sp = 0u;
;     for (;;) {
;         sum = 0u; cnt = 0u; mine = 0u;
; #pragma unroll
;         for (unsigned j = 0; j < 16; ++j) { const unsigned c = xb_ld(&bar[XB_XCNT(j)]); sum += c; cnt += (c > 0u) ? 1u : 0u; mine = (j == x) ? c : mine; }
;         if (sum == G) break;
; __device__ __forceinline__ void xcd_barrier(const XcdBarrier& b) {
;     asm volatile("s_waitcnt vmcnt(0)" ::: "memory");
;     __syncthreads();
;     if (threadIdx.x == 0) {
;         unsigned* bar = b.bar;
;         __builtin_amdgcn_s_waitcnt(0);
;         unsigned nloc = b.st[0], nx = b.st[1];
;         if (nloc == 0u) { xcd_barrier_complete(bar, b.x, nloc, nx); b.st[0] = nloc; b.st[1] = nx; }
.Lsc1_done:
	v_readlane_b32 s92, v247, 56
	v_readlane_b32 s93, v247, 57
	s_cmp_lt_i32 s95, 15
	s_cbranch_scc1 .LBB0_4021
	s_waitcnt vmcnt(0)
	s_waitcnt lgkmcnt(0)
	s_barrier
	s_mov_b64 s[0:1], exec
	v_readlane_b32 s2, v247, 5
	v_readlane_b32 s3, v247, 6
	s_and_b64 s[2:3], s[0:1], s[2:3]
	s_mov_b64 exec, s[2:3]
	s_cbranch_execz .LBB0_4020
	s_add_i32 s2, 0, 0x27ff0
	v_mov_b32_e32 v0, s2
	s_waitcnt vmcnt(0) expcnt(0) lgkmcnt(0)
	ds_read_b32 v2, v0
	s_add_i32 s2, 0, 0x27ff4
	v_mov_b32_e32 v0, s2
	ds_read_b32 v0, v0
	s_waitcnt lgkmcnt(1)
	v_cmp_ne_u32_e32 vcc, 0, v2
	s_cbranch_vccnz .LBB0_3984
	v_readlane_b32 s2, v247, 4
	s_mul_i32 s20, s85, s2
	s_add_u32 s2, s96, 0x1f1ede00
	s_addc_u32 s3, s97, 0
	s_add_u32 s4, s96, 0x1f1ee000
	s_addc_u32 s5, s97, 0
	s_add_u32 s6, s96, 0x1f1ee100
	s_addc_u32 s7, s97, 0
	s_add_u32 s8, s96, 0x1f1ee200
	s_addc_u32 s9, s97, 0
	s_add_u32 s10, s96, 0x1f1ee300
	s_addc_u32 s11, s97, 0
	s_add_u32 s12, s96, 0x1f1ee400
	s_addc_u32 s13, s97, 0
	s_add_u32 s14, s96, 0x1f1ee500
	s_addc_u32 s15, s97, 0
	s_add_u32 s16, s96, 0x1f1ee600
	s_addc_u32 s17, s97, 0
	s_add_u32 s18, s96, 0x1f1ee700
	s_addc_u32 s19, s97, 0
	s_add_u32 s28, s96, 0x1f1ee800
	s_addc_u32 s29, s97, 0
	s_add_u32 s30, s96, 0x1f1ee900
	s_addc_u32 s31, s97, 0
	s_add_u32 s34, s96, 0x1f1eea00
	s_addc_u32 s35, s97, 0
	s_add_u32 s36, s96, 0x1f1eeb00
	s_addc_u32 s37, s97, 0
	s_add_u32 s38, s96, 0x1f1eec00
	s_addc_u32 s39, s97, 0
	s_add_u32 s40, s96, 0x1f1eed00
	s_addc_u32 s41, s97, 0
	s_add_u32 s42, s96, 0x1f1eee00
	s_addc_u32 s43, s97, 0
	s_add_u32 s44, s96, 0x1f1eef00
	s_mul_i32 s20, s20, s84
	s_addc_u32 s45, s97, 0
	s_mov_b32 s21, 1
	v_mov_b32_e32 v16, 0
	s_branch .LBB0_3972

; __device__ __forceinline__ float delta_prep(const Params& p, int l, int h, bool isP, int grow0, int t0, int nvalid, int bb, char* sm) {
;     ...
;       if (tid < 256) {
;         float a[16];
; #pragma unroll
;         for (int ii = 0; ii < 16; ++ii) a[ii] = xs[(ib * 16 + ii) * 256 + tid];
; #pragma unroll
;         for (int j = 0; j < 16; ++j) {
;           const float xj = a[j];
;           const float* mp = MT + (ib * 16 + j) * 64 + ib * 16;
; #pragma unroll
;           for (int ii = j + 1; ii < 16; ++ii) a[ii] -= mp[ii] * xj;
;         }
;         bfraw* dst = (tid < 128) ? XTu + tid * 72 + ib * 16 : XTw + (tid - 128) * 72 + ib * 16;
;         *(uint4*)dst = pack8(a);
;         *(uint4*)(dst + 8) = pack8(a + 8);
;       }
.LBB0_4219:
	s_or_b64 exec, exec, s[0:1]
	v_mul_lo_u32 v1, v0, s47
	s_movk_i32 s0, 0x100
	v_add_u32_e32 v1, 0, v1
	v_cmp_gt_i32_e32 vcc, s0, v0
	v_add_u32_e32 v15, 0xffffb800, v1
	s_waitcnt lgkmcnt(0)
	s_barrier
	s_and_saveexec_b64 s[0:1], vcc
	s_cbranch_execz .LBB0_4221
	s_movk_i32 s2, 0x80
	v_cmp_gt_i32_e32 vcc, s2, v0
	v_lshl_add_u32 v4, v0, 2, 0
	v_add_u32_e32 v6, 0x13c00, v4
	v_add_u32_e32 v19, 0xf400, v1
	v_cndmask_b32_e32 v11, v15, v19, vcc
	ds_read2st64_b32 v[168:169], v6 offset1:4
	ds_read2st64_b32 v[170:171], v6 offset0:8 offset1:12
	ds_read2st64_b32 v[172:173], v6 offset0:16 offset1:20
	ds_read2st64_b32 v[174:175], v6 offset0:24 offset1:28
	ds_read2st64_b32 v[176:177], v6 offset0:32 offset1:36
	ds_read2st64_b32 v[178:179], v6 offset0:40 offset1:44
	ds_read2st64_b32 v[180:181], v6 offset0:48 offset1:52
	ds_read2st64_b32 v[182:183], v6 offset0:56 offset1:60
	v_mov_b32_e32 v167, 0x23c00
	ds_read_b32 v184, v167 offset:4
	ds_read_b64 v[186:187], v167 offset:8
	ds_read_b128 v[188:191], v167 offset:16
	ds_read_b128 v[192:195], v167 offset:32
	ds_read_b128 v[196:199], v167 offset:48
	ds_read_b64 v[200:201], v167 offset:264
	ds_read_b128 v[202:205], v167 offset:272
	ds_read_b128 v[206:209], v167 offset:288
	ds_read_b128 v[210:213], v167 offset:304
	ds_read_b32 v185, v167 offset:524
	ds_read_b128 v[214:217], v167 offset:528
	ds_read_b128 v[218:221], v167 offset:544
	ds_read_b128 v[226:229], v167 offset:560
	s_waitcnt lgkmcnt(13)
	ds_read_b128 v[230:233], v167 offset:784
	ds_read_b128 v[234:237], v167 offset:800
	ds_read_b128 v[238:241], v167 offset:816
	s_waitcnt lgkmcnt(11)
	v_fma_f32 v169, -v168, v184, v169
	v_pk_fma_f32 v[170:171], v[168:169], v[186:187], v[170:171] op_sel_hi:[0,1,1] neg_lo:[1,0,0] neg_hi:[1,0,0]
	v_pk_fma_f32 v[172:173], v[168:169], v[188:189], v[172:173] op_sel_hi:[0,1,1] neg_lo:[1,0,0] neg_hi:[1,0,0]
	v_pk_fma_f32 v[174:175], v[168:169], v[190:191], v[174:175] op_sel_hi:[0,1,1] neg_lo:[1,0,0] neg_hi:[1,0,0]
	v_pk_fma_f32 v[176:177], v[168:169], v[192:193], v[176:177] op_sel_hi:[0,1,1] neg_lo:[1,0,0] neg_hi:[1,0,0]
	v_pk_fma_f32 v[178:179], v[168:169], v[194:195], v[178:179] op_sel_hi:[0,1,1] neg_lo:[1,0,0] neg_hi:[1,0,0]
	v_pk_fma_f32 v[180:181], v[168:169], v[196:197], v[180:181] op_sel_hi:[0,1,1] neg_lo:[1,0,0] neg_hi:[1,0,0]
	v_pk_fma_f32 v[182:183], v[168:169], v[198:199], v[182:183] op_sel_hi:[0,1,1] neg_lo:[1,0,0] neg_hi:[1,0,0]
	ds_read_b32 v184, v167 offset:1044
	ds_read_b64 v[186:187], v167 offset:1048
	ds_read_b128 v[188:191], v167 offset:1056
	ds_read_b128 v[192:195], v167 offset:1072
	s_waitcnt lgkmcnt(11)
	v_pk_fma_f32 v[170:171], v[168:169], v[200:201], v[170:171] op_sel:[1,0,0] op_sel_hi:[1,1,1] neg_lo:[1,0,0] neg_hi:[1,0,0]
	v_pk_fma_f32 v[172:173], v[168:169], v[202:203], v[172:173] op_sel:[1,0,0] op_sel_hi:[1,1,1] neg_lo:[1,0,0] neg_hi:[1,0,0]
	v_pk_fma_f32 v[174:175], v[168:169], v[204:205], v[174:175] op_sel:[1,0,0] op_sel_hi:[1,1,1] neg_lo:[1,0,0] neg_hi:[1,0,0]
	v_pk_fma_f32 v[176:177], v[168:169], v[206:207], v[176:177] op_sel:[1,0,0] op_sel_hi:[1,1,1] neg_lo:[1,0,0] neg_hi:[1,0,0]
	v_pk_fma_f32 v[178:179], v[168:169], v[208:209], v[178:179] op_sel:[1,0,0] op_sel_hi:[1,1,1] neg_lo:[1,0,0] neg_hi:[1,0,0]
	v_pk_fma_f32 v[180:181], v[168:169], v[210:211], v[180:181] op_sel:[1,0,0] op_sel_hi:[1,1,1] neg_lo:[1,0,0] neg_hi:[1,0,0]
	v_pk_fma_f32 v[182:183], v[168:169], v[212:213], v[182:183] op_sel:[1,0,0] op_sel_hi:[1,1,1] neg_lo:[1,0,0] neg_hi:[1,0,0]
	ds_read_b64 v[196:197], v167 offset:1304
	ds_read_b128 v[198:201], v167 offset:1312
	ds_read_b128 v[202:205], v167 offset:1328
	s_waitcnt lgkmcnt(10)
	v_fma_f32 v171, -v170, v185, v171
	v_pk_fma_f32 v[172:173], v[170:171], v[214:215], v[172:173] op_sel_hi:[0,1,1] neg_lo:[1,0,0] neg_hi:[1,0,0]
	v_pk_fma_f32 v[174:175], v[170:171], v[216:217], v[174:175] op_sel_hi:[0,1,1] neg_lo:[1,0,0] neg_hi:[1,0,0]
	v_pk_fma_f32 v[176:177], v[170:171], v[218:219], v[176:177] op_sel_hi:[0,1,1] neg_lo:[1,0,0] neg_hi:[1,0,0]
	v_pk_fma_f32 v[178:179], v[170:171], v[220:221], v[178:179] op_sel_hi:[0,1,1] neg_lo:[1,0,0] neg_hi:[1,0,0]
	v_pk_fma_f32 v[180:181], v[170:171], v[226:227], v[180:181] op_sel_hi:[0,1,1] neg_lo:[1,0,0] neg_hi:[1,0,0]
	v_pk_fma_f32 v[182:183], v[170:171], v[228:229], v[182:183] op_sel_hi:[0,1,1] neg_lo:[1,0,0] neg_hi:[1,0,0]
	ds_read_b32 v185, v167 offset:1564
	ds_read_b128 v[206:209], v167 offset:1568
	ds_read_b128 v[210:213], v167 offset:1584
	s_waitcnt lgkmcnt(10)
	v_pk_fma_f32 v[172:173], v[170:171], v[230:231], v[172:173] op_sel:[1,0,0] op_sel_hi:[1,1,1] neg_lo:[1,0,0] neg_hi:[1,0,0]
	v_pk_fma_f32 v[174:175], v[170:171], v[232:233], v[174:175] op_sel:[1,0,0] op_sel_hi:[1,1,1] neg_lo:[1,0,0] neg_hi:[1,0,0]
	v_pk_fma_f32 v[176:177], v[170:171], v[234:235], v[176:177] op_sel:[1,0,0] op_sel_hi:[1,1,1] neg_lo:[1,0,0] neg_hi:[1,0,0]
	v_pk_fma_f32 v[178:179], v[170:171], v[236:237], v[178:179] op_sel:[1,0,0] op_sel_hi:[1,1,1] neg_lo:[1,0,0] neg_hi:[1,0,0]
	v_pk_fma_f32 v[180:181], v[170:171], v[238:239], v[180:181] op_sel:[1,0,0] op_sel_hi:[1,1,1] neg_lo:[1,0,0] neg_hi:[1,0,0]
	v_pk_fma_f32 v[182:183], v[170:171], v[240:241], v[182:183] op_sel:[1,0,0] op_sel_hi:[1,1,1] neg_lo:[1,0,0] neg_hi:[1,0,0]
	ds_read_b128 v[214:217], v167 offset:1824
	ds_read_b128 v[218:221], v167 offset:1840
	s_waitcnt lgkmcnt(8)
; __device__ __forceinline__ float delta_prep(const Params& p, int l, int h, bool isP, int grow0, int t0, int nvalid, int bb, char* sm) {
;     ...
;       if (tid < 256) {
;         float a[16];
; #pragma unroll
;         for (int ii = 0; ii < 16; ++ii) a[ii] = xs[(ib * 16 + ii) * 256 + tid];
; #pragma unroll
;         for (int j = 0; j < 16; ++j) {
;           const float xj = a[j];
;           const float* mp = MT + (ib * 16 + j) * 64 + ib * 16;
; #pragma unroll
;           for (int ii = j + 1; ii < 16; ++ii) a[ii] -= mp[ii] * xj;
;         }
;         bfraw* dst = (tid < 128) ? XTu + tid * 72 + ib * 16 : XTw + (tid - 128) * 72 + ib * 16;
;         *(uint4*)dst = pack8(a);
;         *(uint4*)(dst + 8) = pack8(a + 8);
;       }
	v_fma_f32 v173, -v172, v184, v173
	v_pk_fma_f32 v[174:175], v[172:173], v[186:187], v[174:175] op_sel_hi:[0,1,1] neg_lo:[1,0,0] neg_hi:[1,0,0]
	v_pk_fma_f32 v[176:177], v[172:173], v[188:189], v[176:177] op_sel_hi:[0,1,1] neg_lo:[1,0,0] neg_hi:[1,0,0]
	v_pk_fma_f32 v[178:179], v[172:173], v[190:191], v[178:179] op_sel_hi:[0,1,1] neg_lo:[1,0,0] neg_hi:[1,0,0]
	v_pk_fma_f32 v[180:181], v[172:173], v[192:193], v[180:181] op_sel_hi:[0,1,1] neg_lo:[1,0,0] neg_hi:[1,0,0]
	v_pk_fma_f32 v[182:183], v[172:173], v[194:195], v[182:183] op_sel_hi:[0,1,1] neg_lo:[1,0,0] neg_hi:[1,0,0]
	ds_read_b32 v184, v167 offset:2084
	ds_read_b64 v[186:187], v167 offset:2088
	ds_read_b128 v[188:191], v167 offset:2096
	s_waitcnt lgkmcnt(8)
	v_pk_fma_f32 v[174:175], v[172:173], v[196:197], v[174:175] op_sel:[1,0,0] op_sel_hi:[1,1,1] neg_lo:[1,0,0] neg_hi:[1,0,0]
	v_pk_fma_f32 v[176:177], v[172:173], v[198:199], v[176:177] op_sel:[1,0,0] op_sel_hi:[1,1,1] neg_lo:[1,0,0] neg_hi:[1,0,0]
	v_pk_fma_f32 v[178:179], v[172:173], v[200:201], v[178:179] op_sel:[1,0,0] op_sel_hi:[1,1,1] neg_lo:[1,0,0] neg_hi:[1,0,0]
	v_pk_fma_f32 v[180:181], v[172:173], v[202:203], v[180:181] op_sel:[1,0,0] op_sel_hi:[1,1,1] neg_lo:[1,0,0] neg_hi:[1,0,0]
	v_pk_fma_f32 v[182:183], v[172:173], v[204:205], v[182:183] op_sel:[1,0,0] op_sel_hi:[1,1,1] neg_lo:[1,0,0] neg_hi:[1,0,0]
	ds_read_b64 v[192:193], v167 offset:2344
	ds_read_b128 v[194:197], v167 offset:2352
	s_waitcnt lgkmcnt(7)
	v_fma_f32 v175, -v174, v185, v175
	v_pk_fma_f32 v[176:177], v[174:175], v[206:207], v[176:177] op_sel_hi:[0,1,1] neg_lo:[1,0,0] neg_hi:[1,0,0]
	v_pk_fma_f32 v[178:179], v[174:175], v[208:209], v[178:179] op_sel_hi:[0,1,1] neg_lo:[1,0,0] neg_hi:[1,0,0]
	v_pk_fma_f32 v[180:181], v[174:175], v[210:211], v[180:181] op_sel_hi:[0,1,1] neg_lo:[1,0,0] neg_hi:[1,0,0]
	v_pk_fma_f32 v[182:183], v[174:175], v[212:213], v[182:183] op_sel_hi:[0,1,1] neg_lo:[1,0,0] neg_hi:[1,0,0]
	ds_read_b32 v185, v167 offset:2604
	ds_read_b128 v[198:201], v167 offset:2608
	s_waitcnt lgkmcnt(7)
	v_pk_fma_f32 v[176:177], v[174:175], v[214:215], v[176:177] op_sel:[1,0,0] op_sel_hi:[1,1,1] neg_lo:[1,0,0] neg_hi:[1,0,0]
	v_pk_fma_f32 v[178:179], v[174:175], v[216:217], v[178:179] op_sel:[1,0,0] op_sel_hi:[1,1,1] neg_lo:[1,0,0] neg_hi:[1,0,0]
	v_pk_fma_f32 v[180:181], v[174:175], v[218:219], v[180:181] op_sel:[1,0,0] op_sel_hi:[1,1,1] neg_lo:[1,0,0] neg_hi:[1,0,0]
	v_pk_fma_f32 v[182:183], v[174:175], v[220:221], v[182:183] op_sel:[1,0,0] op_sel_hi:[1,1,1] neg_lo:[1,0,0] neg_hi:[1,0,0]
	ds_read_b128 v[202:205], v167 offset:2864
	s_waitcnt lgkmcnt(5)
	v_fma_f32 v177, -v176, v184, v177
	v_pk_fma_f32 v[178:179], v[176:177], v[186:187], v[178:179] op_sel_hi:[0,1,1] neg_lo:[1,0,0] neg_hi:[1,0,0]
	v_pk_fma_f32 v[180:181], v[176:177], v[188:189], v[180:181] op_sel_hi:[0,1,1] neg_lo:[1,0,0] neg_hi:[1,0,0]
	v_pk_fma_f32 v[182:183], v[176:177], v[190:191], v[182:183] op_sel_hi:[0,1,1] neg_lo:[1,0,0] neg_hi:[1,0,0]
	ds_read_b32 v184, v167 offset:3124
	ds_read_b64 v[186:187], v167 offset:3128
	s_waitcnt lgkmcnt(5)
	v_pk_fma_f32 v[178:179], v[176:177], v[192:193], v[178:179] op_sel:[1,0,0] op_sel_hi:[1,1,1] neg_lo:[1,0,0] neg_hi:[1,0,0]
	v_pk_fma_f32 v[180:181], v[176:177], v[194:195], v[180:181] op_sel:[1,0,0] op_sel_hi:[1,1,1] neg_lo:[1,0,0] neg_hi:[1,0,0]
	v_pk_fma_f32 v[182:183], v[176:177], v[196:197], v[182:183] op_sel:[1,0,0] op_sel_hi:[1,1,1] neg_lo:[1,0,0] neg_hi:[1,0,0]
	ds_read_b64 v[188:189], v167 offset:3384
	s_waitcnt lgkmcnt(4)
	v_fma_f32 v179, -v178, v185, v179
	v_pk_fma_f32 v[180:181], v[178:179], v[198:199], v[180:181] op_sel_hi:[0,1,1] neg_lo:[1,0,0] neg_hi:[1,0,0]
	v_pk_fma_f32 v[182:183], v[178:179], v[200:201], v[182:183] op_sel_hi:[0,1,1] neg_lo:[1,0,0] neg_hi:[1,0,0]
	ds_read_b32 v185, v167 offset:3644
	s_waitcnt lgkmcnt(4)
	v_pk_fma_f32 v[180:181], v[178:179], v[202:203], v[180:181] op_sel:[1,0,0] op_sel_hi:[1,1,1] neg_lo:[1,0,0] neg_hi:[1,0,0]
	v_pk_fma_f32 v[182:183], v[178:179], v[204:205], v[182:183] op_sel:[1,0,0] op_sel_hi:[1,1,1] neg_lo:[1,0,0] neg_hi:[1,0,0]
	s_waitcnt lgkmcnt(2)
	v_fma_f32 v181, -v180, v184, v181
	v_pk_fma_f32 v[182:183], v[180:181], v[186:187], v[182:183] op_sel_hi:[0,1,1] neg_lo:[1,0,0] neg_hi:[1,0,0]
	s_waitcnt lgkmcnt(1)
	v_pk_fma_f32 v[182:183], v[180:181], v[188:189], v[182:183] op_sel:[1,0,0] op_sel_hi:[1,1,1] neg_lo:[1,0,0] neg_hi:[1,0,0]
	s_waitcnt lgkmcnt(0)
	v_fma_f32 v183, -v182, v185, v183
	v_cvt_pk_bf16_f32 v184, v168, v169
	v_cvt_pk_bf16_f32 v185, v170, v171
	v_cvt_pk_bf16_f32 v186, v172, v173
	v_cvt_pk_bf16_f32 v187, v174, v175
	ds_write_b128 v11, v[184:187]
	v_cvt_pk_bf16_f32 v188, v176, v177
	v_cvt_pk_bf16_f32 v189, v178, v179
	v_cvt_pk_bf16_f32 v190, v180, v181
	v_cvt_pk_bf16_f32 v191, v182, v183
	ds_write_b128 v11, v[188:191] offset:16
	v_readlane_b32 s2, v246, 43

; __device__ __forceinline__ int opq(int x) { asm volatile("" : "+v"(x)); return x; }
; __device__ __forceinline__ void down_reduce(const Params& p) {
;   const float* PS = (const float*)(p.ws + WS_A);
;   g8::StaticOrder S; S.init(MP, 1024, 1, 0); S.sub(DOWN_FULL, DOWN_TAIL, 1, 0);
;   for (int i = blockIdx.x * NTHR + opq(threadIdx.x); i < DOWN_TAIL * 16384; i += gridDim.x * NTHR) {
;     const int t = i >> 14, e = i & 16383, rl = e >> 6, c4 = (e & 63) * 4;
;     g8::Unit u; S.next(t, u);
;     const int row = u.pm * 256 + rl;
;     if (row >= ROWS) continue;
;     f32x4 s = (f32x4){0.f, 0.f, 0.f, 0.f};
; #pragma unroll
;     for (int k = 0; k < DOWN_KS; ++k) s += *(const f32x4*)(PS + (size_t)(t * DOWN_KS + k) * 65536 + rl * 256 + c4);
;     float* xd = resid(p, row) + u.pn * 256 + c4;
;     *(f32x4*)xd = *(const f32x4*)xd + s;
;   }
; }
.LBB0_5414:
	s_cmp_gt_i32 s94, 21
	s_cselect_b64 s[0:1], -1, 0
	s_cmp_lt_i32 s95, 22
	s_cselect_b64 s[2:3], -1, 0
	s_or_b64 s[0:1], s[0:1], s[2:3]
	s_branch .LBB0_5486

; __device__ __forceinline__ int opq(int x) { asm volatile("" : "+v"(x)); return x; }
; __device__ __forceinline__ void phase_final(const Params& p) {
;     ...
;   for (int r = blockIdx.x * 8 + w; r < ROWS; r += gridDim.x * 8) {
;     if (r < ROWS_P && (r % TP) < 16) continue;
;     float* src = resid(p, r);
;     float4 v[4];
;     float ss = 0.f;
; #pragma unroll
;     for (int j = 0; j < 4; ++j) {
;       v[j] = *(const float4*)(src + j * 256 + lane * 4);
; __device__ __forceinline__ void down_reduce(const Params& p) {
;     ...
;   for (int i = blockIdx.x * NTHR + opq(threadIdx.x); i < DOWN_TAIL * 16384; i += gridDim.x * NTHR) {
;     const int t = i >> 14, e = i & 16383, rl = e >> 6, c4 = (e & 63) * 4;
;     g8::Unit u; S.next(t, u);
;     const int row = u.pm * 256 + rl;
;     if (row >= ROWS) continue;
;     f32x4 s = (f32x4){0.f, 0.f, 0.f, 0.f};
; #pragma unroll
;     for (int k = 0; k < DOWN_KS; ++k) s += *(const f32x4*)(PS + (size_t)(t * DOWN_KS + k) * 65536 + rl * 256 + c4);
;     float* xd = resid(p, row) + u.pn * 256 + c4;
;     *(f32x4*)xd = *(const f32x4*)xd + s;
.LBB0_5490:
	s_or_b64 exec, exec, s[10:11]
	v_lshlrev_b64 v[18:19], 12, v[18:19]
	v_lshl_add_u64 v[18:19], v[22:23], 0, v[18:19]
	v_lshl_add_u64 v[22:23], v[18:19], 0, v[16:17]
	global_load_dwordx4 v[18:21], v[22:23], off
	global_load_dwordx4 v[28:31], v[22:23], off offset:1024
	global_load_dwordx4 v[32:35], v[22:23], off offset:2048
	global_load_dwordx4 v[36:39], v[22:23], off offset:3072
	v_readfirstlane_b32 s60, v24
	s_lshr_b32 s61, s60, 8
	s_mov_b32 s62, -1
	s_cmp_eq_u32 s61, 16
	s_cmov_b32 s62, 0x0
	s_cmp_eq_u32 s61, 35
	s_cmov_b32 s62, 0x1
	s_cmp_eq_u32 s61, 54
	s_cmov_b32 s62, 0x2
	s_cmp_eq_u32 s61, 65
	s_cmov_b32 s62, 0x103
	s_cmp_eq_u32 s61, 84
	s_cmov_b32 s62, 0x104
	s_cmp_eq_u32 s61, 102
	s_cmov_b32 s62, 0x105
	s_cmp_eq_u32 s61, 112
	s_cmov_b32 s62, 0x206
	s_cmp_eq_u32 s61, 131
	s_cmov_b32 s62, 0x307
	s_cmp_eq_u32 s61, 17
	s_cmov_b32 s62, 0x8
	s_cmp_eq_u32 s61, 36
	s_cmov_b32 s62, 0x9
	s_cmp_eq_u32 s61, 55
	s_cmov_b32 s62, 0xa
	s_cmp_eq_u32 s61, 66
	s_cmov_b32 s62, 0x10b
	s_cmp_eq_u32 s61, 85
	s_cmov_b32 s62, 0x10c
	s_cmp_eq_u32 s61, 103
	s_cmov_b32 s62, 0x10d
	s_cmp_eq_u32 s61, 113
	s_cmov_b32 s62, 0x20e
	s_cmp_eq_u32 s61, 132
	s_cmov_b32 s62, 0x30f
	s_cmp_eq_u32 s61, 18
	s_cmov_b32 s62, 0x10
	s_cmp_eq_u32 s61, 37
	s_cmov_b32 s62, 0x11
	s_cmp_eq_u32 s61, 48
	s_cmov_b32 s62, 0x112
	s_cmp_eq_u32 s61, 67
	s_cmov_b32 s62, 0x113
	s_cmp_lt_i32 s62, 0
	s_cbranch_scc1 .Lfold_skip
	s_and_b32 s63, s62, 0xff
	s_lshr_b32 s62, s62, 8
	s_and_b32 s64, s60, 0xff
	s_lshl_b32 s64, s64, 10
	s_lshl_b32 s65, s63, 21
	s_add_u32 s64, s64, s65
	s_add_u32 s64, s64, 0x21a0000
	s_add_u32 s66, s96, s64
	s_addc_u32 s67, s97, 0
	global_load_dwordx4 v[60:63], v16, s[66:67]
	s_add_u32 s66, s66, 0x40000
	s_addc_u32 s67, s67, 0
	global_load_dwordx4 v[64:67], v16, s[66:67]
	s_add_u32 s66, s66, 0x40000
	s_addc_u32 s67, s67, 0
	global_load_dwordx4 v[68:71], v16, s[66:67]
	s_add_u32 s66, s66, 0x40000
	s_addc_u32 s67, s67, 0
	global_load_dwordx4 v[72:75], v16, s[66:67]
	s_add_u32 s66, s66, 0x40000
	s_addc_u32 s67, s67, 0
	global_load_dwordx4 v[76:79], v16, s[66:67]
	s_add_u32 s66, s66, 0x40000
	s_addc_u32 s67, s67, 0
	global_load_dwordx4 v[80:83], v16, s[66:67]
	s_add_u32 s66, s66, 0x40000
	s_addc_u32 s67, s67, 0
	global_load_dwordx4 v[84:87], v16, s[66:67]
	s_add_u32 s66, s66, 0x40000
	s_addc_u32 s67, s67, 0
	global_load_dwordx4 v[88:91], v16, s[66:67]
	s_waitcnt vmcnt(0)
	v_pk_add_f32 v[60:61], v[60:61], 0 op_sel_hi:[1,0]
	v_pk_add_f32 v[62:63], v[62:63], 0 op_sel_hi:[1,0]
	v_pk_add_f32 v[60:61], v[60:61], v[64:65]
	v_pk_add_f32 v[62:63], v[62:63], v[66:67]
	v_pk_add_f32 v[60:61], v[60:61], v[68:69]
	v_pk_add_f32 v[62:63], v[62:63], v[70:71]
	v_pk_add_f32 v[60:61], v[60:61], v[72:73]
	v_pk_add_f32 v[62:63], v[62:63], v[74:75]
	v_pk_add_f32 v[60:61], v[60:61], v[76:77]
	v_pk_add_f32 v[62:63], v[62:63], v[78:79]
	v_pk_add_f32 v[60:61], v[60:61], v[80:81]
	v_pk_add_f32 v[62:63], v[62:63], v[82:83]
	v_pk_add_f32 v[60:61], v[60:61], v[84:85]
	v_pk_add_f32 v[62:63], v[62:63], v[86:87]
	v_pk_add_f32 v[60:61], v[60:61], v[88:89]
	v_pk_add_f32 v[62:63], v[62:63], v[90:91]
	s_cmp_lg_u32 s62, 0
	s_cbranch_scc1 .Lfold_j0
	v_pk_add_f32 v[18:19], v[18:19], v[60:61]
	v_pk_add_f32 v[20:21], v[20:21], v[62:63]
.Lfold_j0:
	s_cmp_lg_u32 s62, 1
	s_cbranch_scc1 .Lfold_j1
	v_pk_add_f32 v[28:29], v[28:29], v[60:61]
	v_pk_add_f32 v[30:31], v[30:31], v[62:63]
.Lfold_j1:
	s_cmp_lg_u32 s62, 2
	s_cbranch_scc1 .Lfold_j2
	v_pk_add_f32 v[32:33], v[32:33], v[60:61]
	v_pk_add_f32 v[34:35], v[34:35], v[62:63]
.Lfold_j2:
	s_cmp_lg_u32 s62, 3
	s_cbranch_scc1 .Lfold_j3
	v_pk_add_f32 v[36:37], v[36:37], v[60:61]
	v_pk_add_f32 v[38:39], v[38:39], v[62:63]
; __device__ __forceinline__ void phase_final(const Params& p) {
;     ...
;     float ss = 0.f;
; #pragma unroll
;     for (int j = 0; j < 4; ++j) {
;       v[j] = *(const float4*)(src + j * 256 + lane * 4);
;       ss += v[j].x * v[j].x + v[j].y * v[j].y + v[j].z * v[j].z + v[j].w * v[j].w;
;     }
; #pragma unroll
;     for (int o = 32; o >= 1; o >>= 1) ss += __shfl_xor(ss, o);
;     float rinv = rsqrtf(ss * (1.f / 1024.f) + EPS);
; #pragma unroll
;     for (int j = 0; j < 4; ++j) {
;       float4 o4 = make_float4(v[j].x * rinv * wv[j].x, v[j].y * rinv * wv[j].y, v[j].z * rinv * wv[j].z, v[j].w * rinv * wv[j].w);
;       *(float4*)(src + j * 256 + lane * 4) = o4;
;     }
.Lfold_j3:
.Lfold_skip:
	v_and_b32_e32 v27, 64, v26
	v_xor_b32_e32 v40, 32, v26
	v_add_u32_e32 v27, 64, v27
	v_cmp_lt_i32_e32 vcc, v40, v27
	s_waitcnt vmcnt(3)
	v_mov_b32_e32 v42, v19
	v_cndmask_b32_e32 v40, v26, v40, vcc
	s_waitcnt vmcnt(2)
	v_mov_b32_e32 v43, v29
	v_lshlrev_b32_e32 v56, 2, v40
	v_mov_b32_e32 v40, v18
	v_mov_b32_e32 v41, v28
	s_waitcnt vmcnt(1)
	v_mov_b32_e32 v50, v33
	s_waitcnt vmcnt(0)
	v_mov_b32_e32 v51, v37
	v_pk_mul_f32 v[42:43], v[42:43], v[42:43]
	v_mov_b32_e32 v44, v20
	v_mov_b32_e32 v45, v30
	v_mov_b32_e32 v48, v32
	v_mov_b32_e32 v49, v36
	v_pk_mul_f32 v[50:51], v[50:51], v[50:51]
	v_pk_fma_f32 v[40:41], v[40:41], v[40:41], v[42:43]
	v_mov_b32_e32 v46, v21
	v_mov_b32_e32 v47, v31
	v_mov_b32_e32 v52, v34
	v_mov_b32_e32 v53, v38
	v_pk_fma_f32 v[42:43], v[48:49], v[48:49], v[50:51]
	v_pk_fma_f32 v[40:41], v[44:45], v[44:45], v[40:41]
	v_mov_b32_e32 v54, v35
	v_mov_b32_e32 v55, v39
	v_pk_fma_f32 v[42:43], v[52:53], v[52:53], v[42:43]
	v_pk_fma_f32 v[40:41], v[46:47], v[46:47], v[40:41]
	v_pk_fma_f32 v[42:43], v[54:55], v[54:55], v[42:43]
	v_add_f32_e32 v40, v40, v41
	v_add_f32_e32 v40, v40, v42
	v_add_f32_e32 v40, v40, v43
	ds_bpermute_b32 v41, v56, v40
	v_xor_b32_e32 v42, 16, v26
	v_cmp_lt_i32_e32 vcc, v42, v27
	s_waitcnt lgkmcnt(0)
	v_add_f32_e32 v40, v40, v41
	v_cndmask_b32_e32 v42, v26, v42, vcc
	v_lshlrev_b32_e32 v42, 2, v42
	ds_bpermute_b32 v41, v42, v40
	v_xor_b32_e32 v42, 8, v26
	v_cmp_lt_i32_e32 vcc, v42, v27
	s_waitcnt lgkmcnt(0)
	v_add_f32_e32 v40, v40, v41
	v_cndmask_b32_e32 v42, v26, v42, vcc
	v_lshlrev_b32_e32 v42, 2, v42
	ds_bpermute_b32 v41, v42, v40
	v_xor_b32_e32 v42, 4, v26
	v_cmp_lt_i32_e32 vcc, v42, v27
	s_waitcnt lgkmcnt(0)
	v_add_f32_e32 v40, v40, v41
	v_cndmask_b32_e32 v42, v26, v42, vcc
	v_lshlrev_b32_e32 v42, 2, v42
	ds_bpermute_b32 v41, v42, v40
	v_xor_b32_e32 v42, 2, v26
	v_cmp_lt_i32_e32 vcc, v42, v27
	s_waitcnt lgkmcnt(0)
	v_add_f32_e32 v40, v40, v41
	v_cndmask_b32_e32 v42, v26, v42, vcc
	v_lshlrev_b32_e32 v42, 2, v42
	ds_bpermute_b32 v41, v42, v40
	v_xor_b32_e32 v42, 1, v26
	v_cmp_lt_i32_e32 vcc, v42, v27
	s_waitcnt lgkmcnt(0)
	v_add_f32_e32 v40, v40, v41
	v_cndmask_b32_e32 v27, v26, v42, vcc
	v_lshlrev_b32_e32 v27, 2, v27
	ds_bpermute_b32 v27, v27, v40
	s_waitcnt lgkmcnt(0)
	v_add_f32_e32 v27, v40, v27
	v_fmamk_f32 v27, v27, 0x3a800000, v25
	v_mul_f32_e32 v40, 0x4b800000, v27
	v_cmp_gt_f32_e32 vcc, s18, v27
	s_nop 1
	v_cndmask_b32_e32 v27, v27, v40, vcc
	v_rsq_f32_e32 v27, v27
	s_nop 0
	v_mul_f32_e32 v40, 0x45800000, v27
	v_cndmask_b32_e32 v40, v27, v40, vcc
	v_pk_mul_f32 v[18:19], v[18:19], v[40:41] op_sel_hi:[1,0]
	v_pk_mul_f32 v[20:21], v[20:21], v[40:41] op_sel_hi:[1,0]
	v_pk_mul_f32 v[28:29], v[28:29], v[40:41] op_sel_hi:[1,0]
	v_pk_mul_f32 v[30:31], v[30:31], v[40:41] op_sel_hi:[1,0]
	v_pk_mul_f32 v[32:33], v[32:33], v[40:41] op_sel_hi:[1,0]
	v_pk_mul_f32 v[34:35], v[34:35], v[40:41] op_sel_hi:[1,0]
	v_pk_mul_f32 v[36:37], v[36:37], v[40:41] op_sel_hi:[1,0]
	v_pk_mul_f32 v[38:39], v[38:39], v[40:41] op_sel_hi:[1,0]
	v_pk_mul_f32 v[18:19], v[0:1], v[18:19]
	v_pk_mul_f32 v[20:21], v[2:3], v[20:21]
	v_pk_mul_f32 v[28:29], v[4:5], v[28:29]
	v_pk_mul_f32 v[30:31], v[6:7], v[30:31]
	v_pk_mul_f32 v[32:33], v[8:9], v[32:33]
	v_pk_mul_f32 v[34:35], v[10:11], v[34:35]
	v_pk_mul_f32 v[36:37], v[12:13], v[36:37]
	v_pk_mul_f32 v[38:39], v[14:15], v[38:39]
	global_store_dwordx4 v[22:23], v[18:21], off
	global_store_dwordx4 v[22:23], v[28:31], off offset:1024
	global_store_dwordx4 v[22:23], v[32:35], off offset:2048
	global_store_dwordx4 v[22:23], v[36:39], off offset:3072

; __global__ void __launch_bounds__(NTHR, 2) fwd_kernel(Params p, int ph_lo, int ph_hi) {
	.amdhsa_kernel _Z10fwd_kernel6Paramsii
		.amdhsa_group_segment_fixed_size 0
		.amdhsa_private_segment_fixed_size 0
		.amdhsa_kernarg_size 480
		.amdhsa_user_sgpr_count 2
		.amdhsa_user_sgpr_dispatch_ptr 0
		.amdhsa_user_sgpr_queue_ptr 0
		.amdhsa_user_sgpr_kernarg_segment_ptr 1
		.amdhsa_user_sgpr_dispatch_id 0
		.amdhsa_user_sgpr_kernarg_preload_length 0
		.amdhsa_user_sgpr_kernarg_preload_offset 0
		.amdhsa_user_sgpr_private_segment_size 0
		.amdhsa_uses_dynamic_stack 0
		.amdhsa_enable_private_segment 0
		.amdhsa_system_sgpr_workgroup_id_x 1
		.amdhsa_system_sgpr_workgroup_id_y 0
		.amdhsa_system_sgpr_workgroup_id_z 0
		.amdhsa_system_sgpr_workgroup_info 0
		.amdhsa_system_vgpr_workitem_id 2
		.amdhsa_next_free_vgpr 248
		.amdhsa_next_free_sgpr 102
		.amdhsa_accum_offset 248
		.amdhsa_reserve_vcc 1
		.amdhsa_float_round_mode_32 0
		.amdhsa_float_round_mode_16_64 0
		.amdhsa_float_denorm_mode_32 3
		.amdhsa_float_denorm_mode_16_64 3
		.amdhsa_dx10_clamp 1
		.amdhsa_ieee_mode 1
		.amdhsa_fp16_overflow 0
		.amdhsa_tg_split 0
		.amdhsa_exception_fp_ieee_invalid_op 0
		.amdhsa_exception_fp_denorm_src 0
		.amdhsa_exception_fp_ieee_div_zero 0
		.amdhsa_exception_fp_ieee_overflow 0
		.amdhsa_exception_fp_ieee_underflow 0
		.amdhsa_exception_fp_ieee_inexact 0
		.amdhsa_exception_int_div_zero 0
	.end_amdhsa_kernel

; __global__ void __launch_bounds__(NTHR, 2) fwd_kernel(Params p, int ph_lo, int ph_hi) {
amdhsa.kernels:
  - .agpr_count:     0
    .args:
      - .offset:         0
        .size:           216
        .value_kind:     by_value
      - .offset:         216
        .size:           4
        .value_kind:     by_value
      - .offset:         220
        .size:           4
        .value_kind:     by_value
      - .offset:         224
        .size:           4
        .value_kind:     hidden_block_count_x
      - .offset:         228
        .size:           4
        .value_kind:     hidden_block_count_y
      - .offset:         232
        .size:           4
        .value_kind:     hidden_block_count_z
      - .offset:         236
        .size:           2
        .value_kind:     hidden_group_size_x
      - .offset:         238
        .size:           2
        .value_kind:     hidden_group_size_y
      - .offset:         240
        .size:           2
        .value_kind:     hidden_group_size_z
      - .offset:         242
        .size:           2
        .value_kind:     hidden_remainder_x
      - .offset:         244
        .size:           2
        .value_kind:     hidden_remainder_y
      - .offset:         246
        .size:           2
        .value_kind:     hidden_remainder_z
      - .offset:         264
        .size:           8
        .value_kind:     hidden_global_offset_x
      - .offset:         272
        .size:           8
        .value_kind:     hidden_global_offset_y
      - .offset:         280
        .size:           8
        .value_kind:     hidden_global_offset_z
      - .offset:         288
        .size:           2
        .value_kind:     hidden_grid_dims
      - .offset:         312
        .size:           8
        .value_kind:     hidden_multigrid_sync_arg
      - .offset:         344
        .size:           4
        .value_kind:     hidden_dynamic_lds_size
    .group_segment_fixed_size: 0
    .kernarg_segment_align: 8
    .kernarg_segment_size: 480
    .language:       OpenCL C
    .language_version:
      - 2
      - 0
    .max_flat_workgroup_size: 512
    .name:           _Z10fwd_kernel6Paramsii
    .private_segment_fixed_size: 0
    .sgpr_count:     108
    .sgpr_spill_count: 449
    .symbol:         _Z10fwd_kernel6Paramsii.kd
    .uniform_work_group_size: 1
    .uses_dynamic_stack: false
    .vgpr_count:     248
    .vgpr_spill_count: 0
    .wavefront_size: 64
